# GLDS interleave extended to all 10 rolled GEMM k-loops
# speedup vs baseline: 1.0080x; 1.0080x over previous
; #define GLDS16(gp, lp) __builtin_amdgcn_global_load_lds((const unsigned*)(gp), (__attribute__((address_space(3))) unsigned*)(lp), 16, 0, 0)
; template <bool SWAP, class Epi, bool THIN = false> ...
;     ...
;   for (; v < voff + ntiles; v += grid) {
;     const int w = v - voff;
;     int mt, nt;
;     if (w < full * 8 * NT) { const int sr = w / (8 * NT), rem = w - sr * 8 * NT; nt = rem >> 3; mt = sr * 8 + (rem & 7); }
;     else { const int w2 = w - full * 8 * NT, rl = MT - full * 8; nt = w2 / rl; mt = full * 8 + (w2 - nt * rl); }
;     unsigned ap[4], bp[4];
; #pragma unroll
;     for (int i = 0; i < 4; ++i) {
;       const int r = (tid >> 3) + 64 * i;
;       const int cs = tid & 7;
;       const int c = ((cs ^ ((r >> 1) & 7)) << 3);
;       const int sub = 2 * mt + (r >> 7);
;       const int g = sub / tpg, ti = sub - g * tpg;
;       int rig = ti * step - halo + (r & 127); rig = rig < 0 ? 0 : (rig > grows - 1 ? grows - 1 : rig);
;       ap[i] = (unsigned)((g * a_gstride + a_goff + rig) * lda + c);
;       int br = nt * 256 + r; br = br > N - 1 ? N - 1 : br;
;       bp[i] = (unsigned)(br * K + c);
;     }
;     const bool have_next = false;
;     f32x4 acc[4][8];
; #pragma unroll
;     for (int m = 0; m < 4; ++m)
; #pragma unroll
;       for (int n = 0; n < 8; ++n) acc[m][n] = (f32x4){0.f, 0.f, 0.f, 0.f};
;     if (!pre_issued) {
; #pragma unroll
;       for (int i = 0; i < 4; ++i) { GLDS16(A + (size_t)ap[i], smem + tid * 16 + i * 8192); GLDS16(Bt + (size_t)bp[i], smem + 32768 + tid * 16 + i * 8192); }
;     }
;     pre_issued = have_next;
.LBB0_338:
	s_ashr_i32 s4, s26, 31
	s_lshr_b32 s4, s4, 28
	s_add_i32 s4, s26, s4
	s_and_b32 s4, s4, -16
	s_sub_i32 s5, s26, s4
	s_ashr_i32 s20, s5, 3
	s_lshl_b32 s5, s26, 1
	s_and_b32 s5, s5, 14
	s_or_b32 s5, s4, s5
	v_add_u32_e32 v2, s5, v149
	v_ashrrev_i32_e32 v3, 31, v2
	v_lshrrev_b32_e32 v3, 28, v3
	v_add_u32_e32 v3, v2, v3
	v_ashrrev_i32_e32 v7, 4, v3
	v_and_b32_e32 v3, -16, v3
	v_sub_u32_e32 v2, v2, v3
	v_lshl_or_b32 v3, v2, 7, v150
	v_min_i32_e32 v3, 0x7ff, v3
	v_cmp_lt_i32_e32 vcc, -1, v2
	s_lshl_b32 s4, s20, 8
	v_mov_b32_e32 v11, v131
	v_cndmask_b32_e32 v2, 0, v3, vcc
	v_mad_u64_u32 v[4:5], s[6:7], v7, s27, v[2:3]
	v_add_u32_e32 v5, s5, v152
	v_ashrrev_i32_e32 v6, 31, v5
	v_lshrrev_b32_e32 v6, 28, v6
	v_add_u32_e32 v6, v5, v6
	v_ashrrev_i32_e32 v13, 4, v6
	v_and_b32_e32 v6, -16, v6
	v_sub_u32_e32 v5, v5, v6
	v_lshl_or_b32 v6, v5, 7, v153
	v_min_i32_e32 v6, 0x7ff, v6
	v_cmp_lt_i32_e32 vcc, -1, v5
	v_lshl_or_b32 v3, v4, 10, v143
	v_add_u32_e32 v130, 0x40000, v3
	v_cndmask_b32_e32 v6, 0, v6, vcc
	v_mad_u64_u32 v[8:9], s[6:7], v13, s27, v[6:7]
	v_lshl_or_b32 v5, v8, 10, v143
	v_add_u32_e32 v8, 0x40000, v5
	v_add_u32_e32 v5, s4, v151
	v_min_i32_e32 v5, 0x1ff, v5
	v_lshlrev_b32_e32 v19, 10, v5
	v_add_u32_e32 v5, s5, v155
	v_ashrrev_i32_e32 v9, 31, v5
	v_lshrrev_b32_e32 v9, 28, v9
	v_add_u32_e32 v9, v5, v9
	v_ashrrev_i32_e32 v26, 4, v9
	v_and_b32_e32 v9, -16, v9
	v_sub_u32_e32 v5, v5, v9
	v_lshl_or_b32 v9, v5, 7, v150
	v_min_i32_e32 v9, 0x7ff, v9
	v_cmp_lt_i32_e32 vcc, -1, v5
	v_add_u32_e32 v3, s4, v142
	v_min_i32_e32 v3, 0x1ff, v3
	v_cndmask_b32_e32 v12, 0, v9, vcc
	v_mad_u64_u32 v[14:15], s[6:7], v26, s27, v[12:13]
	v_lshl_or_b32 v5, v14, 10, v143
	v_add_u32_e32 v14, 0x40000, v5
	v_add_u32_e32 v5, s4, v154
	v_min_i32_e32 v5, 0x1ff, v5
	v_lshlrev_b32_e32 v27, 10, v5
	v_add_u32_e32 v5, s5, v157
	v_ashrrev_i32_e32 v9, 31, v5
	v_lshrrev_b32_e32 v9, 28, v9
	v_add_u32_e32 v9, v5, v9
	v_ashrrev_i32_e32 v28, 4, v9
	v_and_b32_e32 v9, -16, v9
	v_sub_u32_e32 v5, v5, v9
	v_lshl_or_b32 v9, v5, 7, v158
	v_min_i32_e32 v9, 0x7ff, v9
	v_cmp_lt_i32_e32 vcc, -1, v5
	v_lshlrev_b32_e32 v3, 10, v3
	v_or_b32_e32 v4, v3, v143
	v_cndmask_b32_e32 v18, 0, v9, vcc
	v_mad_u64_u32 v[20:21], s[6:7], v28, s27, v[18:19]
	v_lshl_or_b32 v5, v20, 10, v143
	v_add_u32_e32 v20, 0x40000, v5
	v_add_u32_e32 v5, s4, v156
	v_min_i32_e32 v5, 0x1ff, v5
	v_readfirstlane_b32 s6, v144
	v_lshlrev_b32_e32 v29, 10, v5
	s_waitcnt lgkmcnt(0)
	v_lshl_add_u64 v[24:25], v[130:131], 1, s[36:37]
	s_mov_b32 m0, s6
	v_mov_b32_e32 v5, v131
	v_readfirstlane_b32 s6, v163
	global_load_lds_dwordx4 v[24:25], off
	v_lshl_add_u64 v[4:5], v[4:5], 1, s[22:23]
	s_mov_b32 m0, s6
	v_mov_b32_e32 v9, v131
	v_readfirstlane_b32 s6, v164
	v_or_b32_e32 v10, v19, v143
	global_load_lds_dwordx4 v[4:5], off
	v_lshl_add_u64 v[4:5], v[8:9], 1, s[36:37]
	s_mov_b32 m0, s6
	v_readfirstlane_b32 s6, v165
	global_load_lds_dwordx4 v[4:5], off
	v_lshl_add_u64 v[4:5], v[10:11], 1, s[22:23]
	s_mov_b32 m0, s6
	v_mov_b32_e32 v15, v131
	v_readfirstlane_b32 s6, v166
	v_or_b32_e32 v16, v27, v143
	global_load_lds_dwordx4 v[4:5], off
	v_lshl_add_u64 v[4:5], v[14:15], 1, s[36:37]
	s_mov_b32 m0, s6
	v_mov_b32_e32 v17, v131
	v_readfirstlane_b32 s6, v167
	global_load_lds_dwordx4 v[4:5], off
	v_lshl_add_u64 v[4:5], v[16:17], 1, s[22:23]
	s_mov_b32 m0, s6
	v_mov_b32_e32 v21, v131
	v_readfirstlane_b32 s6, v168
	v_or_b32_e32 v22, v29, v143
	global_load_lds_dwordx4 v[4:5], off
	v_lshl_add_u64 v[4:5], v[20:21], 1, s[36:37]
	s_mov_b32 m0, s6
	v_mov_b32_e32 v23, v131
	v_readfirstlane_b32 s6, v169
	global_load_lds_dwordx4 v[4:5], off
	v_lshl_add_u64 v[4:5], v[22:23], 1, s[22:23]
	s_mov_b32 m0, s6
	v_or_b32_e32 v138, v161, v3
	global_load_lds_dwordx4 v[4:5], off
	v_mul_lo_u32 v4, v28, s28
	v_lshlrev_b32_e32 v5, 10, v18
	v_add3_u32 v133, v162, v4, v5
	v_mul_lo_u32 v4, v26, s28
	v_lshlrev_b32_e32 v5, 10, v12
	v_add3_u32 v135, v162, v4, v5
	v_mul_lo_u32 v4, v13, s28
	v_lshlrev_b32_e32 v5, 10, v6
	v_mul_lo_u32 v3, v7, s28
	v_lshlrev_b32_e32 v2, 10, v2
	v_or_b32_e32 v132, v161, v29
	v_or_b32_e32 v134, v161, v27
	v_or_b32_e32 v136, v161, v19
	v_add3_u32 v137, v162, v4, v5
	v_add3_u32 v139, v162, v3, v2
	s_mov_b32 s6, 0
	s_mov_b32 s7, 0
	v_mov_b32_e32 v90, v131
	v_mov_b32_e32 v91, v131
	v_mov_b32_e32 v92, v131
	v_mov_b32_e32 v93, v131
	v_mov_b32_e32 v2, v131
	v_mov_b32_e32 v3, v131
	v_mov_b32_e32 v4, v131
	v_mov_b32_e32 v5, v131
	v_mov_b32_e32 v6, v131
	v_mov_b32_e32 v7, v131
	v_mov_b32_e32 v8, v131
	v_mov_b32_e32 v10, v131
	v_mov_b32_e32 v12, v131
	v_mov_b32_e32 v13, v131
	v_mov_b32_e32 v22, v131
	v_mov_b32_e32 v24, v131
	v_mov_b32_e32 v25, v131
	v_mov_b32_e32 v26, v131
	v_mov_b32_e32 v27, v131
	v_mov_b32_e32 v28, v131
	v_mov_b32_e32 v29, v131
	v_mov_b32_e32 v42, v131
	v_mov_b32_e32 v43, v131
	v_mov_b32_e32 v44, v131
	v_mov_b32_e32 v45, v131
	v_mov_b32_e32 v50, v131
	v_mov_b32_e32 v51, v131
	v_mov_b32_e32 v52, v131
	v_mov_b32_e32 v53, v131
	v_mov_b32_e32 v14, v131
	v_mov_b32_e32 v16, v131
	v_mov_b32_e32 v18, v131
	v_mov_b32_e32 v19, v131
	v_mov_b32_e32 v20, v131
	v_mov_b32_e32 v30, v131
	v_mov_b32_e32 v31, v131
	v_mov_b32_e32 v32, v131
	v_mov_b32_e32 v33, v131
	v_mov_b32_e32 v46, v131
	v_mov_b32_e32 v47, v131
	v_mov_b32_e32 v48, v131
	v_mov_b32_e32 v49, v131
	v_mov_b32_e32 v54, v131
	v_mov_b32_e32 v55, v131
	v_mov_b32_e32 v56, v131
	v_mov_b32_e32 v57, v131
	v_mov_b32_e32 v58, v131
	v_mov_b32_e32 v59, v131
	v_mov_b32_e32 v60, v131
	v_mov_b32_e32 v61, v131
	v_mov_b32_e32 v78, v131
	v_mov_b32_e32 v79, v131
	v_mov_b32_e32 v80, v131
	v_mov_b32_e32 v81, v131
	v_mov_b32_e32 v82, v131
	v_mov_b32_e32 v83, v131
	v_mov_b32_e32 v84, v131
	v_mov_b32_e32 v85, v131
; template <bool SWAP, class Epi, bool THIN = false> ...
;     ...
;     for (int st = 0; st < ns; ++st) {
;       asm volatile("s_waitcnt vmcnt(0)" ::: "memory");
;       __builtin_amdgcn_s_barrier();
;       asm volatile("" ::: "memory");
;       if (st + 1 < ns) {
;         char* nb = smem + ((st + 1) & 1) * 65536;
;         const int ko = (st + 1) * 64;
; #pragma unroll
;         for (int i = 0; i < 4; ++i) { GLDS16(A + (size_t)(ap[i] + ko), nb + tid * 16 + i * 8192); GLDS16(Bt + (size_t)(bp[i] + ko), nb + 32768 + tid * 16 + i * 8192); }
;       }
;       const char* sa = smem + (st & 1) * 65536 + (wr * 64 + fr) * 128;
;       const char* sb = smem + (st & 1) * 65536 + 32768 + (wc * 128 + fr) * 128;
;       if constexpr (THIN) {
;         if (wc == 0) {
; #pragma unroll
;           for (int ks = 0; ks < 2; ++ks) {
;             bf16x8 af[4], bf[2];
; #pragma unroll
;             for (int m = 0; m < 4; ++m) af[m] = *(const bf16x8*)(sa + m * 2048 + (((ks * 4 + fq) ^ swz) << 4));
; #pragma unroll
;             for (int n = 0; n < 2; ++n) bf[n] = *(const bf16x8*)(sb + n * 2048 + (((ks * 4 + fq) ^ swz) << 4));
; #pragma unroll
;             for (int m = 0; m < 4; ++m)
; #pragma unroll
;               for (int n = 0; n < 2; ++n)
;                 acc[m][n] = SWAP ? __builtin_amdgcn_mfma_f32_16x16x32_bf16(bf[n], af[m], acc[m][n], 0, 0, 0)
;                                  : __builtin_amdgcn_mfma_f32_16x16x32_bf16(af[m], bf[n], acc[m][n], 0, 0, 0);
;           }
;         }
;       } else {
;       bf16x8 afA[4], afB[4], bfb[2][2];
; #pragma unroll
;       for (int m = 0; m < 4; ++m) afA[m] = *(const bf16x8*)(sa + m * 2048 + ((fq ^ swz) << 4));
; #pragma unroll
;       for (int n = 0; n < 2; ++n) bfb[0][n] = *(const bf16x8*)(sb + n * 2048 + ((fq ^ swz) << 4));
; #pragma unroll
;       for (int gq = 0; gq < 8; ++gq) {
;         const int ks = gq >> 2, nh = gq & 3;
;         if (gq < 7) {
;           const int ks2 = (gq + 1) >> 2, nh2 = (gq + 1) & 3;
; #pragma unroll
;           for (int n = 0; n < 2; ++n) bfb[(gq + 1) & 1][n] = *(const bf16x8*)(sb + (nh2 * 2 + n) * 2048 + (((ks2 * 4 + fq) ^ swz) << 4));
;         }
;         if (gq == 3) {
; #pragma unroll
;           for (int m = 0; m < 4; ++m) afB[m] = *(const bf16x8*)(sa + m * 2048 + (((4 + fq) ^ swz) << 4));
;         }
;         __builtin_amdgcn_sched_barrier(0);
; #pragma unroll
	v_mov_b32_e32 v34, v131
	v_mov_b32_e32 v35, v131
	v_mov_b32_e32 v36, v131
	v_mov_b32_e32 v37, v131
	v_mov_b32_e32 v38, v131
	v_mov_b32_e32 v39, v131
	v_mov_b32_e32 v40, v131
	v_mov_b32_e32 v41, v131
	v_mov_b32_e32 v66, v131
	v_mov_b32_e32 v67, v131
	v_mov_b32_e32 v68, v131
	v_mov_b32_e32 v69, v131
	v_mov_b32_e32 v74, v131
	v_mov_b32_e32 v75, v131
	v_mov_b32_e32 v76, v131
	v_mov_b32_e32 v77, v131
	v_mov_b32_e32 v86, v131
	v_mov_b32_e32 v87, v131
	v_mov_b32_e32 v88, v131
	v_mov_b32_e32 v89, v131
	v_mov_b32_e32 v94, v131
	v_mov_b32_e32 v95, v131
	v_mov_b32_e32 v96, v131
	v_mov_b32_e32 v97, v131
	v_mov_b32_e32 v106, v131
	v_mov_b32_e32 v107, v131
	v_mov_b32_e32 v108, v131
	v_mov_b32_e32 v109, v131
	v_mov_b32_e32 v110, v131
	v_mov_b32_e32 v111, v131
	v_mov_b32_e32 v112, v131
	v_mov_b32_e32 v113, v131
	v_mov_b32_e32 v62, v131
	v_mov_b32_e32 v63, v131
	v_mov_b32_e32 v64, v131
	v_mov_b32_e32 v65, v131
	v_mov_b32_e32 v70, v131
	v_mov_b32_e32 v71, v131
	v_mov_b32_e32 v72, v131
	v_mov_b32_e32 v73, v131
	v_mov_b32_e32 v98, v131
	v_mov_b32_e32 v99, v131
	v_mov_b32_e32 v100, v131
	v_mov_b32_e32 v101, v131
	v_mov_b32_e32 v102, v131
	v_mov_b32_e32 v103, v131
	v_mov_b32_e32 v104, v131
	v_mov_b32_e32 v105, v131
	v_mov_b32_e32 v114, v131
	v_mov_b32_e32 v115, v131
	v_mov_b32_e32 v116, v131
	v_mov_b32_e32 v117, v131
	v_mov_b32_e32 v118, v131
	v_mov_b32_e32 v119, v131
	v_mov_b32_e32 v120, v131
	v_mov_b32_e32 v121, v131
	v_mov_b32_e32 v122, v131
	v_mov_b32_e32 v123, v131
	v_mov_b32_e32 v124, v131
	v_mov_b32_e32 v125, v131
	v_mov_b32_e32 v126, v131
	v_mov_b32_e32 v127, v131
	v_mov_b32_e32 v128, v131
	v_mov_b32_e32 v129, v131
	v_lshlrev_b32_e32 v139, 1, v139
	v_lshlrev_b32_e32 v138, 1, v138
	v_lshlrev_b32_e32 v137, 1, v137
	v_lshlrev_b32_e32 v136, 1, v136
	v_lshlrev_b32_e32 v135, 1, v135
	v_lshlrev_b32_e32 v134, 1, v134
	v_lshlrev_b32_e32 v133, 1, v133
	v_lshlrev_b32_e32 v132, 1, v132
.LBB0_339:
	s_add_i32 s8, s7, 0x10000
	s_and_b32 s9, s8, 0x10000
	v_add_u32_e32 v171, s9, v144
	s_nop 0
	v_readfirstlane_b32 s9, v171
	s_waitcnt vmcnt(0)
	s_barrier
	s_and_b32 s7, s7, 0x10000
	v_add_u32_e32 v130, s7, v145
	v_add_u32_e32 v140, v130, v147
	ds_read_b128 v[172:175], v140
	ds_read_b128 v[176:179], v140 offset:2048
	ds_read_b128 v[180:183], v140 offset:4096
	ds_read_b128 v[184:187], v140 offset:6144
	v_or_b32_e32 v140, s7, v146
	v_add_u32_e32 v141, v140, v147
	ds_read_b128 v[188:191], v141 offset:32768
	ds_read_b128 v[192:195], v141 offset:34816
	ds_read_b128 v[196:199], v141 offset:36864
	ds_read_b128 v[200:203], v141 offset:38912
	v_add_u32_e32 v130, v130, v148
	s_waitcnt lgkmcnt(0)
	v_mfma_f32_16x16x32_bf16 v[126:129], v[188:191], v[172:175], v[126:129]
	s_mov_b32 m0, s9
	v_mfma_f32_16x16x32_bf16 v[110:113], v[188:191], v[176:179], v[110:113]
	global_load_lds_dwordx4 v139, s[36:37]
	v_add_u32_e32 v139, 0x80, v139
	v_mfma_f32_16x16x32_bf16 v[82:85], v[188:191], v[180:183], v[82:85]
	v_mfma_f32_16x16x32_bf16 v[50:53], v[188:191], v[184:187], v[50:53]
	ds_read_b128 v[188:191], v141 offset:40960
	ds_read_b128 v[204:207], v141 offset:43008
	v_mfma_f32_16x16x32_bf16 v[122:125], v[192:195], v[172:175], v[122:125]
	s_add_u32 m0, s9, 0x8000
	v_mfma_f32_16x16x32_bf16 v[106:109], v[192:195], v[176:179], v[106:109]
	global_load_lds_dwordx4 v138, s[22:23]
	v_add_u32_e32 v138, 0x80, v138
	v_mfma_f32_16x16x32_bf16 v[78:81], v[192:195], v[180:183], v[78:81]
	v_mfma_f32_16x16x32_bf16 v[42:45], v[192:195], v[184:187], v[42:45]
	v_mfma_f32_16x16x32_bf16 v[118:121], v[196:199], v[172:175], v[118:121]
	s_add_u32 m0, s9, 0x2000
	v_mfma_f32_16x16x32_bf16 v[94:97], v[196:199], v[176:179], v[94:97]
	global_load_lds_dwordx4 v137, s[36:37]
	v_add_u32_e32 v137, 0x80, v137
	v_mfma_f32_16x16x32_bf16 v[58:61], v[196:199], v[180:183], v[58:61]
	v_mfma_f32_16x16x32_bf16 v[26:29], v[196:199], v[184:187], v[26:29]
	ds_read_b128 v[192:195], v141 offset:45056
	ds_read_b128 v[196:199], v141 offset:47104
	v_mfma_f32_16x16x32_bf16 v[114:117], v[200:203], v[172:175], v[114:117]
	s_add_u32 m0, s9, 0xa000
	v_mfma_f32_16x16x32_bf16 v[86:89], v[200:203], v[176:179], v[86:89]
	global_load_lds_dwordx4 v136, s[22:23]
	v_add_u32_e32 v136, 0x80, v136
	v_mfma_f32_16x16x32_bf16 v[54:57], v[200:203], v[180:183], v[54:57]
	v_mfma_f32_16x16x32_bf16 v[22:25], v[200:203], v[184:187], v[22:25]
	v_add_u32_e32 v140, v140, v148
	s_waitcnt lgkmcnt(0)
	v_mfma_f32_16x16x32_bf16 v[102:105], v[188:191], v[172:175], v[102:105]
	ds_read_b128 v[200:203], v140 offset:32768
	ds_read_b128 v[208:211], v140 offset:34816
	s_add_u32 m0, s9, 0x4000
	v_mfma_f32_16x16x32_bf16 v[74:77], v[188:191], v[176:179], v[74:77]
	global_load_lds_dwordx4 v135, s[36:37]
	v_add_u32_e32 v135, 0x80, v135
	v_mfma_f32_16x16x32_bf16 v[46:49], v[188:191], v[180:183], v[46:49]
	v_mfma_f32_16x16x32_bf16 v[10:13], v[188:191], v[184:187], v[10:13]
	ds_read_b128 v[188:191], v130
	ds_read_b128 v[212:215], v130 offset:2048
	ds_read_b128 v[216:219], v130 offset:4096
	ds_read_b128 v[220:223], v130 offset:6144
	v_mfma_f32_16x16x32_bf16 v[98:101], v[204:207], v[172:175], v[98:101]
	s_add_u32 m0, s9, 0xc000
	v_mfma_f32_16x16x32_bf16 v[66:69], v[204:207], v[176:179], v[66:69]
	global_load_lds_dwordx4 v134, s[22:23]
	v_add_u32_e32 v134, 0x80, v134
	v_mfma_f32_16x16x32_bf16 v[30:33], v[204:207], v[180:183], v[30:33]
	v_mfma_f32_16x16x32_bf16 v[6:9], v[204:207], v[184:187], v[6:9]
	v_mfma_f32_16x16x32_bf16 v[70:73], v[192:195], v[172:175], v[70:73]
	s_add_u32 m0, s9, 0x6000
	v_mfma_f32_16x16x32_bf16 v[62:65], v[196:199], v[172:175], v[62:65]
	global_load_lds_dwordx4 v133, s[36:37]
	v_add_u32_e32 v133, 0x80, v133
	v_mfma_f32_16x16x32_bf16 v[38:41], v[192:195], v[176:179], v[38:41]
	v_mfma_f32_16x16x32_bf16 v[34:37], v[196:199], v[176:179], v[34:37]
	ds_read_b128 v[172:175], v140 offset:36864
	ds_read_b128 v[176:179], v140 offset:38912
	v_mfma_f32_16x16x32_bf16 v[18:21], v[192:195], v[180:183], v[18:21]
	s_add_u32 m0, s9, 0xe000
	v_mfma_f32_16x16x32_bf16 v[14:17], v[196:199], v[180:183], v[14:17]
	global_load_lds_dwordx4 v132, s[22:23]
	v_add_u32_e32 v132, 0x80, v132
	v_mfma_f32_16x16x32_bf16 v[2:5], v[192:195], v[184:187], v[2:5]
	v_mfma_f32_16x16x32_bf16 v[90:93], v[196:199], v[184:187], v[90:93]
	ds_read_b128 v[180:183], v140 offset:40960
	ds_read_b128 v[184:187], v140 offset:43008
	s_waitcnt lgkmcnt(0)
; template <bool SWAP, class Epi, bool THIN = false> ...
;     ...
;       bf16x8 afA[4], afB[4], bfb[2][2];
; #pragma unroll
;       for (int m = 0; m < 4; ++m) afA[m] = *(const bf16x8*)(sa + m * 2048 + ((fq ^ swz) << 4));
; #pragma unroll
;       for (int n = 0; n < 2; ++n) bfb[0][n] = *(const bf16x8*)(sb + n * 2048 + ((fq ^ swz) << 4));
; #pragma unroll
;       for (int gq = 0; gq < 8; ++gq) {
;         const int ks = gq >> 2, nh = gq & 3;
;         if (gq < 7) {
;           const int ks2 = (gq + 1) >> 2, nh2 = (gq + 1) & 3;
; #pragma unroll
;           for (int n = 0; n < 2; ++n) bfb[(gq + 1) & 1][n] = *(const bf16x8*)(sb + (nh2 * 2 + n) * 2048 + (((ks2 * 4 + fq) ^ swz) << 4));
;         }
;         if (gq == 3) {
; #pragma unroll
;           for (int m = 0; m < 4; ++m) afB[m] = *(const bf16x8*)(sa + m * 2048 + (((4 + fq) ^ swz) << 4));
;         }
;         __builtin_amdgcn_sched_barrier(0);
; #pragma unroll
;         for (int m = 0; m < 4; ++m)
; #pragma unroll
;           for (int n = 0; n < 2; ++n) {
;             const bf16x8 av = ks ? afB[m] : afA[m];
;             acc[m][nh * 2 + n] = SWAP ? __builtin_amdgcn_mfma_f32_16x16x32_bf16(bfb[gq & 1][n], av, acc[m][nh * 2 + n], 0, 0, 0)
;                                       : __builtin_amdgcn_mfma_f32_16x16x32_bf16(av, bfb[gq & 1][n], acc[m][nh * 2 + n], 0, 0, 0);
;           }
;       }
	v_mfma_f32_16x16x32_bf16 v[126:129], v[200:203], v[188:191], v[126:129]
	v_mfma_f32_16x16x32_bf16 v[122:125], v[208:211], v[188:191], v[122:125]
	v_mfma_f32_16x16x32_bf16 v[110:113], v[200:203], v[212:215], v[110:113]
	v_mfma_f32_16x16x32_bf16 v[106:109], v[208:211], v[212:215], v[106:109]
	v_mfma_f32_16x16x32_bf16 v[82:85], v[200:203], v[216:219], v[82:85]
	v_mfma_f32_16x16x32_bf16 v[78:81], v[208:211], v[216:219], v[78:81]
	v_mfma_f32_16x16x32_bf16 v[50:53], v[200:203], v[220:223], v[50:53]
	v_mfma_f32_16x16x32_bf16 v[42:45], v[208:211], v[220:223], v[42:45]
	v_mfma_f32_16x16x32_bf16 v[118:121], v[172:175], v[188:191], v[118:121]
	v_mfma_f32_16x16x32_bf16 v[94:97], v[172:175], v[212:215], v[94:97]
	v_mfma_f32_16x16x32_bf16 v[58:61], v[172:175], v[216:219], v[58:61]
	v_mfma_f32_16x16x32_bf16 v[26:29], v[172:175], v[220:223], v[26:29]
	ds_read_b128 v[172:175], v140 offset:45056
	ds_read_b128 v[192:195], v140 offset:47104
	v_mfma_f32_16x16x32_bf16 v[114:117], v[176:179], v[188:191], v[114:117]
	v_mfma_f32_16x16x32_bf16 v[86:89], v[176:179], v[212:215], v[86:89]
	v_mfma_f32_16x16x32_bf16 v[54:57], v[176:179], v[216:219], v[54:57]
	v_mfma_f32_16x16x32_bf16 v[22:25], v[176:179], v[220:223], v[22:25]
	v_mfma_f32_16x16x32_bf16 v[102:105], v[180:183], v[188:191], v[102:105]
	v_mfma_f32_16x16x32_bf16 v[98:101], v[184:187], v[188:191], v[98:101]
	v_mfma_f32_16x16x32_bf16 v[74:77], v[180:183], v[212:215], v[74:77]
	v_mfma_f32_16x16x32_bf16 v[66:69], v[184:187], v[212:215], v[66:69]
	v_mfma_f32_16x16x32_bf16 v[46:49], v[180:183], v[216:219], v[46:49]
	v_mfma_f32_16x16x32_bf16 v[30:33], v[184:187], v[216:219], v[30:33]
	v_mfma_f32_16x16x32_bf16 v[10:13], v[180:183], v[220:223], v[10:13]
	v_mfma_f32_16x16x32_bf16 v[6:9], v[184:187], v[220:223], v[6:9]
	s_waitcnt lgkmcnt(0)
	v_mfma_f32_16x16x32_bf16 v[70:73], v[172:175], v[188:191], v[70:73]
	s_add_i32 s6, s6, 64
	s_cmpk_eq_i32 s6, 0x3c0
	s_mov_b32 s7, s8
	v_mfma_f32_16x16x32_bf16 v[62:65], v[192:195], v[188:191], v[62:65]
	v_mfma_f32_16x16x32_bf16 v[38:41], v[172:175], v[212:215], v[38:41]
	v_mfma_f32_16x16x32_bf16 v[34:37], v[192:195], v[212:215], v[34:37]
	v_mfma_f32_16x16x32_bf16 v[18:21], v[172:175], v[216:219], v[18:21]
	v_mfma_f32_16x16x32_bf16 v[14:17], v[192:195], v[216:219], v[14:17]
	v_mfma_f32_16x16x32_bf16 v[2:5], v[172:175], v[220:223], v[2:5]
	v_mfma_f32_16x16x32_bf16 v[90:93], v[192:195], v[220:223], v[90:93]
	s_cbranch_scc0 .LBB0_339
	s_waitcnt vmcnt(0)
	s_barrier
	v_add_u32_e32 v130, v159, v147
	ds_read_b128 v[132:135], v130
	ds_read_b128 v[136:139], v130 offset:2048
	ds_read_b128 v[172:175], v130 offset:4096
	ds_read_b128 v[176:179], v130 offset:6144
	v_add_u32_e32 v130, v160, v147
	ds_read_b128 v[180:183], v130
	ds_read_b128 v[184:187], v130 offset:2048
	ds_read_b128 v[188:191], v130 offset:4096
	ds_read_b128 v[192:195], v130 offset:6144
	s_waitcnt lgkmcnt(0)
	v_mfma_f32_16x16x32_bf16 v[126:129], v[180:183], v[132:135], v[126:129]
	v_mfma_f32_16x16x32_bf16 v[110:113], v[180:183], v[136:139], v[110:113]
	v_mfma_f32_16x16x32_bf16 v[82:85], v[180:183], v[172:175], v[82:85]
	v_mfma_f32_16x16x32_bf16 v[50:53], v[180:183], v[176:179], v[50:53]
	ds_read_b128 v[180:183], v130 offset:8192
	ds_read_b128 v[196:199], v130 offset:10240
	v_mfma_f32_16x16x32_bf16 v[122:125], v[184:187], v[132:135], v[122:125]
	v_mfma_f32_16x16x32_bf16 v[106:109], v[184:187], v[136:139], v[106:109]
	v_mfma_f32_16x16x32_bf16 v[78:81], v[184:187], v[172:175], v[78:81]
	v_mfma_f32_16x16x32_bf16 v[42:45], v[184:187], v[176:179], v[42:45]
	v_mfma_f32_16x16x32_bf16 v[118:121], v[188:191], v[132:135], v[118:121]
	v_mfma_f32_16x16x32_bf16 v[184:187], v[188:191], v[136:139], v[94:97]
	v_mfma_f32_16x16x32_bf16 v[204:207], v[188:191], v[172:175], v[58:61]
	v_mfma_f32_16x16x32_bf16 v[208:211], v[192:195], v[172:175], v[54:57]
	v_mfma_f32_16x16x32_bf16 v[188:191], v[188:191], v[176:179], v[26:29]
	s_nop 2
	ds_read_b128 v[26:29], v130 offset:12288
	ds_read_b128 v[54:57], v130 offset:14336
	v_mfma_f32_16x16x32_bf16 v[114:117], v[192:195], v[132:135], v[114:117]
	v_mfma_f32_16x16x32_bf16 v[200:203], v[192:195], v[136:139], v[86:89]
	v_mfma_f32_16x16x32_bf16 v[192:195], v[192:195], v[176:179], v[22:25]
	v_add_u32_e32 v130, v160, v148
	s_waitcnt lgkmcnt(0)
;   __device__ __forceinline__ float c4(int g, int rig, int col, f32x4 v) const {
;     ...
;     uint2 u; u.x = pack2(v[0], v[1]); u.y = pack2(v[2], v[3]);
; template <bool SWAP, class Epi, bool THIN = false> ...
;     ...
;       bf16x8 afA[4], afB[4], bfb[2][2];
; #pragma unroll
;       for (int m = 0; m < 4; ++m) afA[m] = *(const bf16x8*)(sa + m * 2048 + ((fq ^ swz) << 4));
; #pragma unroll
;       for (int n = 0; n < 2; ++n) bfb[0][n] = *(const bf16x8*)(sb + n * 2048 + ((fq ^ swz) << 4));
; #pragma unroll
;       for (int gq = 0; gq < 8; ++gq) {
;         const int ks = gq >> 2, nh = gq & 3;
;         if (gq < 7) {
;           const int ks2 = (gq + 1) >> 2, nh2 = (gq + 1) & 3;
; #pragma unroll
;           for (int n = 0; n < 2; ++n) bfb[(gq + 1) & 1][n] = *(const bf16x8*)(sb + (nh2 * 2 + n) * 2048 + (((ks2 * 4 + fq) ^ swz) << 4));
;         }
;         if (gq == 3) {
; #pragma unroll
;           for (int m = 0; m < 4; ++m) afB[m] = *(const bf16x8*)(sa + m * 2048 + (((4 + fq) ^ swz) << 4));
;         }
;         __builtin_amdgcn_sched_barrier(0);
; #pragma unroll
;         for (int m = 0; m < 4; ++m)
; #pragma unroll
;           for (int n = 0; n < 2; ++n) {
;             const bf16x8 av = ks ? afB[m] : afA[m];
;             acc[m][nh * 2 + n] = SWAP ? __builtin_amdgcn_mfma_f32_16x16x32_bf16(bfb[gq & 1][n], av, acc[m][nh * 2 + n], 0, 0, 0)
;                                       : __builtin_amdgcn_mfma_f32_16x16x32_bf16(av, bfb[gq & 1][n], acc[m][nh * 2 + n], 0, 0, 0);
;           }
;       }
;       }
;     }
;     __syncthreads();
;     const int te = get_tid512();
;     const int fr_e = te & 15, fq_e = (te & 63) >> 4, wr_e = te >> 7, wc_e = (te >> 6) & 1;
;     const int sub = 2 * mt + (wr_e >> 1);
;     const int g = sub / tpg, ti = sub - g * tpg;
;     const int rig0 = ti * step - halo;
;     const int rw = (wr_e & 1) * 64;
;     if constexpr (Epi::KIND == 0) {
; #pragma unroll
;       for (int m = 0; m < 4; ++m) {
;         const int rig = rig0 + rw + m * 16 + fr_e;
;         if constexpr (Epi::ROWSUM) {
;           float ss = 0.f;
; #pragma unroll
;           for (int n = 0; n < 8; ++n) {
;             const int col = nt * 256 + wc_e * 128 + n * 16 + fq_e * 4;
;             if (col < N) ss += epi.c4(g, rig, col, acc[m][n]);
;           }
;           ss += __shfl_xor(ss, 16); ss += __shfl_xor(ss, 32);
;           if (fq_e == 0) epi.rowsum(g, rig, nt * 2 + wc_e, ss);
	v_mfma_f32_16x16x32_bf16 v[212:215], v[196:199], v[172:175], v[30:33]
	ds_read_b128 v[22:25], v130
	ds_read_b128 v[86:89], v130 offset:2048
	s_nop 0
	v_add_u32_e32 v30, v159, v148
	v_mfma_f32_16x16x32_bf16 v[102:105], v[180:183], v[132:135], v[102:105]
	v_mfma_f32_16x16x32_bf16 v[74:77], v[180:183], v[136:139], v[74:77]
	v_mfma_f32_16x16x32_bf16 v[46:49], v[180:183], v[172:175], v[46:49]
	v_mfma_f32_16x16x32_bf16 v[10:13], v[180:183], v[176:179], v[10:13]
	ds_read_b128 v[180:183], v30
	ds_read_b128 v[216:219], v30 offset:2048
	ds_read_b128 v[220:223], v30 offset:4096
	ds_read_b128 v[224:227], v30 offset:6144
	v_mfma_f32_16x16x32_bf16 v[98:101], v[196:199], v[132:135], v[98:101]
	v_mfma_f32_16x16x32_bf16 v[66:69], v[196:199], v[136:139], v[66:69]
	v_mfma_f32_16x16x32_bf16 v[6:9], v[196:199], v[176:179], v[6:9]
	v_mfma_f32_16x16x32_bf16 v[196:199], v[26:29], v[172:175], v[18:21]
	v_mfma_f32_16x16x32_bf16 v[172:175], v[54:57], v[172:175], v[14:17]
	s_nop 2
	ds_read_b128 v[14:17], v130 offset:4096
	ds_read_b128 v[18:21], v130 offset:6144
	v_mfma_f32_16x16x32_bf16 v[70:73], v[26:29], v[132:135], v[70:73]
	v_mfma_f32_16x16x32_bf16 v[132:135], v[54:57], v[132:135], v[62:65]
	v_mfma_f32_16x16x32_bf16 v[38:41], v[26:29], v[136:139], v[38:41]
	v_mfma_f32_16x16x32_bf16 v[34:37], v[54:57], v[136:139], v[34:37]
	v_mfma_f32_16x16x32_bf16 v[2:5], v[26:29], v[176:179], v[2:5]
	v_mfma_f32_16x16x32_bf16 v[176:179], v[54:57], v[176:179], v[90:93]
	ds_read_b128 v[136:139], v130 offset:8192
	ds_read_b128 v[228:231], v130 offset:10240
	s_waitcnt lgkmcnt(0)
	v_mfma_f32_16x16x32_bf16 v[126:129], v[22:25], v[180:183], v[126:129]
	v_mfma_f32_16x16x32_bf16 v[122:125], v[86:89], v[180:183], v[122:125]
	v_mfma_f32_16x16x32_bf16 v[94:97], v[22:25], v[216:219], v[110:113]
	v_mfma_f32_16x16x32_bf16 v[90:93], v[86:89], v[216:219], v[106:109]
	v_mfma_f32_16x16x32_bf16 v[62:65], v[22:25], v[220:223], v[82:85]
	v_mfma_f32_16x16x32_bf16 v[58:61], v[86:89], v[220:223], v[78:81]
	v_mfma_f32_16x16x32_bf16 v[30:33], v[22:25], v[224:227], v[50:53]
	v_mfma_f32_16x16x32_bf16 v[26:29], v[86:89], v[224:227], v[42:45]
	v_mfma_f32_16x16x32_bf16 v[86:89], v[14:17], v[216:219], v[184:187]
	v_mfma_f32_16x16x32_bf16 v[22:25], v[14:17], v[224:227], v[188:191]
	s_nop 1
	ds_read_b128 v[184:187], v130 offset:12288
	ds_read_b128 v[188:191], v130 offset:14336
	v_mfma_f32_16x16x32_bf16 v[118:121], v[14:17], v[180:183], v[118:121]
	v_mfma_f32_16x16x32_bf16 v[114:117], v[18:21], v[180:183], v[114:117]
	v_mfma_f32_16x16x32_bf16 v[82:85], v[18:21], v[216:219], v[200:203]
	v_mfma_f32_16x16x32_bf16 v[54:57], v[14:17], v[220:223], v[204:207]
	v_mfma_f32_16x16x32_bf16 v[50:53], v[18:21], v[220:223], v[208:211]
	v_mfma_f32_16x16x32_bf16 v[18:21], v[18:21], v[224:227], v[192:195]
	v_mfma_f32_16x16x32_bf16 v[110:113], v[136:139], v[180:183], v[102:105]
	v_mfma_f32_16x16x32_bf16 v[106:109], v[228:231], v[180:183], v[98:101]
	v_mfma_f32_16x16x32_bf16 v[78:81], v[136:139], v[216:219], v[74:77]
	v_mfma_f32_16x16x32_bf16 v[74:77], v[228:231], v[216:219], v[66:69]
	v_mfma_f32_16x16x32_bf16 v[46:49], v[136:139], v[220:223], v[46:49]
	v_mfma_f32_16x16x32_bf16 v[42:45], v[228:231], v[220:223], v[212:215]
	v_mfma_f32_16x16x32_bf16 v[14:17], v[136:139], v[224:227], v[10:13]
	v_mfma_f32_16x16x32_bf16 v[6:9], v[228:231], v[224:227], v[6:9]
	s_nop 1
	v_mov_b32_e32 v10, v1
	s_waitcnt vmcnt(0) lgkmcnt(0)
	s_barrier
	v_mfma_f32_16x16x32_bf16 v[98:101], v[188:191], v[180:183], v[132:135]
	v_ashrrev_i32_e32 v11, 8, v10
	v_add_u32_e32 v11, s5, v11
	v_ashrrev_i32_e32 v12, 31, v11
	v_lshrrev_b32_e32 v12, 28, v12
	v_add_u32_e32 v12, v11, v12
	v_ashrrev_i32_e32 v138, 4, v12
	v_and_b32_e32 v132, 15, v10
	v_bfe_u32 v130, v10, 4, 2
	v_bfe_u32 v171, v10, 6, 1
	v_lshlrev_b32_e32 v12, 11, v138
	v_lshlrev_b32_e32 v11, 7, v11
	v_lshrrev_b32_e32 v10, 1, v10
	v_sub_u32_e32 v133, v11, v12
	v_and_b32_e32 v135, 64, v10
	v_lshlrev_b32_e32 v134, 7, v171
	v_mfma_f32_16x16x32_bf16 v[10:13], v[184:187], v[224:227], v[2:5]
	v_ashrrev_i32_e32 v139, 31, v138
	v_or3_b32 v132, v133, v135, v132
	v_ashrrev_i32_e32 v133, 31, v132
	v_lshlrev_b32_e32 v2, 2, v130
	v_mfma_f32_16x16x32_bf16 v[102:105], v[184:187], v[180:183], v[70:73]
	v_or3_b32 v134, v134, v2, s4
	v_lshlrev_b64 v[136:137], 21, v[138:139]
	v_cmp_gt_i32_e32 vcc, s29, v134
	v_mfma_f32_16x16x32_bf16 v[70:73], v[184:187], v[216:219], v[38:41]
	v_lshlrev_b64 v[140:141], 10, v[132:133]
	v_ashrrev_i32_e32 v135, 31, v134
	v_lshl_add_u64 v[136:137], s[38:39], 0, v[136:137]
	v_mfma_f32_16x16x32_bf16 v[66:69], v[188:191], v[216:219], v[34:37]
	v_mfma_f32_16x16x32_bf16 v[38:41], v[184:187], v[220:223], v[196:199]
	v_mfma_f32_16x16x32_bf16 v[34:37], v[188:191], v[220:223], v[172:175]
	v_mfma_f32_16x16x32_bf16 v[2:5], v[188:191], v[224:227], v[176:179]
	s_nop 1
	v_mov_b32_e32 v172, 0
	s_and_saveexec_b64 s[4:5], vcc
	s_cbranch_execz .LBB0_342
	v_cvt_pk_bf16_f32 v172, v126, v127
	v_pk_mul_f32 v[126:127], v[126:127], v[126:127]
	v_cvt_pk_bf16_f32 v173, v128, v129
	v_lshl_add_u64 v[174:175], v[136:137], 0, v[140:141]
	v_pk_mul_f32 v[128:129], v[128:129], v[128:129]
	v_add_f32_e32 v126, v126, v127
	v_lshl_add_u64 v[174:175], v[134:135], 1, v[174:175]
	v_add_f32_e32 v126, v128, v126
	global_store_dwordx2 v[174:175], v[172:173], off
	v_add_f32_e32 v172, v129, v126

; #define GLDS16(gp, lp) __builtin_amdgcn_global_load_lds((const unsigned*)(gp), (__attribute__((address_space(3))) unsigned*)(lp), 16, 0, 0)
; template <bool SWAP, class Epi, bool THIN = false> ...
;     ...
;   for (; v < voff + ntiles; v += grid) {
;     const int w = v - voff;
;     int mt, nt;
;     if (w < full * 8 * NT) { const int sr = w / (8 * NT), rem = w - sr * 8 * NT; nt = rem >> 3; mt = sr * 8 + (rem & 7); }
;     else { const int w2 = w - full * 8 * NT, rl = MT - full * 8; nt = w2 / rl; mt = full * 8 + (w2 - nt * rl); }
;     unsigned ap[4], bp[4];
; #pragma unroll
;     for (int i = 0; i < 4; ++i) {
;       const int r = (tid >> 3) + 64 * i;
;       const int cs = tid & 7;
;       const int c = ((cs ^ ((r >> 1) & 7)) << 3);
;       const int sub = 2 * mt + (r >> 7);
;       const int g = sub / tpg, ti = sub - g * tpg;
;       int rig = ti * step - halo + (r & 127); rig = rig < 0 ? 0 : (rig > grows - 1 ? grows - 1 : rig);
;       ap[i] = (unsigned)((g * a_gstride + a_goff + rig) * lda + c);
;       int br = nt * 256 + r; br = br > N - 1 ? N - 1 : br;
;       bp[i] = (unsigned)(br * K + c);
;     }
;     const bool have_next = false;
;     f32x4 acc[4][8];
; #pragma unroll
;     for (int m = 0; m < 4; ++m)
; #pragma unroll
;       for (int n = 0; n < 8; ++n) acc[m][n] = (f32x4){0.f, 0.f, 0.f, 0.f};
;     if (!pre_issued) {
; #pragma unroll
;       for (int i = 0; i < 4; ++i) { GLDS16(A + (size_t)ap[i], smem + tid * 16 + i * 8192); GLDS16(Bt + (size_t)bp[i], smem + 32768 + tid * 16 + i * 8192); }
;     }
;     pre_issued = have_next;
.LBB0_417:
	s_add_i32 s4, s22, 0xffffff80
	s_ashr_i32 s5, s4, 31
	s_lshr_b32 s5, s5, 29
	s_add_i32 s5, s4, s5
	s_and_b32 s5, s5, -8
	s_sub_i32 s4, s4, s5
	s_ashr_i32 s20, s4, 3
	s_and_b32 s4, s22, 7
	s_or_b32 s4, s5, s4
	s_lshl_b32 s5, s4, 1
	v_add_u32_e32 v2, s5, v143
	v_mul_hi_i32 v3, v2, s23
	v_lshrrev_b32_e32 v4, 31, v3
	v_ashrrev_i32_e32 v3, 2, v3
	v_add_u32_e32 v26, v3, v4
	v_mad_u64_u32 v[2:3], s[6:7], v26, s24, v[2:3]
	v_lshl_or_b32 v3, v2, 7, v144
	v_min_i32_e32 v3, 0x8ff, v3
	v_cmp_lt_i32_e32 vcc, -1, v2
	v_add_u32_e32 v6, s5, v146
	s_lshl_b32 s4, s20, 8
	v_cndmask_b32_e32 v2, 0, v3, vcc
	v_mad_u64_u32 v[4:5], s[6:7], v26, s25, v[2:3]
	v_mul_hi_i32 v5, v6, s23
	v_lshrrev_b32_e32 v7, 31, v5
	v_ashrrev_i32_e32 v5, 2, v5
	v_add_u32_e32 v27, v5, v7
	v_mad_u64_u32 v[6:7], s[6:7], v27, s24, v[6:7]
	v_lshl_or_b32 v5, v6, 7, v147
	v_min_i32_e32 v5, 0x8ff, v5
	v_cmp_lt_i32_e32 vcc, -1, v6
	v_add_u32_e32 v12, s5, v149
	v_add_u32_e32 v18, s5, v151
	v_cndmask_b32_e32 v6, 0, v5, vcc
	v_add_u32_e32 v5, s4, v145
	v_min_i32_e32 v5, 0xff, v5
	v_mad_u64_u32 v[8:9], s[6:7], v27, s25, v[6:7]
	v_lshlrev_b32_e32 v7, 10, v5
	v_mul_hi_i32 v5, v12, s23
	v_lshrrev_b32_e32 v9, 31, v5
	v_ashrrev_i32_e32 v5, 2, v5
	v_add_u32_e32 v28, v5, v9
	v_mad_u64_u32 v[12:13], s[6:7], v28, s24, v[12:13]
	v_lshl_or_b32 v5, v12, 7, v144
	v_min_i32_e32 v5, 0x8ff, v5
	v_cmp_lt_i32_e32 vcc, -1, v12
	v_add_u32_e32 v3, s4, v136
	v_min_i32_e32 v3, 0xff, v3
	v_cndmask_b32_e32 v12, 0, v5, vcc
	v_add_u32_e32 v5, s4, v148
	v_min_i32_e32 v5, 0xff, v5
	v_mad_u64_u32 v[14:15], s[6:7], v28, s25, v[12:13]
	v_lshlrev_b32_e32 v13, 10, v5
	v_mul_hi_i32 v5, v18, s23
	v_lshrrev_b32_e32 v9, 31, v5
	v_ashrrev_i32_e32 v5, 2, v5
	v_add_u32_e32 v29, v5, v9
	v_mad_u64_u32 v[18:19], s[6:7], v29, s24, v[18:19]
	v_lshl_or_b32 v5, v18, 7, v152
	v_min_i32_e32 v5, 0x8ff, v5
	v_cmp_lt_i32_e32 vcc, -1, v18
	v_lshl_or_b32 v130, v4, 10, v137
	v_lshlrev_b32_e32 v3, 10, v3
	v_cndmask_b32_e32 v18, 0, v5, vcc
	v_mad_u64_u32 v[20:21], s[6:7], v29, s25, v[18:19]
	v_add_u32_e32 v5, s4, v150
	v_min_i32_e32 v5, 0xff, v5
	v_readfirstlane_b32 s6, v138
	v_or_b32_e32 v4, v3, v137
	v_lshlrev_b32_e32 v19, 10, v5
	v_lshl_add_u64 v[24:25], v[130:131], 1, s[36:37]
	s_mov_b32 m0, s6
	v_mov_b32_e32 v5, v131
	v_readfirstlane_b32 s6, v156
	v_lshl_or_b32 v8, v8, 10, v137
	global_load_lds_dwordx4 v[24:25], off
	s_waitcnt lgkmcnt(0)
	v_lshl_add_u64 v[4:5], v[4:5], 1, s[38:39]
	s_mov_b32 m0, s6
	v_mov_b32_e32 v9, v131
	v_readfirstlane_b32 s6, v157
	v_or_b32_e32 v10, v7, v137
	global_load_lds_dwordx4 v[4:5], off
	v_lshl_add_u64 v[4:5], v[8:9], 1, s[36:37]
	s_mov_b32 m0, s6
	v_mov_b32_e32 v11, v131
	v_readfirstlane_b32 s6, v158
	v_lshl_or_b32 v14, v14, 10, v137
	global_load_lds_dwordx4 v[4:5], off
	v_lshl_add_u64 v[4:5], v[10:11], 1, s[38:39]
	s_mov_b32 m0, s6
	v_mov_b32_e32 v15, v131
	v_readfirstlane_b32 s6, v159
	v_or_b32_e32 v16, v13, v137
	global_load_lds_dwordx4 v[4:5], off
	v_lshl_add_u64 v[4:5], v[14:15], 1, s[36:37]
	s_mov_b32 m0, s6
	v_mov_b32_e32 v17, v131
	v_readfirstlane_b32 s6, v160
	v_lshl_or_b32 v20, v20, 10, v137
	global_load_lds_dwordx4 v[4:5], off
	v_lshl_add_u64 v[4:5], v[16:17], 1, s[38:39]
	s_mov_b32 m0, s6
	v_mov_b32_e32 v21, v131
	v_readfirstlane_b32 s6, v161
	v_or_b32_e32 v22, v19, v137
	global_load_lds_dwordx4 v[4:5], off
	v_lshl_add_u64 v[4:5], v[20:21], 1, s[36:37]
	s_mov_b32 m0, s6
	v_mov_b32_e32 v23, v131
	v_readfirstlane_b32 s6, v162
	global_load_lds_dwordx4 v[4:5], off
	v_lshl_add_u64 v[4:5], v[22:23], 1, s[38:39]
	s_mov_b32 m0, s6
	v_or_b32_e32 v166, v155, v3
	global_load_lds_dwordx4 v[4:5], off
	v_mul_lo_u32 v4, v29, s26
	v_or_b32_e32 v4, v155, v4
	v_lshl_add_u32 v133, v18, 10, v4
	v_mul_lo_u32 v4, v28, s26
	v_or_b32_e32 v4, v155, v4
	v_lshl_add_u32 v135, v12, 10, v4
	v_mul_lo_u32 v4, v27, s26
	v_mul_lo_u32 v3, v26, s26
	v_or_b32_e32 v4, v155, v4
	v_or_b32_e32 v3, v155, v3
	v_or_b32_e32 v132, v155, v19
	v_or_b32_e32 v134, v155, v13
	v_or_b32_e32 v164, v155, v7
	v_lshl_add_u32 v165, v6, 10, v4
	v_lshl_add_u32 v167, v2, 10, v3
	s_mov_b32 s6, 0
	s_mov_b32 s7, 0
	v_mov_b32_e32 v90, v131
	v_mov_b32_e32 v91, v131
	v_mov_b32_e32 v92, v131
	v_mov_b32_e32 v93, v131
	v_mov_b32_e32 v2, v131
	v_mov_b32_e32 v3, v131
	v_mov_b32_e32 v4, v131
	v_mov_b32_e32 v5, v131
	v_mov_b32_e32 v6, v131
	v_mov_b32_e32 v7, v131
	v_mov_b32_e32 v8, v131
	v_mov_b32_e32 v10, v131
	v_mov_b32_e32 v12, v131
	v_mov_b32_e32 v13, v131
	v_mov_b32_e32 v22, v131
	v_mov_b32_e32 v24, v131
	v_mov_b32_e32 v25, v131
	v_mov_b32_e32 v26, v131
	v_mov_b32_e32 v27, v131
	v_mov_b32_e32 v28, v131
	v_mov_b32_e32 v29, v131
	v_mov_b32_e32 v42, v131
	v_mov_b32_e32 v43, v131
	v_mov_b32_e32 v44, v131
	v_mov_b32_e32 v45, v131
	v_mov_b32_e32 v50, v131
	v_mov_b32_e32 v51, v131
	v_mov_b32_e32 v52, v131
	v_mov_b32_e32 v53, v131
	v_mov_b32_e32 v14, v131
	v_mov_b32_e32 v16, v131
	v_mov_b32_e32 v18, v131
	v_mov_b32_e32 v19, v131
	v_mov_b32_e32 v20, v131
	v_mov_b32_e32 v30, v131
	v_mov_b32_e32 v31, v131
	v_mov_b32_e32 v32, v131
	v_mov_b32_e32 v33, v131
	v_mov_b32_e32 v46, v131
	v_mov_b32_e32 v47, v131
	v_mov_b32_e32 v48, v131
	v_mov_b32_e32 v49, v131
	v_mov_b32_e32 v54, v131
	v_mov_b32_e32 v55, v131
	v_mov_b32_e32 v56, v131
	v_mov_b32_e32 v57, v131
	v_mov_b32_e32 v58, v131
	v_mov_b32_e32 v59, v131
	v_mov_b32_e32 v60, v131
	v_mov_b32_e32 v61, v131
	v_mov_b32_e32 v78, v131
	v_mov_b32_e32 v79, v131
	v_mov_b32_e32 v80, v131
	v_mov_b32_e32 v81, v131
	v_mov_b32_e32 v82, v131
	v_mov_b32_e32 v83, v131
	v_mov_b32_e32 v84, v131
	v_mov_b32_e32 v85, v131
	v_mov_b32_e32 v34, v131
	v_mov_b32_e32 v35, v131
	v_mov_b32_e32 v36, v131
	v_mov_b32_e32 v37, v131
	v_mov_b32_e32 v38, v131
; template <bool SWAP, class Epi, bool THIN = false> ...
;     ...
;     for (int st = 0; st < ns; ++st) {
;       asm volatile("s_waitcnt vmcnt(0)" ::: "memory");
;       __builtin_amdgcn_s_barrier();
;       asm volatile("" ::: "memory");
;       if (st + 1 < ns) {
;         char* nb = smem + ((st + 1) & 1) * 65536;
;         const int ko = (st + 1) * 64;
; #pragma unroll
;         for (int i = 0; i < 4; ++i) { GLDS16(A + (size_t)(ap[i] + ko), nb + tid * 16 + i * 8192); GLDS16(Bt + (size_t)(bp[i] + ko), nb + 32768 + tid * 16 + i * 8192); }
;       }
;       const char* sa = smem + (st & 1) * 65536 + (wr * 64 + fr) * 128;
;       const char* sb = smem + (st & 1) * 65536 + 32768 + (wc * 128 + fr) * 128;
;       if constexpr (THIN) {
;         if (wc == 0) {
; #pragma unroll
;           for (int ks = 0; ks < 2; ++ks) {
;             bf16x8 af[4], bf[2];
; #pragma unroll
;             for (int m = 0; m < 4; ++m) af[m] = *(const bf16x8*)(sa + m * 2048 + (((ks * 4 + fq) ^ swz) << 4));
; #pragma unroll
;             for (int n = 0; n < 2; ++n) bf[n] = *(const bf16x8*)(sb + n * 2048 + (((ks * 4 + fq) ^ swz) << 4));
; #pragma unroll
;             for (int m = 0; m < 4; ++m)
; #pragma unroll
;               for (int n = 0; n < 2; ++n)
;                 acc[m][n] = SWAP ? __builtin_amdgcn_mfma_f32_16x16x32_bf16(bf[n], af[m], acc[m][n], 0, 0, 0)
;                                  : __builtin_amdgcn_mfma_f32_16x16x32_bf16(af[m], bf[n], acc[m][n], 0, 0, 0);
;           }
;         }
;       } else {
;       bf16x8 afA[4], afB[4], bfb[2][2];
; #pragma unroll
;       for (int m = 0; m < 4; ++m) afA[m] = *(const bf16x8*)(sa + m * 2048 + ((fq ^ swz) << 4));
; #pragma unroll
;       for (int n = 0; n < 2; ++n) bfb[0][n] = *(const bf16x8*)(sb + n * 2048 + ((fq ^ swz) << 4));
; #pragma unroll
;       for (int gq = 0; gq < 8; ++gq) {
;         const int ks = gq >> 2, nh = gq & 3;
;         if (gq < 7) {
;           const int ks2 = (gq + 1) >> 2, nh2 = (gq + 1) & 3;
; #pragma unroll
;           for (int n = 0; n < 2; ++n) bfb[(gq + 1) & 1][n] = *(const bf16x8*)(sb + (nh2 * 2 + n) * 2048 + (((ks2 * 4 + fq) ^ swz) << 4));
;         }
;         if (gq == 3) {
; #pragma unroll
;           for (int m = 0; m < 4; ++m) afB[m] = *(const bf16x8*)(sa + m * 2048 + (((4 + fq) ^ swz) << 4));
;         }
;         __builtin_amdgcn_sched_barrier(0);
; #pragma unroll
	v_mov_b32_e32 v39, v131
	v_mov_b32_e32 v40, v131
	v_mov_b32_e32 v41, v131
	v_mov_b32_e32 v66, v131
	v_mov_b32_e32 v67, v131
	v_mov_b32_e32 v68, v131
	v_mov_b32_e32 v69, v131
	v_mov_b32_e32 v74, v131
	v_mov_b32_e32 v75, v131
	v_mov_b32_e32 v76, v131
	v_mov_b32_e32 v77, v131
	v_mov_b32_e32 v86, v131
	v_mov_b32_e32 v87, v131
	v_mov_b32_e32 v88, v131
	v_mov_b32_e32 v89, v131
	v_mov_b32_e32 v94, v131
	v_mov_b32_e32 v95, v131
	v_mov_b32_e32 v96, v131
	v_mov_b32_e32 v97, v131
	v_mov_b32_e32 v106, v131
	v_mov_b32_e32 v107, v131
	v_mov_b32_e32 v108, v131
	v_mov_b32_e32 v109, v131
	v_mov_b32_e32 v110, v131
	v_mov_b32_e32 v111, v131
	v_mov_b32_e32 v112, v131
	v_mov_b32_e32 v113, v131
	v_mov_b32_e32 v62, v131
	v_mov_b32_e32 v63, v131
	v_mov_b32_e32 v64, v131
	v_mov_b32_e32 v65, v131
	v_mov_b32_e32 v70, v131
	v_mov_b32_e32 v71, v131
	v_mov_b32_e32 v72, v131
	v_mov_b32_e32 v73, v131
	v_mov_b32_e32 v98, v131
	v_mov_b32_e32 v99, v131
	v_mov_b32_e32 v100, v131
	v_mov_b32_e32 v101, v131
	v_mov_b32_e32 v102, v131
	v_mov_b32_e32 v103, v131
	v_mov_b32_e32 v104, v131
	v_mov_b32_e32 v105, v131
	v_mov_b32_e32 v114, v131
	v_mov_b32_e32 v115, v131
	v_mov_b32_e32 v116, v131
	v_mov_b32_e32 v117, v131
	v_mov_b32_e32 v118, v131
	v_mov_b32_e32 v119, v131
	v_mov_b32_e32 v120, v131
	v_mov_b32_e32 v121, v131
	v_mov_b32_e32 v122, v131
	v_mov_b32_e32 v123, v131
	v_mov_b32_e32 v124, v131
	v_mov_b32_e32 v125, v131
	v_mov_b32_e32 v126, v131
	v_mov_b32_e32 v127, v131
	v_mov_b32_e32 v128, v131
	v_mov_b32_e32 v129, v131
	v_lshlrev_b32_e32 v167, 1, v167
	v_lshlrev_b32_e32 v166, 1, v166
	v_lshlrev_b32_e32 v165, 1, v165
	v_lshlrev_b32_e32 v164, 1, v164
	v_lshlrev_b32_e32 v135, 1, v135
	v_lshlrev_b32_e32 v134, 1, v134
	v_lshlrev_b32_e32 v133, 1, v133
	v_lshlrev_b32_e32 v132, 1, v132
.LBB0_418:
	s_add_i32 s8, s7, 0x10000
	s_and_b32 s9, s8, 0x10000
	v_add_u32_e32 v170, s9, v138
	s_nop 0
	v_readfirstlane_b32 s9, v170
	s_waitcnt vmcnt(0)
	s_barrier
	s_and_b32 s7, s7, 0x10000
	v_or_b32_e32 v204, s7, v140
	v_add_u32_e32 v205, v204, v141
	v_add_u32_e32 v130, s7, v139
	v_add_u32_e32 v180, v130, v141
	ds_read_b128 v[168:171], v180
	ds_read_b128 v[172:175], v180 offset:2048
	ds_read_b128 v[176:179], v180 offset:4096
	ds_read_b128 v[180:183], v180 offset:6144
	ds_read_b128 v[184:187], v205 offset:32768
	ds_read_b128 v[188:191], v205 offset:34816
	ds_read_b128 v[192:195], v205 offset:36864
	ds_read_b128 v[196:199], v205 offset:38912
	v_add_u32_e32 v130, v130, v142
	s_waitcnt lgkmcnt(0)
	v_mfma_f32_16x16x32_bf16 v[126:129], v[184:187], v[168:171], v[126:129]
	s_mov_b32 m0, s9
	v_mfma_f32_16x16x32_bf16 v[110:113], v[184:187], v[172:175], v[110:113]
	global_load_lds_dwordx4 v167, s[36:37]
	v_add_u32_e32 v167, 0x80, v167
	v_mfma_f32_16x16x32_bf16 v[82:85], v[184:187], v[176:179], v[82:85]
	v_mfma_f32_16x16x32_bf16 v[50:53], v[184:187], v[180:183], v[50:53]
	ds_read_b128 v[184:187], v205 offset:40960
	ds_read_b128 v[200:203], v205 offset:43008
	v_mfma_f32_16x16x32_bf16 v[122:125], v[188:191], v[168:171], v[122:125]
	s_add_u32 m0, s9, 0x8000
	v_mfma_f32_16x16x32_bf16 v[106:109], v[188:191], v[172:175], v[106:109]
	global_load_lds_dwordx4 v166, s[38:39]
	v_add_u32_e32 v166, 0x80, v166
	v_mfma_f32_16x16x32_bf16 v[78:81], v[188:191], v[176:179], v[78:81]
	v_mfma_f32_16x16x32_bf16 v[42:45], v[188:191], v[180:183], v[42:45]
	v_mfma_f32_16x16x32_bf16 v[118:121], v[192:195], v[168:171], v[118:121]
	s_add_u32 m0, s9, 0x2000
	v_mfma_f32_16x16x32_bf16 v[94:97], v[192:195], v[172:175], v[94:97]
	global_load_lds_dwordx4 v165, s[36:37]
	v_add_u32_e32 v165, 0x80, v165
	v_mfma_f32_16x16x32_bf16 v[58:61], v[192:195], v[176:179], v[58:61]
	v_mfma_f32_16x16x32_bf16 v[26:29], v[192:195], v[180:183], v[26:29]
	ds_read_b128 v[188:191], v205 offset:45056
	ds_read_b128 v[192:195], v205 offset:47104
	v_mfma_f32_16x16x32_bf16 v[114:117], v[196:199], v[168:171], v[114:117]
	s_add_u32 m0, s9, 0xa000
	v_mfma_f32_16x16x32_bf16 v[86:89], v[196:199], v[172:175], v[86:89]
	global_load_lds_dwordx4 v164, s[38:39]
	v_add_u32_e32 v164, 0x80, v164
	v_mfma_f32_16x16x32_bf16 v[54:57], v[196:199], v[176:179], v[54:57]
	v_mfma_f32_16x16x32_bf16 v[22:25], v[196:199], v[180:183], v[22:25]
	v_add_u32_e32 v220, v204, v142
	s_waitcnt lgkmcnt(0)
	v_mfma_f32_16x16x32_bf16 v[102:105], v[184:187], v[168:171], v[102:105]
	ds_read_b128 v[196:199], v220 offset:32768
	ds_read_b128 v[204:207], v220 offset:34816
	s_add_u32 m0, s9, 0x4000
	v_mfma_f32_16x16x32_bf16 v[74:77], v[184:187], v[172:175], v[74:77]
	global_load_lds_dwordx4 v135, s[36:37]
	v_add_u32_e32 v135, 0x80, v135
	v_mfma_f32_16x16x32_bf16 v[46:49], v[184:187], v[176:179], v[46:49]
	v_mfma_f32_16x16x32_bf16 v[10:13], v[184:187], v[180:183], v[10:13]
	ds_read_b128 v[184:187], v130
	ds_read_b128 v[208:211], v130 offset:2048
	ds_read_b128 v[212:215], v130 offset:4096
	ds_read_b128 v[216:219], v130 offset:6144
	v_mfma_f32_16x16x32_bf16 v[98:101], v[200:203], v[168:171], v[98:101]
	s_add_u32 m0, s9, 0xc000
	v_mfma_f32_16x16x32_bf16 v[66:69], v[200:203], v[172:175], v[66:69]
	global_load_lds_dwordx4 v134, s[38:39]
	v_add_u32_e32 v134, 0x80, v134
	v_mfma_f32_16x16x32_bf16 v[30:33], v[200:203], v[176:179], v[30:33]
	v_mfma_f32_16x16x32_bf16 v[6:9], v[200:203], v[180:183], v[6:9]
	v_mfma_f32_16x16x32_bf16 v[70:73], v[188:191], v[168:171], v[70:73]
	s_add_u32 m0, s9, 0x6000
	v_mfma_f32_16x16x32_bf16 v[62:65], v[192:195], v[168:171], v[62:65]
	global_load_lds_dwordx4 v133, s[36:37]
	v_add_u32_e32 v133, 0x80, v133
	v_mfma_f32_16x16x32_bf16 v[38:41], v[188:191], v[172:175], v[38:41]
	v_mfma_f32_16x16x32_bf16 v[34:37], v[192:195], v[172:175], v[34:37]
	ds_read_b128 v[168:171], v220 offset:36864
	ds_read_b128 v[172:175], v220 offset:38912
	v_mfma_f32_16x16x32_bf16 v[18:21], v[188:191], v[176:179], v[18:21]
	s_add_u32 m0, s9, 0xe000
	v_mfma_f32_16x16x32_bf16 v[14:17], v[192:195], v[176:179], v[14:17]
	global_load_lds_dwordx4 v132, s[38:39]
	v_add_u32_e32 v132, 0x80, v132
	v_mfma_f32_16x16x32_bf16 v[2:5], v[188:191], v[180:183], v[2:5]
	v_mfma_f32_16x16x32_bf16 v[90:93], v[192:195], v[180:183], v[90:93]
	ds_read_b128 v[176:179], v220 offset:40960
	ds_read_b128 v[180:183], v220 offset:43008
	s_waitcnt lgkmcnt(0)
; template <bool SWAP, class Epi, bool THIN = false> ...
;     ...
;       bf16x8 afA[4], afB[4], bfb[2][2];
; #pragma unroll
;       for (int m = 0; m < 4; ++m) afA[m] = *(const bf16x8*)(sa + m * 2048 + ((fq ^ swz) << 4));
; #pragma unroll
;       for (int n = 0; n < 2; ++n) bfb[0][n] = *(const bf16x8*)(sb + n * 2048 + ((fq ^ swz) << 4));
; #pragma unroll
;       for (int gq = 0; gq < 8; ++gq) {
;         const int ks = gq >> 2, nh = gq & 3;
;         if (gq < 7) {
;           const int ks2 = (gq + 1) >> 2, nh2 = (gq + 1) & 3;
; #pragma unroll
;           for (int n = 0; n < 2; ++n) bfb[(gq + 1) & 1][n] = *(const bf16x8*)(sb + (nh2 * 2 + n) * 2048 + (((ks2 * 4 + fq) ^ swz) << 4));
;         }
;         if (gq == 3) {
; #pragma unroll
;           for (int m = 0; m < 4; ++m) afB[m] = *(const bf16x8*)(sa + m * 2048 + (((4 + fq) ^ swz) << 4));
;         }
;         __builtin_amdgcn_sched_barrier(0);
; #pragma unroll
;         for (int m = 0; m < 4; ++m)
; #pragma unroll
;           for (int n = 0; n < 2; ++n) {
;             const bf16x8 av = ks ? afB[m] : afA[m];
;             acc[m][nh * 2 + n] = SWAP ? __builtin_amdgcn_mfma_f32_16x16x32_bf16(bfb[gq & 1][n], av, acc[m][nh * 2 + n], 0, 0, 0)
;                                       : __builtin_amdgcn_mfma_f32_16x16x32_bf16(av, bfb[gq & 1][n], acc[m][nh * 2 + n], 0, 0, 0);
;           }
;       }
	v_mfma_f32_16x16x32_bf16 v[126:129], v[196:199], v[184:187], v[126:129]
	v_mfma_f32_16x16x32_bf16 v[122:125], v[204:207], v[184:187], v[122:125]
	v_mfma_f32_16x16x32_bf16 v[110:113], v[196:199], v[208:211], v[110:113]
	v_mfma_f32_16x16x32_bf16 v[106:109], v[204:207], v[208:211], v[106:109]
	v_mfma_f32_16x16x32_bf16 v[82:85], v[196:199], v[212:215], v[82:85]
	v_mfma_f32_16x16x32_bf16 v[78:81], v[204:207], v[212:215], v[78:81]
	v_mfma_f32_16x16x32_bf16 v[50:53], v[196:199], v[216:219], v[50:53]
	v_mfma_f32_16x16x32_bf16 v[42:45], v[204:207], v[216:219], v[42:45]
	v_mfma_f32_16x16x32_bf16 v[118:121], v[168:171], v[184:187], v[118:121]
	v_mfma_f32_16x16x32_bf16 v[94:97], v[168:171], v[208:211], v[94:97]
	v_mfma_f32_16x16x32_bf16 v[58:61], v[168:171], v[212:215], v[58:61]
	v_mfma_f32_16x16x32_bf16 v[26:29], v[168:171], v[216:219], v[26:29]
	ds_read_b128 v[168:171], v220 offset:45056
	ds_read_b128 v[188:191], v220 offset:47104
	v_mfma_f32_16x16x32_bf16 v[114:117], v[172:175], v[184:187], v[114:117]
	v_mfma_f32_16x16x32_bf16 v[86:89], v[172:175], v[208:211], v[86:89]
	v_mfma_f32_16x16x32_bf16 v[54:57], v[172:175], v[212:215], v[54:57]
	v_mfma_f32_16x16x32_bf16 v[22:25], v[172:175], v[216:219], v[22:25]
	v_mfma_f32_16x16x32_bf16 v[102:105], v[176:179], v[184:187], v[102:105]
	v_mfma_f32_16x16x32_bf16 v[98:101], v[180:183], v[184:187], v[98:101]
	v_mfma_f32_16x16x32_bf16 v[74:77], v[176:179], v[208:211], v[74:77]
	v_mfma_f32_16x16x32_bf16 v[66:69], v[180:183], v[208:211], v[66:69]
	v_mfma_f32_16x16x32_bf16 v[46:49], v[176:179], v[212:215], v[46:49]
	v_mfma_f32_16x16x32_bf16 v[30:33], v[180:183], v[212:215], v[30:33]
	v_mfma_f32_16x16x32_bf16 v[10:13], v[176:179], v[216:219], v[10:13]
	v_mfma_f32_16x16x32_bf16 v[6:9], v[180:183], v[216:219], v[6:9]
	s_waitcnt lgkmcnt(0)
	v_mfma_f32_16x16x32_bf16 v[70:73], v[168:171], v[184:187], v[70:73]
	s_add_i32 s6, s6, 64
	s_cmpk_eq_i32 s6, 0x3c0
	s_mov_b32 s7, s8
	v_mfma_f32_16x16x32_bf16 v[62:65], v[188:191], v[184:187], v[62:65]
	v_mfma_f32_16x16x32_bf16 v[38:41], v[168:171], v[208:211], v[38:41]
	v_mfma_f32_16x16x32_bf16 v[34:37], v[188:191], v[208:211], v[34:37]
	v_mfma_f32_16x16x32_bf16 v[18:21], v[168:171], v[212:215], v[18:21]
	v_mfma_f32_16x16x32_bf16 v[14:17], v[188:191], v[212:215], v[14:17]
	v_mfma_f32_16x16x32_bf16 v[2:5], v[168:171], v[216:219], v[2:5]
	v_mfma_f32_16x16x32_bf16 v[90:93], v[188:191], v[216:219], v[90:93]
	s_cbranch_scc0 .LBB0_418
	s_waitcnt vmcnt(0)
	s_barrier
;   __device__ __forceinline__ float c4(int g, int rig, int col, f32x4 v) const {
;     ...
;     uint2 u; u.x = pack2(v[0], v[1]); u.y = pack2(v[2], v[3]);
; template <bool SWAP, class Epi, bool THIN = false> ...
;     ...
;       bf16x8 afA[4], afB[4], bfb[2][2];
; #pragma unroll
;       for (int m = 0; m < 4; ++m) afA[m] = *(const bf16x8*)(sa + m * 2048 + ((fq ^ swz) << 4));
; #pragma unroll
;       for (int n = 0; n < 2; ++n) bfb[0][n] = *(const bf16x8*)(sb + n * 2048 + ((fq ^ swz) << 4));
; #pragma unroll
;       for (int gq = 0; gq < 8; ++gq) {
;         const int ks = gq >> 2, nh = gq & 3;
;         if (gq < 7) {
;           const int ks2 = (gq + 1) >> 2, nh2 = (gq + 1) & 3;
; #pragma unroll
;           for (int n = 0; n < 2; ++n) bfb[(gq + 1) & 1][n] = *(const bf16x8*)(sb + (nh2 * 2 + n) * 2048 + (((ks2 * 4 + fq) ^ swz) << 4));
;         }
;         if (gq == 3) {
; #pragma unroll
;           for (int m = 0; m < 4; ++m) afB[m] = *(const bf16x8*)(sa + m * 2048 + (((4 + fq) ^ swz) << 4));
;         }
;         __builtin_amdgcn_sched_barrier(0);
; #pragma unroll
;         for (int m = 0; m < 4; ++m)
; #pragma unroll
;           for (int n = 0; n < 2; ++n) {
;             const bf16x8 av = ks ? afB[m] : afA[m];
;             acc[m][nh * 2 + n] = SWAP ? __builtin_amdgcn_mfma_f32_16x16x32_bf16(bfb[gq & 1][n], av, acc[m][nh * 2 + n], 0, 0, 0)
;                                       : __builtin_amdgcn_mfma_f32_16x16x32_bf16(av, bfb[gq & 1][n], acc[m][nh * 2 + n], 0, 0, 0);
;           }
;       }
;       }
;     }
;     __syncthreads();
;     const int te = get_tid512();
;     const int fr_e = te & 15, fq_e = (te & 63) >> 4, wr_e = te >> 7, wc_e = (te >> 6) & 1;
;     const int sub = 2 * mt + (wr_e >> 1);
;     const int g = sub / tpg, ti = sub - g * tpg;
;     const int rig0 = ti * step - halo;
;     const int rw = (wr_e & 1) * 64;
;     if constexpr (Epi::KIND == 0) {
; #pragma unroll
;       for (int m = 0; m < 4; ++m) {
;         const int rig = rig0 + rw + m * 16 + fr_e;
;         if constexpr (Epi::ROWSUM) {
;           float ss = 0.f;
; #pragma unroll
;           for (int n = 0; n < 8; ++n) {
;             const int col = nt * 256 + wc_e * 128 + n * 16 + fq_e * 4;
;             if (col < N) ss += epi.c4(g, rig, col, acc[m][n]);
;           }
;           ss += __shfl_xor(ss, 16); ss += __shfl_xor(ss, 32);
;           if (fq_e == 0) epi.rowsum(g, rig, nt * 2 + wc_e, ss);
	v_add_u32_e32 v130, v153, v141
	ds_read_b128 v[132:135], v130
	ds_read_b128 v[164:167], v130 offset:2048
	ds_read_b128 v[168:171], v130 offset:4096
	ds_read_b128 v[172:175], v130 offset:6144
	v_add_u32_e32 v130, v154, v141
	ds_read_b128 v[176:179], v130
	ds_read_b128 v[180:183], v130 offset:2048
	ds_read_b128 v[184:187], v130 offset:4096
	ds_read_b128 v[188:191], v130 offset:6144
	s_waitcnt lgkmcnt(0)
	v_mfma_f32_16x16x32_bf16 v[126:129], v[176:179], v[132:135], v[126:129]
	v_mfma_f32_16x16x32_bf16 v[110:113], v[176:179], v[164:167], v[110:113]
	v_mfma_f32_16x16x32_bf16 v[82:85], v[176:179], v[168:171], v[82:85]
	v_mfma_f32_16x16x32_bf16 v[50:53], v[176:179], v[172:175], v[50:53]
	ds_read_b128 v[176:179], v130 offset:8192
	ds_read_b128 v[192:195], v130 offset:10240
	v_mfma_f32_16x16x32_bf16 v[122:125], v[180:183], v[132:135], v[122:125]
	v_mfma_f32_16x16x32_bf16 v[106:109], v[180:183], v[164:167], v[106:109]
	v_mfma_f32_16x16x32_bf16 v[78:81], v[180:183], v[168:171], v[78:81]
	v_mfma_f32_16x16x32_bf16 v[42:45], v[180:183], v[172:175], v[42:45]
	v_mfma_f32_16x16x32_bf16 v[118:121], v[184:187], v[132:135], v[118:121]
	v_mfma_f32_16x16x32_bf16 v[180:183], v[184:187], v[164:167], v[94:97]
	v_mfma_f32_16x16x32_bf16 v[200:203], v[184:187], v[168:171], v[58:61]
	v_mfma_f32_16x16x32_bf16 v[204:207], v[188:191], v[168:171], v[54:57]
	v_mfma_f32_16x16x32_bf16 v[184:187], v[184:187], v[172:175], v[26:29]
	s_nop 2
	ds_read_b128 v[26:29], v130 offset:12288
	ds_read_b128 v[54:57], v130 offset:14336
	v_mfma_f32_16x16x32_bf16 v[114:117], v[188:191], v[132:135], v[114:117]
	v_mfma_f32_16x16x32_bf16 v[196:199], v[188:191], v[164:167], v[86:89]
	v_mfma_f32_16x16x32_bf16 v[188:191], v[188:191], v[172:175], v[22:25]
	v_add_u32_e32 v130, v154, v142
	s_waitcnt lgkmcnt(0)
	v_mfma_f32_16x16x32_bf16 v[208:211], v[192:195], v[168:171], v[30:33]
	ds_read_b128 v[22:25], v130
	ds_read_b128 v[86:89], v130 offset:2048
	s_nop 0
	v_add_u32_e32 v30, v153, v142
	v_mfma_f32_16x16x32_bf16 v[102:105], v[176:179], v[132:135], v[102:105]
	v_mfma_f32_16x16x32_bf16 v[74:77], v[176:179], v[164:167], v[74:77]
	v_mfma_f32_16x16x32_bf16 v[46:49], v[176:179], v[168:171], v[46:49]
	v_mfma_f32_16x16x32_bf16 v[10:13], v[176:179], v[172:175], v[10:13]
	ds_read_b128 v[176:179], v30
	ds_read_b128 v[212:215], v30 offset:2048
	ds_read_b128 v[216:219], v30 offset:4096
	ds_read_b128 v[220:223], v30 offset:6144
	v_mfma_f32_16x16x32_bf16 v[98:101], v[192:195], v[132:135], v[98:101]
	v_mfma_f32_16x16x32_bf16 v[66:69], v[192:195], v[164:167], v[66:69]
	v_mfma_f32_16x16x32_bf16 v[6:9], v[192:195], v[172:175], v[6:9]
	v_mfma_f32_16x16x32_bf16 v[38:41], v[26:29], v[164:167], v[38:41]
	v_mfma_f32_16x16x32_bf16 v[34:37], v[54:57], v[164:167], v[34:37]
	v_mfma_f32_16x16x32_bf16 v[192:195], v[26:29], v[168:171], v[18:21]
	v_mfma_f32_16x16x32_bf16 v[166:169], v[54:57], v[168:171], v[14:17]
	s_nop 2
	ds_read_b128 v[14:17], v130 offset:4096
	ds_read_b128 v[18:21], v130 offset:6144
	v_mfma_f32_16x16x32_bf16 v[70:73], v[26:29], v[132:135], v[70:73]
	v_mfma_f32_16x16x32_bf16 v[132:135], v[54:57], v[132:135], v[62:65]
	v_mfma_f32_16x16x32_bf16 v[2:5], v[26:29], v[172:175], v[2:5]
	v_mfma_f32_16x16x32_bf16 v[170:173], v[54:57], v[172:175], v[90:93]
	ds_read_b128 v[224:227], v130 offset:8192
	ds_read_b128 v[228:231], v130 offset:10240
	s_waitcnt lgkmcnt(0)
	v_mfma_f32_16x16x32_bf16 v[126:129], v[22:25], v[176:179], v[126:129]
	v_mfma_f32_16x16x32_bf16 v[122:125], v[86:89], v[176:179], v[122:125]
	v_mfma_f32_16x16x32_bf16 v[94:97], v[22:25], v[212:215], v[110:113]
	v_mfma_f32_16x16x32_bf16 v[90:93], v[86:89], v[212:215], v[106:109]
	v_mfma_f32_16x16x32_bf16 v[62:65], v[22:25], v[216:219], v[82:85]
	v_mfma_f32_16x16x32_bf16 v[58:61], v[86:89], v[216:219], v[78:81]
	v_mfma_f32_16x16x32_bf16 v[30:33], v[22:25], v[220:223], v[50:53]
	v_mfma_f32_16x16x32_bf16 v[26:29], v[86:89], v[220:223], v[42:45]
	v_mfma_f32_16x16x32_bf16 v[86:89], v[14:17], v[212:215], v[180:183]
	v_mfma_f32_16x16x32_bf16 v[22:25], v[14:17], v[220:223], v[184:187]
	s_nop 1
	ds_read_b128 v[180:183], v130 offset:12288
	ds_read_b128 v[184:187], v130 offset:14336
	v_mfma_f32_16x16x32_bf16 v[118:121], v[14:17], v[176:179], v[118:121]
	v_mfma_f32_16x16x32_bf16 v[114:117], v[18:21], v[176:179], v[114:117]
	v_mfma_f32_16x16x32_bf16 v[82:85], v[18:21], v[212:215], v[196:199]
	v_mfma_f32_16x16x32_bf16 v[54:57], v[14:17], v[216:219], v[200:203]
	v_mfma_f32_16x16x32_bf16 v[50:53], v[18:21], v[216:219], v[204:207]
	v_mfma_f32_16x16x32_bf16 v[18:21], v[18:21], v[220:223], v[188:191]
	v_mfma_f32_16x16x32_bf16 v[110:113], v[224:227], v[176:179], v[102:105]
	v_mfma_f32_16x16x32_bf16 v[106:109], v[228:231], v[176:179], v[98:101]
	v_mfma_f32_16x16x32_bf16 v[78:81], v[224:227], v[212:215], v[74:77]
	v_mfma_f32_16x16x32_bf16 v[74:77], v[228:231], v[212:215], v[66:69]
	v_mfma_f32_16x16x32_bf16 v[46:49], v[224:227], v[216:219], v[46:49]
	v_mfma_f32_16x16x32_bf16 v[42:45], v[228:231], v[216:219], v[208:211]
	v_mfma_f32_16x16x32_bf16 v[14:17], v[224:227], v[220:223], v[10:13]
	v_mfma_f32_16x16x32_bf16 v[10:13], v[228:231], v[220:223], v[6:9]
	s_nop 2
	v_mov_b32_e32 v6, v1
	s_waitcnt vmcnt(0) lgkmcnt(0)
	s_barrier
	v_mfma_f32_16x16x32_bf16 v[98:101], v[184:187], v[176:179], v[132:135]
	v_ashrrev_i32_e32 v7, 8, v6
	v_add_u32_e32 v7, s5, v7
	v_mul_hi_i32 v8, v7, s23
	v_lshrrev_b32_e32 v9, 31, v8
	v_ashrrev_i32_e32 v8, 2, v8
	v_add_u32_e32 v130, v8, v9
	v_and_b32_e32 v132, 15, v6
	v_bfe_u32 v164, v6, 4, 2
	v_bfe_u32 v165, v6, 6, 1
	v_mul_lo_u32 v8, v130, s24
	v_lshrrev_b32_e32 v6, 1, v6
	v_mfma_f32_16x16x32_bf16 v[102:105], v[180:183], v[176:179], v[70:73]
	v_add_lshl_u32 v133, v8, v7, 7
	v_and_b32_e32 v135, 64, v6
	v_lshlrev_b32_e32 v134, 7, v165
	v_mfma_f32_16x16x32_bf16 v[70:73], v[180:183], v[212:215], v[38:41]
	v_or3_b32 v132, v133, v135, v132
	v_ashrrev_i32_e32 v133, 31, v132
	v_mfma_f32_16x16x32_bf16 v[66:69], v[184:187], v[212:215], v[34:37]
	v_mfma_f32_16x16x32_bf16 v[38:41], v[180:183], v[216:219], v[192:195]
	v_mfma_f32_16x16x32_bf16 v[34:37], v[184:187], v[216:219], v[166:169]
	v_mfma_f32_16x16x32_bf16 v[6:9], v[180:183], v[220:223], v[2:5]
	s_nop 1
	v_lshlrev_b32_e32 v166, 2, v164
	v_or3_b32 v134, v134, v166, s4
	v_cmp_gt_i32_e32 vcc, s27, v134
	v_mfma_f32_16x16x32_bf16 v[2:5], v[184:187], v[220:223], v[170:173]
	v_mov_b32_e32 v166, 0
	v_ashrrev_i32_e32 v135, 31, v134
	s_and_saveexec_b64 s[4:5], vcc
	s_cbranch_execz .LBB0_421
	v_mad_i64_i32 v[166:167], s[6:7], v130, s25, v[132:133]
	v_mov_b64_e32 v[170:171], s[30:31]
	v_cvt_pk_bf16_f32 v168, v126, v127
	v_mad_u64_u32 v[170:171], s[6:7], v166, s28, v[170:171]
	v_pk_mul_f32 v[126:127], v[126:127], v[126:127]
	v_cvt_pk_bf16_f32 v169, v128, v129
	v_mad_i32_i24 v171, v167, s28, v171
	v_pk_mul_f32 v[128:129], v[128:129], v[128:129]
	v_add_f32_e32 v126, v126, v127
	v_lshl_add_u64 v[166:167], v[134:135], 1, v[170:171]
	v_add_f32_e32 v126, v128, v126
	global_store_dwordx2 v[166:167], v[168:169], off
	v_add_f32_e32 v166, v129, v126

; #define GLDS16(gp, lp) __builtin_amdgcn_global_load_lds((const unsigned*)(gp), (__attribute__((address_space(3))) unsigned*)(lp), 16, 0, 0)
; template <bool SWAP, class Epi, bool THIN = false> ...
;     ...
;   for (; v < voff + ntiles; v += grid) {
;     const int w = v - voff;
;     int mt, nt;
;     if (w < full * 8 * NT) { const int sr = w / (8 * NT), rem = w - sr * 8 * NT; nt = rem >> 3; mt = sr * 8 + (rem & 7); }
;     else { const int w2 = w - full * 8 * NT, rl = MT - full * 8; nt = w2 / rl; mt = full * 8 + (w2 - nt * rl); }
;     unsigned ap[4], bp[4];
; #pragma unroll
;     for (int i = 0; i < 4; ++i) {
;       const int r = (tid >> 3) + 64 * i;
;       const int cs = tid & 7;
;       const int c = ((cs ^ ((r >> 1) & 7)) << 3);
;       const int sub = 2 * mt + (r >> 7);
;       const int g = sub / tpg, ti = sub - g * tpg;
;       int rig = ti * step - halo + (r & 127); rig = rig < 0 ? 0 : (rig > grows - 1 ? grows - 1 : rig);
;       ap[i] = (unsigned)((g * a_gstride + a_goff + rig) * lda + c);
;       int br = nt * 256 + r; br = br > N - 1 ? N - 1 : br;
;       bp[i] = (unsigned)(br * K + c);
;     }
;     const bool have_next = false;
;     f32x4 acc[4][8];
; #pragma unroll
;     for (int m = 0; m < 4; ++m)
; #pragma unroll
;       for (int n = 0; n < 8; ++n) acc[m][n] = (f32x4){0.f, 0.f, 0.f, 0.f};
;     if (!pre_issued) {
; #pragma unroll
;       for (int i = 0; i < 4; ++i) { GLDS16(A + (size_t)ap[i], smem + tid * 16 + i * 8192); GLDS16(Bt + (size_t)bp[i], smem + 32768 + tid * 16 + i * 8192); }
;     }
;     pre_issued = have_next;
.LBB0_2115:
	s_ashr_i32 s4, s3, 31
	s_lshr_b32 s4, s4, 27
	s_add_i32 s4, s3, s4
	s_ashr_i32 s4, s4, 5
	s_lshl_b32 s6, s3, 1
	s_lshl_b32 s5, s4, 4
	s_and_b32 s6, s6, 14
	s_or_b32 s5, s5, s6
	v_add_u32_e32 v2, s5, v149
	v_ashrrev_i32_e32 v3, 31, v2
	v_lshrrev_b32_e32 v3, 28, v3
	v_add_u32_e32 v3, v2, v3
	v_ashrrev_i32_e32 v3, 4, v3
	v_lshlrev_b32_e32 v4, 11, v3
	v_lshlrev_b32_e32 v2, 7, v2
	v_sub_u32_e32 v2, v2, v4
	v_or_b32_e32 v4, v2, v150
	v_min_i32_e32 v4, 0x7ff, v4
	v_lshlrev_b32_e32 v4, 10, v4
	v_cmp_lt_i32_e32 vcc, -1, v2
	s_lshl_b32 s6, s4, 10
	s_lshl_b32 s4, s3, 5
	v_cndmask_b32_e32 v2, 0, v4, vcc
	v_lshl_add_u32 v18, v3, 21, v2
	v_add_u32_e32 v3, s5, v152
	v_ashrrev_i32_e32 v4, 31, v3
	v_lshrrev_b32_e32 v4, 28, v4
	v_add_u32_e32 v4, v3, v4
	v_ashrrev_i32_e32 v4, 4, v4
	v_lshlrev_b32_e32 v5, 11, v4
	v_lshlrev_b32_e32 v3, 7, v3
	v_sub_u32_e32 v3, v3, v5
	v_or_b32_e32 v5, v3, v153
	v_min_i32_e32 v5, 0x7ff, v5
	s_sub_i32 s4, s4, s6
	v_lshlrev_b32_e32 v5, 10, v5
	v_cmp_lt_i32_e32 vcc, -1, v3
	s_and_b32 s4, s4, 0xffffff00
	v_add_u32_e32 v2, s4, v142
	v_cndmask_b32_e32 v3, 0, v5, vcc
	v_lshl_add_u32 v19, v4, 21, v3
	v_add_u32_e32 v3, s4, v151
	v_min_i32_e32 v3, 0x3ff, v3
	v_lshl_or_b32 v6, v3, 10, v143
	v_add_u32_e32 v3, s5, v155
	v_ashrrev_i32_e32 v5, 31, v3
	v_lshrrev_b32_e32 v5, 28, v5
	v_add_u32_e32 v5, v3, v5
	v_ashrrev_i32_e32 v5, 4, v5
	v_lshlrev_b32_e32 v7, 11, v5
	v_lshlrev_b32_e32 v3, 7, v3
	v_sub_u32_e32 v3, v3, v7
	v_or_b32_e32 v7, v3, v150
	v_min_i32_e32 v7, 0x7ff, v7
	v_lshlrev_b32_e32 v7, 10, v7
	v_cmp_lt_i32_e32 vcc, -1, v3
	v_or_b32_e32 v130, v18, v143
	v_min_i32_e32 v2, 0x3ff, v2
	v_cndmask_b32_e32 v3, 0, v7, vcc
	v_lshl_add_u32 v20, v5, 21, v3
	v_add_u32_e32 v3, s4, v154
	v_min_i32_e32 v3, 0x3ff, v3
	v_lshl_or_b32 v10, v3, 10, v143
	v_add_u32_e32 v3, s5, v157
	v_ashrrev_i32_e32 v5, 31, v3
	v_lshrrev_b32_e32 v5, 28, v5
	v_add_u32_e32 v5, v3, v5
	v_ashrrev_i32_e32 v5, 4, v5
	v_lshlrev_b32_e32 v7, 11, v5
	v_lshlrev_b32_e32 v3, 7, v3
	v_sub_u32_e32 v3, v3, v7
	v_or_b32_e32 v7, v3, v158
	v_min_i32_e32 v7, 0x7ff, v7
	v_lshlrev_b32_e32 v7, 10, v7
	v_cmp_lt_i32_e32 vcc, -1, v3
	v_readfirstlane_b32 s7, v144
	v_lshl_or_b32 v2, v2, 10, v143
	v_cndmask_b32_e32 v3, 0, v7, vcc
	v_lshl_add_u32 v21, v5, 21, v3
	v_add_u32_e32 v3, s4, v156
	v_min_i32_e32 v3, 0x3ff, v3
	v_lshl_or_b32 v14, v3, 10, v143
	v_lshl_add_u64 v[16:17], v[130:131], 1, s[18:19]
	s_mov_b32 m0, s7
	v_mov_b32_e32 v3, v131
	v_readfirstlane_b32 s7, v162
	v_or_b32_e32 v4, v19, v143
	global_load_lds_dwordx4 v[16:17], off
	v_lshl_add_u64 v[2:3], v[2:3], 1, s[24:25]
	s_mov_b32 m0, s7
	v_mov_b32_e32 v5, v131
	v_readfirstlane_b32 s7, v163
	global_load_lds_dwordx4 v[2:3], off
	v_lshl_add_u64 v[2:3], v[4:5], 1, s[18:19]
	s_mov_b32 m0, s7
	v_mov_b32_e32 v7, v131
	v_readfirstlane_b32 s7, v164
	v_or_b32_e32 v8, v20, v143
	global_load_lds_dwordx4 v[2:3], off
	v_lshl_add_u64 v[2:3], v[6:7], 1, s[24:25]
	s_mov_b32 m0, s7
	v_mov_b32_e32 v9, v131
	v_readfirstlane_b32 s7, v165
	global_load_lds_dwordx4 v[2:3], off
	v_lshl_add_u64 v[2:3], v[8:9], 1, s[18:19]
	s_mov_b32 m0, s7
	v_mov_b32_e32 v11, v131
	v_readfirstlane_b32 s7, v166
	v_or_b32_e32 v12, v21, v143
	global_load_lds_dwordx4 v[2:3], off
	v_lshl_add_u64 v[2:3], v[10:11], 1, s[24:25]
	s_mov_b32 m0, s7
	v_mov_b32_e32 v13, v131
	v_readfirstlane_b32 s7, v167
	global_load_lds_dwordx4 v[2:3], off
	v_lshl_add_u64 v[2:3], v[12:13], 1, s[18:19]
	s_mov_b32 m0, s7
	v_mov_b32_e32 v15, v131
	v_readfirstlane_b32 s7, v168
	global_load_lds_dwordx4 v[2:3], off
	v_lshl_add_u64 v[2:3], v[14:15], 1, s[24:25]
	s_mov_b32 m0, s7
	s_sub_i32 s6, s30, s6
	global_load_lds_dwordx4 v[2:3], off
	s_and_b32 s6, s6, 0xffffff00
	v_add_u32_e32 v2, s6, v156
	v_min_i32_e32 v2, 0x3ff, v2
	v_lshl_or_b32 v132, v2, 10, v161
	v_add_u32_e32 v2, s6, v154
	v_min_i32_e32 v2, 0x3ff, v2
	v_lshl_or_b32 v134, v2, 10, v161
	v_add_u32_e32 v2, s6, v151
	v_min_i32_e32 v2, 0x3ff, v2
	v_lshl_or_b32 v136, v2, 10, v161
	v_add_u32_e32 v2, s6, v142
	v_min_i32_e32 v2, 0x3ff, v2
	v_or_b32_e32 v133, v21, v161
	v_or_b32_e32 v135, v20, v161
	v_or_b32_e32 v137, v19, v161
	v_lshl_or_b32 v138, v2, 10, v161
	v_or_b32_e32 v139, v18, v161
	s_mov_b32 s6, 0
	s_mov_b32 s7, 0
	v_mov_b32_e32 v90, v131
	v_mov_b32_e32 v91, v131
	v_mov_b32_e32 v92, v131
	v_mov_b32_e32 v93, v131
	v_mov_b32_e32 v2, v131
	v_mov_b32_e32 v3, v131
	v_mov_b32_e32 v4, v131
	v_mov_b32_e32 v6, v131
	v_mov_b32_e32 v8, v131
	v_mov_b32_e32 v10, v131
	v_mov_b32_e32 v12, v131
	v_mov_b32_e32 v22, v131
	v_mov_b32_e32 v23, v131
	v_mov_b32_e32 v24, v131
	v_mov_b32_e32 v25, v131
	v_mov_b32_e32 v26, v131
	v_mov_b32_e32 v27, v131
	v_mov_b32_e32 v28, v131
	v_mov_b32_e32 v29, v131
	v_mov_b32_e32 v42, v131
	v_mov_b32_e32 v43, v131
	v_mov_b32_e32 v44, v131
	v_mov_b32_e32 v45, v131
	v_mov_b32_e32 v50, v131
	v_mov_b32_e32 v51, v131
	v_mov_b32_e32 v52, v131
	v_mov_b32_e32 v53, v131
	v_mov_b32_e32 v14, v131
	v_mov_b32_e32 v16, v131
	v_mov_b32_e32 v17, v131
	v_mov_b32_e32 v18, v131
	v_mov_b32_e32 v19, v131
	v_mov_b32_e32 v20, v131
	v_mov_b32_e32 v21, v131
	v_mov_b32_e32 v30, v131
	v_mov_b32_e32 v31, v131
	v_mov_b32_e32 v32, v131
	v_mov_b32_e32 v33, v131
	v_mov_b32_e32 v46, v131
	v_mov_b32_e32 v47, v131
	v_mov_b32_e32 v48, v131
	v_mov_b32_e32 v49, v131
	v_mov_b32_e32 v54, v131
	v_mov_b32_e32 v55, v131
	v_mov_b32_e32 v56, v131
	v_mov_b32_e32 v57, v131
	v_mov_b32_e32 v58, v131
	v_mov_b32_e32 v59, v131
	v_mov_b32_e32 v60, v131
	v_mov_b32_e32 v61, v131
	v_mov_b32_e32 v78, v131
	v_mov_b32_e32 v79, v131
	v_mov_b32_e32 v80, v131
	v_mov_b32_e32 v81, v131
	v_mov_b32_e32 v82, v131
	v_mov_b32_e32 v83, v131
	v_mov_b32_e32 v84, v131
	v_mov_b32_e32 v85, v131
; template <bool SWAP, class Epi, bool THIN = false> ...
;     ...
;     for (int st = 0; st < ns; ++st) {
;       asm volatile("s_waitcnt vmcnt(0)" ::: "memory");
;       __builtin_amdgcn_s_barrier();
;       asm volatile("" ::: "memory");
;       if (st + 1 < ns) {
;         char* nb = smem + ((st + 1) & 1) * 65536;
;         const int ko = (st + 1) * 64;
; #pragma unroll
;         for (int i = 0; i < 4; ++i) { GLDS16(A + (size_t)(ap[i] + ko), nb + tid * 16 + i * 8192); GLDS16(Bt + (size_t)(bp[i] + ko), nb + 32768 + tid * 16 + i * 8192); }
;       }
;       const char* sa = smem + (st & 1) * 65536 + (wr * 64 + fr) * 128;
;       const char* sb = smem + (st & 1) * 65536 + 32768 + (wc * 128 + fr) * 128;
;       if constexpr (THIN) {
;         if (wc == 0) {
; #pragma unroll
;           for (int ks = 0; ks < 2; ++ks) {
;             bf16x8 af[4], bf[2];
; #pragma unroll
;             for (int m = 0; m < 4; ++m) af[m] = *(const bf16x8*)(sa + m * 2048 + (((ks * 4 + fq) ^ swz) << 4));
; #pragma unroll
;             for (int n = 0; n < 2; ++n) bf[n] = *(const bf16x8*)(sb + n * 2048 + (((ks * 4 + fq) ^ swz) << 4));
; #pragma unroll
;             for (int m = 0; m < 4; ++m)
; #pragma unroll
;               for (int n = 0; n < 2; ++n)
;                 acc[m][n] = SWAP ? __builtin_amdgcn_mfma_f32_16x16x32_bf16(bf[n], af[m], acc[m][n], 0, 0, 0)
;                                  : __builtin_amdgcn_mfma_f32_16x16x32_bf16(af[m], bf[n], acc[m][n], 0, 0, 0);
;           }
;         }
;       } else {
;       bf16x8 afA[4], afB[4], bfb[2][2];
; #pragma unroll
;       for (int m = 0; m < 4; ++m) afA[m] = *(const bf16x8*)(sa + m * 2048 + ((fq ^ swz) << 4));
; #pragma unroll
;       for (int n = 0; n < 2; ++n) bfb[0][n] = *(const bf16x8*)(sb + n * 2048 + ((fq ^ swz) << 4));
; #pragma unroll
;       for (int gq = 0; gq < 8; ++gq) {
;         const int ks = gq >> 2, nh = gq & 3;
;         if (gq < 7) {
;           const int ks2 = (gq + 1) >> 2, nh2 = (gq + 1) & 3;
; #pragma unroll
;           for (int n = 0; n < 2; ++n) bfb[(gq + 1) & 1][n] = *(const bf16x8*)(sb + (nh2 * 2 + n) * 2048 + (((ks2 * 4 + fq) ^ swz) << 4));
;         }
;         if (gq == 3) {
; #pragma unroll
;           for (int m = 0; m < 4; ++m) afB[m] = *(const bf16x8*)(sa + m * 2048 + (((4 + fq) ^ swz) << 4));
;         }
;         __builtin_amdgcn_sched_barrier(0);
; #pragma unroll
	v_mov_b32_e32 v34, v131
	v_mov_b32_e32 v35, v131
	v_mov_b32_e32 v36, v131
	v_mov_b32_e32 v37, v131
	v_mov_b32_e32 v38, v131
	v_mov_b32_e32 v39, v131
	v_mov_b32_e32 v40, v131
	v_mov_b32_e32 v41, v131
	v_mov_b32_e32 v66, v131
	v_mov_b32_e32 v67, v131
	v_mov_b32_e32 v68, v131
	v_mov_b32_e32 v69, v131
	v_mov_b32_e32 v74, v131
	v_mov_b32_e32 v75, v131
	v_mov_b32_e32 v76, v131
	v_mov_b32_e32 v77, v131
	v_mov_b32_e32 v86, v131
	v_mov_b32_e32 v87, v131
	v_mov_b32_e32 v88, v131
	v_mov_b32_e32 v89, v131
	v_mov_b32_e32 v94, v131
	v_mov_b32_e32 v95, v131
	v_mov_b32_e32 v96, v131
	v_mov_b32_e32 v97, v131
	v_mov_b32_e32 v106, v131
	v_mov_b32_e32 v107, v131
	v_mov_b32_e32 v108, v131
	v_mov_b32_e32 v109, v131
	v_mov_b32_e32 v110, v131
	v_mov_b32_e32 v111, v131
	v_mov_b32_e32 v112, v131
	v_mov_b32_e32 v113, v131
	v_mov_b32_e32 v62, v131
	v_mov_b32_e32 v63, v131
	v_mov_b32_e32 v64, v131
	v_mov_b32_e32 v65, v131
	v_mov_b32_e32 v70, v131
	v_mov_b32_e32 v71, v131
	v_mov_b32_e32 v72, v131
	v_mov_b32_e32 v73, v131
	v_mov_b32_e32 v98, v131
	v_mov_b32_e32 v99, v131
	v_mov_b32_e32 v100, v131
	v_mov_b32_e32 v101, v131
	v_mov_b32_e32 v102, v131
	v_mov_b32_e32 v103, v131
	v_mov_b32_e32 v104, v131
	v_mov_b32_e32 v105, v131
	v_mov_b32_e32 v114, v131
	v_mov_b32_e32 v115, v131
	v_mov_b32_e32 v116, v131
	v_mov_b32_e32 v117, v131
	v_mov_b32_e32 v118, v131
	v_mov_b32_e32 v119, v131
	v_mov_b32_e32 v120, v131
	v_mov_b32_e32 v121, v131
	v_mov_b32_e32 v122, v131
	v_mov_b32_e32 v123, v131
	v_mov_b32_e32 v124, v131
	v_mov_b32_e32 v125, v131
	v_mov_b32_e32 v126, v131
	v_mov_b32_e32 v127, v131
	v_mov_b32_e32 v128, v131
	v_mov_b32_e32 v129, v131
	v_lshlrev_b32_e32 v139, 1, v139
	v_lshlrev_b32_e32 v138, 1, v138
	v_lshlrev_b32_e32 v137, 1, v137
	v_lshlrev_b32_e32 v136, 1, v136
	v_lshlrev_b32_e32 v135, 1, v135
	v_lshlrev_b32_e32 v134, 1, v134
	v_lshlrev_b32_e32 v133, 1, v133
	v_lshlrev_b32_e32 v132, 1, v132
.LBB0_2116:
	s_add_i32 s8, s7, 0x10000
	s_and_b32 s9, s8, 0x10000
	v_add_u32_e32 v169, s9, v144
	s_nop 0
	v_readfirstlane_b32 s9, v169
	s_waitcnt vmcnt(0)
	s_barrier
	s_and_b32 s7, s7, 0x10000
	v_add_u32_e32 v130, s7, v145
	v_add_u32_e32 v140, v130, v147
	ds_read_b128 v[170:173], v140
	ds_read_b128 v[174:177], v140 offset:2048
	ds_read_b128 v[178:181], v140 offset:4096
	ds_read_b128 v[182:185], v140 offset:6144
	v_or_b32_e32 v140, s7, v146
	v_add_u32_e32 v141, v140, v147
	ds_read_b128 v[186:189], v141 offset:32768
	ds_read_b128 v[190:193], v141 offset:34816
	ds_read_b128 v[194:197], v141 offset:36864
	ds_read_b128 v[198:201], v141 offset:38912
	v_add_u32_e32 v130, v130, v148
	s_waitcnt lgkmcnt(0)
	v_mfma_f32_16x16x32_bf16 v[126:129], v[186:189], v[170:173], v[126:129]
	s_mov_b32 m0, s9
	v_mfma_f32_16x16x32_bf16 v[110:113], v[186:189], v[174:177], v[110:113]
	global_load_lds_dwordx4 v139, s[18:19]
	v_add_u32_e32 v139, 0x80, v139
	v_mfma_f32_16x16x32_bf16 v[82:85], v[186:189], v[178:181], v[82:85]
	v_mfma_f32_16x16x32_bf16 v[50:53], v[186:189], v[182:185], v[50:53]
	ds_read_b128 v[186:189], v141 offset:40960
	ds_read_b128 v[202:205], v141 offset:43008
	v_mfma_f32_16x16x32_bf16 v[122:125], v[190:193], v[170:173], v[122:125]
	s_add_u32 m0, s9, 0x8000
	v_mfma_f32_16x16x32_bf16 v[106:109], v[190:193], v[174:177], v[106:109]
	global_load_lds_dwordx4 v138, s[24:25]
	v_add_u32_e32 v138, 0x80, v138
	v_mfma_f32_16x16x32_bf16 v[78:81], v[190:193], v[178:181], v[78:81]
	v_mfma_f32_16x16x32_bf16 v[42:45], v[190:193], v[182:185], v[42:45]
	v_mfma_f32_16x16x32_bf16 v[118:121], v[194:197], v[170:173], v[118:121]
	s_add_u32 m0, s9, 0x2000
	v_mfma_f32_16x16x32_bf16 v[94:97], v[194:197], v[174:177], v[94:97]
	global_load_lds_dwordx4 v137, s[18:19]
	v_add_u32_e32 v137, 0x80, v137
	v_mfma_f32_16x16x32_bf16 v[58:61], v[194:197], v[178:181], v[58:61]
	v_mfma_f32_16x16x32_bf16 v[26:29], v[194:197], v[182:185], v[26:29]
	ds_read_b128 v[190:193], v141 offset:45056
	ds_read_b128 v[194:197], v141 offset:47104
	v_mfma_f32_16x16x32_bf16 v[114:117], v[198:201], v[170:173], v[114:117]
	s_add_u32 m0, s9, 0xa000
	v_mfma_f32_16x16x32_bf16 v[86:89], v[198:201], v[174:177], v[86:89]
	global_load_lds_dwordx4 v136, s[24:25]
	v_add_u32_e32 v136, 0x80, v136
	v_mfma_f32_16x16x32_bf16 v[54:57], v[198:201], v[178:181], v[54:57]
	v_mfma_f32_16x16x32_bf16 v[22:25], v[198:201], v[182:185], v[22:25]
	v_add_u32_e32 v140, v140, v148
	s_waitcnt lgkmcnt(0)
	v_mfma_f32_16x16x32_bf16 v[102:105], v[186:189], v[170:173], v[102:105]
	ds_read_b128 v[198:201], v140 offset:32768
	ds_read_b128 v[206:209], v140 offset:34816
	s_add_u32 m0, s9, 0x4000
	v_mfma_f32_16x16x32_bf16 v[74:77], v[186:189], v[174:177], v[74:77]
	global_load_lds_dwordx4 v135, s[18:19]
	v_add_u32_e32 v135, 0x80, v135
	v_mfma_f32_16x16x32_bf16 v[46:49], v[186:189], v[178:181], v[46:49]
	v_mfma_f32_16x16x32_bf16 v[10:13], v[186:189], v[182:185], v[10:13]
	ds_read_b128 v[186:189], v130
	ds_read_b128 v[210:213], v130 offset:2048
	ds_read_b128 v[214:217], v130 offset:4096
	ds_read_b128 v[218:221], v130 offset:6144
	v_mfma_f32_16x16x32_bf16 v[98:101], v[202:205], v[170:173], v[98:101]
	s_add_u32 m0, s9, 0xc000
	v_mfma_f32_16x16x32_bf16 v[66:69], v[202:205], v[174:177], v[66:69]
	global_load_lds_dwordx4 v134, s[24:25]
	v_add_u32_e32 v134, 0x80, v134
	v_mfma_f32_16x16x32_bf16 v[30:33], v[202:205], v[178:181], v[30:33]
	v_mfma_f32_16x16x32_bf16 v[6:9], v[202:205], v[182:185], v[6:9]
	v_mfma_f32_16x16x32_bf16 v[70:73], v[190:193], v[170:173], v[70:73]
	s_add_u32 m0, s9, 0x6000
	v_mfma_f32_16x16x32_bf16 v[62:65], v[194:197], v[170:173], v[62:65]
	global_load_lds_dwordx4 v133, s[18:19]
	v_add_u32_e32 v133, 0x80, v133
	v_mfma_f32_16x16x32_bf16 v[38:41], v[190:193], v[174:177], v[38:41]
	v_mfma_f32_16x16x32_bf16 v[34:37], v[194:197], v[174:177], v[34:37]
	ds_read_b128 v[170:173], v140 offset:36864
	ds_read_b128 v[174:177], v140 offset:38912
	v_mfma_f32_16x16x32_bf16 v[18:21], v[190:193], v[178:181], v[18:21]
	s_add_u32 m0, s9, 0xe000
	v_mfma_f32_16x16x32_bf16 v[14:17], v[194:197], v[178:181], v[14:17]
	global_load_lds_dwordx4 v132, s[24:25]
	v_add_u32_e32 v132, 0x80, v132
	v_mfma_f32_16x16x32_bf16 v[2:5], v[190:193], v[182:185], v[2:5]
	v_mfma_f32_16x16x32_bf16 v[90:93], v[194:197], v[182:185], v[90:93]
	ds_read_b128 v[178:181], v140 offset:40960
	ds_read_b128 v[182:185], v140 offset:43008
	s_waitcnt lgkmcnt(0)
; template <bool SWAP, class Epi, bool THIN = false> ...
;     ...
;       bf16x8 afA[4], afB[4], bfb[2][2];
; #pragma unroll
;       for (int m = 0; m < 4; ++m) afA[m] = *(const bf16x8*)(sa + m * 2048 + ((fq ^ swz) << 4));
; #pragma unroll
;       for (int n = 0; n < 2; ++n) bfb[0][n] = *(const bf16x8*)(sb + n * 2048 + ((fq ^ swz) << 4));
; #pragma unroll
;       for (int gq = 0; gq < 8; ++gq) {
;         const int ks = gq >> 2, nh = gq & 3;
;         if (gq < 7) {
;           const int ks2 = (gq + 1) >> 2, nh2 = (gq + 1) & 3;
; #pragma unroll
;           for (int n = 0; n < 2; ++n) bfb[(gq + 1) & 1][n] = *(const bf16x8*)(sb + (nh2 * 2 + n) * 2048 + (((ks2 * 4 + fq) ^ swz) << 4));
;         }
;         if (gq == 3) {
; #pragma unroll
;           for (int m = 0; m < 4; ++m) afB[m] = *(const bf16x8*)(sa + m * 2048 + (((4 + fq) ^ swz) << 4));
;         }
;         __builtin_amdgcn_sched_barrier(0);
; #pragma unroll
;         for (int m = 0; m < 4; ++m)
; #pragma unroll
;           for (int n = 0; n < 2; ++n) {
;             const bf16x8 av = ks ? afB[m] : afA[m];
;             acc[m][nh * 2 + n] = SWAP ? __builtin_amdgcn_mfma_f32_16x16x32_bf16(bfb[gq & 1][n], av, acc[m][nh * 2 + n], 0, 0, 0)
;                                       : __builtin_amdgcn_mfma_f32_16x16x32_bf16(av, bfb[gq & 1][n], acc[m][nh * 2 + n], 0, 0, 0);
;           }
;       }
	v_mfma_f32_16x16x32_bf16 v[126:129], v[198:201], v[186:189], v[126:129]
	v_mfma_f32_16x16x32_bf16 v[122:125], v[206:209], v[186:189], v[122:125]
	v_mfma_f32_16x16x32_bf16 v[110:113], v[198:201], v[210:213], v[110:113]
	v_mfma_f32_16x16x32_bf16 v[106:109], v[206:209], v[210:213], v[106:109]
	v_mfma_f32_16x16x32_bf16 v[82:85], v[198:201], v[214:217], v[82:85]
	v_mfma_f32_16x16x32_bf16 v[78:81], v[206:209], v[214:217], v[78:81]
	v_mfma_f32_16x16x32_bf16 v[50:53], v[198:201], v[218:221], v[50:53]
	v_mfma_f32_16x16x32_bf16 v[42:45], v[206:209], v[218:221], v[42:45]
	v_mfma_f32_16x16x32_bf16 v[118:121], v[170:173], v[186:189], v[118:121]
	v_mfma_f32_16x16x32_bf16 v[94:97], v[170:173], v[210:213], v[94:97]
	v_mfma_f32_16x16x32_bf16 v[58:61], v[170:173], v[214:217], v[58:61]
	v_mfma_f32_16x16x32_bf16 v[26:29], v[170:173], v[218:221], v[26:29]
	ds_read_b128 v[170:173], v140 offset:45056
	ds_read_b128 v[190:193], v140 offset:47104
	v_mfma_f32_16x16x32_bf16 v[114:117], v[174:177], v[186:189], v[114:117]
	v_mfma_f32_16x16x32_bf16 v[86:89], v[174:177], v[210:213], v[86:89]
	v_mfma_f32_16x16x32_bf16 v[54:57], v[174:177], v[214:217], v[54:57]
	v_mfma_f32_16x16x32_bf16 v[22:25], v[174:177], v[218:221], v[22:25]
	v_mfma_f32_16x16x32_bf16 v[102:105], v[178:181], v[186:189], v[102:105]
	v_mfma_f32_16x16x32_bf16 v[98:101], v[182:185], v[186:189], v[98:101]
	v_mfma_f32_16x16x32_bf16 v[74:77], v[178:181], v[210:213], v[74:77]
	v_mfma_f32_16x16x32_bf16 v[66:69], v[182:185], v[210:213], v[66:69]
	v_mfma_f32_16x16x32_bf16 v[46:49], v[178:181], v[214:217], v[46:49]
	v_mfma_f32_16x16x32_bf16 v[30:33], v[182:185], v[214:217], v[30:33]
	v_mfma_f32_16x16x32_bf16 v[10:13], v[178:181], v[218:221], v[10:13]
	v_mfma_f32_16x16x32_bf16 v[6:9], v[182:185], v[218:221], v[6:9]
	s_waitcnt lgkmcnt(0)
	v_mfma_f32_16x16x32_bf16 v[70:73], v[170:173], v[186:189], v[70:73]
	s_add_i32 s6, s6, 64
	s_cmpk_eq_i32 s6, 0x3c0
	s_mov_b32 s7, s8
	v_mfma_f32_16x16x32_bf16 v[62:65], v[190:193], v[186:189], v[62:65]
	v_mfma_f32_16x16x32_bf16 v[38:41], v[170:173], v[210:213], v[38:41]
	v_mfma_f32_16x16x32_bf16 v[34:37], v[190:193], v[210:213], v[34:37]
	v_mfma_f32_16x16x32_bf16 v[18:21], v[170:173], v[214:217], v[18:21]
	v_mfma_f32_16x16x32_bf16 v[14:17], v[190:193], v[214:217], v[14:17]
	v_mfma_f32_16x16x32_bf16 v[2:5], v[170:173], v[218:221], v[2:5]
	v_mfma_f32_16x16x32_bf16 v[90:93], v[190:193], v[218:221], v[90:93]
	s_cbranch_scc0 .LBB0_2116
	s_waitcnt vmcnt(0)
	s_barrier
	v_add_u32_e32 v130, v159, v147
	ds_read_b128 v[132:135], v130
	ds_read_b128 v[136:139], v130 offset:2048
	ds_read_b128 v[170:173], v130 offset:4096
	ds_read_b128 v[174:177], v130 offset:6144
	v_add_u32_e32 v130, v160, v147
	ds_read_b128 v[178:181], v130
	ds_read_b128 v[182:185], v130 offset:2048
	ds_read_b128 v[186:189], v130 offset:4096
	ds_read_b128 v[190:193], v130 offset:6144
	s_waitcnt lgkmcnt(0)
	v_mfma_f32_16x16x32_bf16 v[126:129], v[178:181], v[132:135], v[126:129]
	v_mfma_f32_16x16x32_bf16 v[110:113], v[178:181], v[136:139], v[110:113]
	v_mfma_f32_16x16x32_bf16 v[82:85], v[178:181], v[170:173], v[82:85]
	v_mfma_f32_16x16x32_bf16 v[50:53], v[178:181], v[174:177], v[50:53]
	ds_read_b128 v[178:181], v130 offset:8192
	ds_read_b128 v[194:197], v130 offset:10240
	v_mfma_f32_16x16x32_bf16 v[122:125], v[182:185], v[132:135], v[122:125]
	v_mfma_f32_16x16x32_bf16 v[106:109], v[182:185], v[136:139], v[106:109]
	v_mfma_f32_16x16x32_bf16 v[78:81], v[182:185], v[170:173], v[78:81]
	v_mfma_f32_16x16x32_bf16 v[42:45], v[182:185], v[174:177], v[42:45]
	v_mfma_f32_16x16x32_bf16 v[118:121], v[186:189], v[132:135], v[118:121]
	v_mfma_f32_16x16x32_bf16 v[182:185], v[186:189], v[136:139], v[94:97]
	v_mfma_f32_16x16x32_bf16 v[202:205], v[186:189], v[170:173], v[58:61]
	v_mfma_f32_16x16x32_bf16 v[206:209], v[190:193], v[170:173], v[54:57]
	v_mfma_f32_16x16x32_bf16 v[186:189], v[186:189], v[174:177], v[26:29]
	s_nop 2
	ds_read_b128 v[26:29], v130 offset:12288
	ds_read_b128 v[54:57], v130 offset:14336
	v_mfma_f32_16x16x32_bf16 v[114:117], v[190:193], v[132:135], v[114:117]
	v_mfma_f32_16x16x32_bf16 v[198:201], v[190:193], v[136:139], v[86:89]
	v_mfma_f32_16x16x32_bf16 v[190:193], v[190:193], v[174:177], v[22:25]
	v_add_u32_e32 v130, v160, v148
	s_waitcnt lgkmcnt(0)
; template <bool SWAP, class Epi, bool THIN = false> ...
;     ...
;       bf16x8 afA[4], afB[4], bfb[2][2];
; #pragma unroll
;       for (int m = 0; m < 4; ++m) afA[m] = *(const bf16x8*)(sa + m * 2048 + ((fq ^ swz) << 4));
; #pragma unroll
;       for (int n = 0; n < 2; ++n) bfb[0][n] = *(const bf16x8*)(sb + n * 2048 + ((fq ^ swz) << 4));
; #pragma unroll
;       for (int gq = 0; gq < 8; ++gq) {
;         const int ks = gq >> 2, nh = gq & 3;
;         if (gq < 7) {
;           const int ks2 = (gq + 1) >> 2, nh2 = (gq + 1) & 3;
; #pragma unroll
;           for (int n = 0; n < 2; ++n) bfb[(gq + 1) & 1][n] = *(const bf16x8*)(sb + (nh2 * 2 + n) * 2048 + (((ks2 * 4 + fq) ^ swz) << 4));
;         }
;         if (gq == 3) {
; #pragma unroll
;           for (int m = 0; m < 4; ++m) afB[m] = *(const bf16x8*)(sa + m * 2048 + (((4 + fq) ^ swz) << 4));
;         }
;         __builtin_amdgcn_sched_barrier(0);
; #pragma unroll
;         for (int m = 0; m < 4; ++m)
; #pragma unroll
;           for (int n = 0; n < 2; ++n) {
;             const bf16x8 av = ks ? afB[m] : afA[m];
;             acc[m][nh * 2 + n] = SWAP ? __builtin_amdgcn_mfma_f32_16x16x32_bf16(bfb[gq & 1][n], av, acc[m][nh * 2 + n], 0, 0, 0)
;                                       : __builtin_amdgcn_mfma_f32_16x16x32_bf16(av, bfb[gq & 1][n], acc[m][nh * 2 + n], 0, 0, 0);
;           }
;       }
;       }
;     }
;     __syncthreads();
;     const int te = get_tid512();
;     const int fr_e = te & 15, fq_e = (te & 63) >> 4, wr_e = te >> 7, wc_e = (te >> 6) & 1;
;     const int sub = 2 * mt + (wr_e >> 1);
;     const int g = sub / tpg, ti = sub - g * tpg;
;     const int rig0 = ti * step - halo;
;     const int rw = (wr_e & 1) * 64;
;     if constexpr (Epi::KIND == 0) {
; #pragma unroll
;       for (int m = 0; m < 4; ++m) {
;         const int rig = rig0 + rw + m * 16 + fr_e;
;         if constexpr (Epi::ROWSUM) {
;           float ss = 0.f;
; #pragma unroll
;           for (int n = 0; n < 8; ++n) {
;             const int col = nt * 256 + wc_e * 128 + n * 16 + fq_e * 4;
;             if (col < N) ss += epi.c4(g, rig, col, acc[m][n]);
;           }
;           ss += __shfl_xor(ss, 16); ss += __shfl_xor(ss, 32);
;           if (fq_e == 0) epi.rowsum(g, rig, nt * 2 + wc_e, ss);
;         } else {
; #pragma unroll
;           for (int n = 0; n < 8; ++n) {
	v_mfma_f32_16x16x32_bf16 v[210:213], v[194:197], v[170:173], v[30:33]
	ds_read_b128 v[22:25], v130
	ds_read_b128 v[86:89], v130 offset:2048
	s_nop 0
	v_add_u32_e32 v30, v159, v148
	v_mfma_f32_16x16x32_bf16 v[102:105], v[178:181], v[132:135], v[102:105]
	v_mfma_f32_16x16x32_bf16 v[74:77], v[178:181], v[136:139], v[74:77]
	v_mfma_f32_16x16x32_bf16 v[46:49], v[178:181], v[170:173], v[46:49]
	v_mfma_f32_16x16x32_bf16 v[10:13], v[178:181], v[174:177], v[10:13]
	ds_read_b128 v[178:181], v30
	ds_read_b128 v[214:217], v30 offset:2048
	ds_read_b128 v[218:221], v30 offset:4096
	ds_read_b128 v[222:225], v30 offset:6144
	v_mfma_f32_16x16x32_bf16 v[98:101], v[194:197], v[132:135], v[98:101]
	v_mfma_f32_16x16x32_bf16 v[66:69], v[194:197], v[136:139], v[66:69]
	v_mfma_f32_16x16x32_bf16 v[6:9], v[194:197], v[174:177], v[6:9]
	v_mfma_f32_16x16x32_bf16 v[38:41], v[26:29], v[136:139], v[38:41]
	v_mfma_f32_16x16x32_bf16 v[34:37], v[54:57], v[136:139], v[34:37]
	v_mfma_f32_16x16x32_bf16 v[136:139], v[26:29], v[170:173], v[18:21]
	v_mfma_f32_16x16x32_bf16 v[170:173], v[54:57], v[170:173], v[14:17]
	s_nop 2
	ds_read_b128 v[14:17], v130 offset:4096
	ds_read_b128 v[18:21], v130 offset:6144
	v_mfma_f32_16x16x32_bf16 v[70:73], v[26:29], v[132:135], v[70:73]
	v_mfma_f32_16x16x32_bf16 v[132:135], v[54:57], v[132:135], v[62:65]
	v_mfma_f32_16x16x32_bf16 v[2:5], v[26:29], v[174:177], v[2:5]
	v_mfma_f32_16x16x32_bf16 v[174:177], v[54:57], v[174:177], v[90:93]
	ds_read_b128 v[194:197], v130 offset:8192
	ds_read_b128 v[226:229], v130 offset:10240
	s_waitcnt lgkmcnt(0)
	v_mfma_f32_16x16x32_bf16 v[126:129], v[22:25], v[178:181], v[126:129]
	v_mfma_f32_16x16x32_bf16 v[122:125], v[86:89], v[178:181], v[122:125]
	v_mfma_f32_16x16x32_bf16 v[94:97], v[22:25], v[214:217], v[110:113]
	v_mfma_f32_16x16x32_bf16 v[90:93], v[86:89], v[214:217], v[106:109]
	v_mfma_f32_16x16x32_bf16 v[62:65], v[22:25], v[218:221], v[82:85]
	v_mfma_f32_16x16x32_bf16 v[58:61], v[86:89], v[218:221], v[78:81]
	v_mfma_f32_16x16x32_bf16 v[30:33], v[22:25], v[222:225], v[50:53]
	v_mfma_f32_16x16x32_bf16 v[26:29], v[86:89], v[222:225], v[42:45]
	v_mfma_f32_16x16x32_bf16 v[86:89], v[14:17], v[214:217], v[182:185]
	v_mfma_f32_16x16x32_bf16 v[22:25], v[14:17], v[222:225], v[186:189]
	s_nop 1
	ds_read_b128 v[182:185], v130 offset:12288
	ds_read_b128 v[186:189], v130 offset:14336
	v_mfma_f32_16x16x32_bf16 v[118:121], v[14:17], v[178:181], v[118:121]
	v_mfma_f32_16x16x32_bf16 v[114:117], v[18:21], v[178:181], v[114:117]
	v_mfma_f32_16x16x32_bf16 v[82:85], v[18:21], v[214:217], v[198:201]
	v_mfma_f32_16x16x32_bf16 v[54:57], v[14:17], v[218:221], v[202:205]
	v_mfma_f32_16x16x32_bf16 v[50:53], v[18:21], v[218:221], v[206:209]
	v_mfma_f32_16x16x32_bf16 v[18:21], v[18:21], v[222:225], v[190:193]
	v_mfma_f32_16x16x32_bf16 v[110:113], v[194:197], v[178:181], v[102:105]
	v_mfma_f32_16x16x32_bf16 v[106:109], v[226:229], v[178:181], v[98:101]
	v_mfma_f32_16x16x32_bf16 v[78:81], v[194:197], v[214:217], v[74:77]
	v_mfma_f32_16x16x32_bf16 v[74:77], v[226:229], v[214:217], v[66:69]
	v_mfma_f32_16x16x32_bf16 v[46:49], v[194:197], v[218:221], v[46:49]
	v_mfma_f32_16x16x32_bf16 v[42:45], v[226:229], v[218:221], v[210:213]
	v_mfma_f32_16x16x32_bf16 v[14:17], v[194:197], v[222:225], v[10:13]
	v_mfma_f32_16x16x32_bf16 v[6:9], v[226:229], v[222:225], v[6:9]
	v_mov_b32_e32 v130, v1
	s_waitcnt vmcnt(0) lgkmcnt(0)
	s_barrier
	v_mfma_f32_16x16x32_bf16 v[98:101], v[186:189], v[178:181], v[132:135]
	v_ashrrev_i32_e32 v11, 8, v130
	v_add_u32_e32 v11, s5, v11
	v_ashrrev_i32_e32 v12, 31, v11
	v_lshrrev_b32_e32 v12, 28, v12
	v_add_u32_e32 v12, v11, v12
	v_ashrrev_i32_e32 v134, 4, v12
	v_lshlrev_b32_e32 v12, 11, v134
	v_lshlrev_b32_e32 v11, 7, v11
	v_sub_u32_e32 v11, v11, v12
	v_lshrrev_b32_e32 v12, 1, v130
	v_and_b32_e32 v10, 15, v130
	v_and_b32_e32 v12, 64, v12
	v_mfma_f32_16x16x32_bf16 v[102:105], v[182:185], v[178:181], v[70:73]
	v_ashrrev_i32_e32 v135, 31, v134
	v_mfma_f32_16x16x32_bf16 v[70:73], v[182:185], v[214:217], v[38:41]
	v_mfma_f32_16x16x32_bf16 v[38:41], v[182:185], v[218:221], v[136:139]
	s_nop 2
	v_or3_b32 v136, v11, v12, v10
	v_lshlrev_b32_e32 v10, 1, v130
	v_and_b32_e32 v132, 0x80, v10
	v_mfma_f32_16x16x32_bf16 v[10:13], v[182:185], v[222:225], v[2:5]
	v_ashrrev_i32_e32 v137, 31, v136
	v_lshlrev_b64 v[138:139], 21, v[134:135]
	v_lshlrev_b64 v[140:141], 10, v[136:137]
	v_lshrrev_b32_e32 v2, 2, v130
	v_and_b32_e32 v2, 12, v2
	v_mfma_f32_16x16x32_bf16 v[66:69], v[186:189], v[214:217], v[34:37]
	v_or3_b32 v132, v2, v132, s4
	v_mad_i64_i32 v[134:135], s[4:5], v134, s33, 0
	v_mfma_f32_16x16x32_bf16 v[34:37], v[186:189], v[218:221], v[170:173]
	v_lshl_add_u64 v[140:141], v[140:141], 0, v[138:139]
	v_cmp_gt_i32_e32 vcc, s34, v132
	v_ashrrev_i32_e32 v133, 31, v132
	v_mfma_f32_16x16x32_bf16 v[2:5], v[186:189], v[222:225], v[174:177]
	v_lshl_add_u64 v[134:135], s[26:27], 0, v[134:135]
	s_and_saveexec_b64 s[4:5], vcc
	s_cbranch_execz .LBB0_2119
	v_lshl_add_u64 v[178:179], v[140:141], 0, v[132:133]
	v_lshl_add_u64 v[174:175], v[178:179], 2, s[22:23]
	v_lshl_add_u64 v[170:171], v[132:133], 2, v[134:135]
	global_load_dwordx4 v[170:173], v[170:171], off
	s_nop 0
	global_load_dwordx4 v[174:177], v[174:175], off nt
	v_add_f32_e32 v126, 0, v126
	v_add_f32_e32 v127, 0, v127
	v_add_f32_e32 v128, 0, v128
	v_add_f32_e32 v129, 0, v129
	s_waitcnt vmcnt(0)
	v_fma_f32 v126, v126, v170, v174
	v_fma_f32 v127, v127, v171, v175
	v_fma_f32 v128, v128, v172, v176
	v_fmac_f32_e32 v177, v129, v173
	v_cvt_pk_bf16_f32 v126, v126, v127
	v_cvt_pk_bf16_f32 v127, v128, v177
	v_lshl_add_u64 v[128:129], v[178:179], 1, s[20:21]
	global_store_dwordx2 v[128:129], v[126:127], off

; #define GLDS16(gp, lp) __builtin_amdgcn_global_load_lds((const unsigned*)(gp), (__attribute__((address_space(3))) unsigned*)(lp), 16, 0, 0)
; template <bool SWAP, class Epi, bool THIN = false> ...
;     ...
;   for (; v < voff + ntiles; v += grid) {
;     const int w = v - voff;
;     int mt, nt;
;     if (w < full * 8 * NT) { const int sr = w / (8 * NT), rem = w - sr * 8 * NT; nt = rem >> 3; mt = sr * 8 + (rem & 7); }
;     else { const int w2 = w - full * 8 * NT, rl = MT - full * 8; nt = w2 / rl; mt = full * 8 + (w2 - nt * rl); }
;     unsigned ap[4], bp[4];
; #pragma unroll
;     for (int i = 0; i < 4; ++i) {
;       const int r = (tid >> 3) + 64 * i;
;       const int cs = tid & 7;
;       const int c = ((cs ^ ((r >> 1) & 7)) << 3);
;       const int sub = 2 * mt + (r >> 7);
;       const int g = sub / tpg, ti = sub - g * tpg;
;       int rig = ti * step - halo + (r & 127); rig = rig < 0 ? 0 : (rig > grows - 1 ? grows - 1 : rig);
;       ap[i] = (unsigned)((g * a_gstride + a_goff + rig) * lda + c);
;       int br = nt * 256 + r; br = br > N - 1 ? N - 1 : br;
;       bp[i] = (unsigned)(br * K + c);
;     }
;     const bool have_next = false;
;     f32x4 acc[4][8];
; #pragma unroll
;     for (int m = 0; m < 4; ++m)
; #pragma unroll
;       for (int n = 0; n < 8; ++n) acc[m][n] = (f32x4){0.f, 0.f, 0.f, 0.f};
;     if (!pre_issued) {
; #pragma unroll
;       for (int i = 0; i < 4; ++i) { GLDS16(A + (size_t)ap[i], smem + tid * 16 + i * 8192); GLDS16(Bt + (size_t)bp[i], smem + 32768 + tid * 16 + i * 8192); }
;     }
;     pre_issued = have_next;
.LBB0_2642:
	s_ashr_i32 s4, s28, 31
	s_lshr_b32 s4, s4, 27
	s_add_i32 s4, s28, s4
	s_ashr_i32 s4, s4, 5
	s_lshl_b32 s6, s28, 1
	s_lshl_b32 s5, s4, 4
	s_and_b32 s6, s6, 14
	s_or_b32 s5, s5, s6
	v_add_u32_e32 v2, s5, v147
	v_ashrrev_i32_e32 v3, 31, v2
	v_lshrrev_b32_e32 v3, 28, v3
	v_add_u32_e32 v3, v2, v3
	v_ashrrev_i32_e32 v3, 4, v3
	v_lshlrev_b32_e32 v4, 11, v3
	v_lshlrev_b32_e32 v2, 7, v2
	v_sub_u32_e32 v2, v2, v4
	v_or_b32_e32 v4, v2, v148
	v_min_i32_e32 v4, 0x7ff, v4
	v_lshlrev_b32_e32 v4, 10, v4
	v_cmp_lt_i32_e32 vcc, -1, v2
	s_lshl_b32 s7, s4, 10
	s_lshl_b32 s4, s28, 5
	v_cndmask_b32_e32 v2, 0, v4, vcc
	v_lshl_add_u32 v18, v3, 21, v2
	v_add_u32_e32 v3, s5, v150
	v_ashrrev_i32_e32 v4, 31, v3
	v_lshrrev_b32_e32 v4, 28, v4
	v_add_u32_e32 v4, v3, v4
	v_ashrrev_i32_e32 v4, 4, v4
	v_lshlrev_b32_e32 v5, 11, v4
	v_lshlrev_b32_e32 v3, 7, v3
	v_sub_u32_e32 v3, v3, v5
	v_or_b32_e32 v5, v3, v151
	v_min_i32_e32 v5, 0x7ff, v5
	s_sub_i32 s4, s4, s7
	v_lshlrev_b32_e32 v5, 10, v5
	v_cmp_lt_i32_e32 vcc, -1, v3
	s_and_b32 s4, s4, 0xffffff00
	v_add_u32_e32 v2, s4, v140
	v_cndmask_b32_e32 v3, 0, v5, vcc
	v_lshl_add_u32 v19, v4, 21, v3
	v_add_u32_e32 v3, s4, v149
	v_min_i32_e32 v3, 0x3ff, v3
	v_lshl_or_b32 v6, v3, 10, v141
	v_add_u32_e32 v3, s5, v153
	v_ashrrev_i32_e32 v5, 31, v3
	v_lshrrev_b32_e32 v5, 28, v5
	v_add_u32_e32 v5, v3, v5
	v_ashrrev_i32_e32 v5, 4, v5
	v_lshlrev_b32_e32 v7, 11, v5
	v_lshlrev_b32_e32 v3, 7, v3
	v_sub_u32_e32 v3, v3, v7
	v_or_b32_e32 v7, v3, v148
	v_min_i32_e32 v7, 0x7ff, v7
	v_lshlrev_b32_e32 v7, 10, v7
	v_cmp_lt_i32_e32 vcc, -1, v3
	v_or_b32_e32 v130, v18, v141
	v_min_i32_e32 v2, 0x3ff, v2
	v_cndmask_b32_e32 v3, 0, v7, vcc
	v_lshl_add_u32 v20, v5, 21, v3
	v_add_u32_e32 v3, s4, v152
	v_min_i32_e32 v3, 0x3ff, v3
	v_lshl_or_b32 v10, v3, 10, v141
	v_add_u32_e32 v3, s5, v155
	v_ashrrev_i32_e32 v5, 31, v3
	v_lshrrev_b32_e32 v5, 28, v5
	v_add_u32_e32 v5, v3, v5
	v_ashrrev_i32_e32 v5, 4, v5
	v_lshlrev_b32_e32 v7, 11, v5
	v_lshlrev_b32_e32 v3, 7, v3
	v_sub_u32_e32 v3, v3, v7
	v_or_b32_e32 v7, v3, v156
	v_min_i32_e32 v7, 0x7ff, v7
	v_lshlrev_b32_e32 v7, 10, v7
	v_cmp_lt_i32_e32 vcc, -1, v3
	v_readfirstlane_b32 s8, v142
	v_lshl_or_b32 v2, v2, 10, v141
	v_cndmask_b32_e32 v3, 0, v7, vcc
	v_lshl_add_u32 v21, v5, 21, v3
	v_add_u32_e32 v3, s4, v154
	v_min_i32_e32 v3, 0x3ff, v3
	v_lshl_or_b32 v14, v3, 10, v141
	v_lshl_add_u64 v[16:17], v[130:131], 1, s[18:19]
	s_mov_b32 m0, s8
	v_mov_b32_e32 v3, v131
	v_readfirstlane_b32 s8, v160
	v_or_b32_e32 v4, v19, v141
	global_load_lds_dwordx4 v[16:17], off
	v_lshl_add_u64 v[2:3], v[2:3], 1, s[24:25]
	s_mov_b32 m0, s8
	v_mov_b32_e32 v5, v131
	v_readfirstlane_b32 s8, v161
	global_load_lds_dwordx4 v[2:3], off
	v_lshl_add_u64 v[2:3], v[4:5], 1, s[18:19]
	s_mov_b32 m0, s8
	v_mov_b32_e32 v7, v131
	v_readfirstlane_b32 s8, v162
	v_or_b32_e32 v8, v20, v141
	global_load_lds_dwordx4 v[2:3], off
	v_lshl_add_u64 v[2:3], v[6:7], 1, s[24:25]
	s_mov_b32 m0, s8
	v_mov_b32_e32 v9, v131
	v_readfirstlane_b32 s8, v163
	global_load_lds_dwordx4 v[2:3], off
	v_lshl_add_u64 v[2:3], v[8:9], 1, s[18:19]
	s_mov_b32 m0, s8
	v_mov_b32_e32 v11, v131
	v_readfirstlane_b32 s8, v164
	v_or_b32_e32 v12, v21, v141
	global_load_lds_dwordx4 v[2:3], off
	v_lshl_add_u64 v[2:3], v[10:11], 1, s[24:25]
	s_mov_b32 m0, s8
	v_mov_b32_e32 v13, v131
	v_readfirstlane_b32 s8, v165
	global_load_lds_dwordx4 v[2:3], off
	v_lshl_add_u64 v[2:3], v[12:13], 1, s[18:19]
	s_mov_b32 m0, s8
	v_mov_b32_e32 v15, v131
	v_readfirstlane_b32 s8, v166
	global_load_lds_dwordx4 v[2:3], off
	v_lshl_add_u64 v[2:3], v[14:15], 1, s[24:25]
	s_mov_b32 m0, s8
	s_sub_i32 s7, s29, s7
	global_load_lds_dwordx4 v[2:3], off
	s_and_b32 s7, s7, 0xffffff00
	v_add_u32_e32 v2, s7, v154
	v_min_i32_e32 v2, 0x3ff, v2
	v_lshl_or_b32 v132, v2, 10, v159
	v_add_u32_e32 v2, s7, v152
	v_min_i32_e32 v2, 0x3ff, v2
	v_lshl_or_b32 v134, v2, 10, v159
	v_add_u32_e32 v2, s7, v149
	v_min_i32_e32 v2, 0x3ff, v2
	v_lshl_or_b32 v136, v2, 10, v159
	v_add_u32_e32 v2, s7, v140
	v_min_i32_e32 v2, 0x3ff, v2
	s_mov_b32 s6, 0
	v_or_b32_e32 v133, v21, v159
	v_or_b32_e32 v135, v20, v159
	v_or_b32_e32 v137, v19, v159
	v_lshl_or_b32 v138, v2, 10, v159
	v_or_b32_e32 v139, v18, v159
	s_mov_b32 s7, 0
	v_mov_b32_e32 v90, v131
	v_mov_b32_e32 v91, v131
	v_mov_b32_e32 v92, v131
	v_mov_b32_e32 v93, v131
	v_mov_b32_e32 v2, v131
	v_mov_b32_e32 v3, v131
	v_mov_b32_e32 v4, v131
	v_mov_b32_e32 v6, v131
	v_mov_b32_e32 v8, v131
	v_mov_b32_e32 v10, v131
	v_mov_b32_e32 v12, v131
	v_mov_b32_e32 v22, v131
	v_mov_b32_e32 v23, v131
	v_mov_b32_e32 v24, v131
	v_mov_b32_e32 v25, v131
	v_mov_b32_e32 v26, v131
	v_mov_b32_e32 v27, v131
	v_mov_b32_e32 v28, v131
	v_mov_b32_e32 v29, v131
	v_mov_b32_e32 v42, v131
	v_mov_b32_e32 v43, v131
	v_mov_b32_e32 v44, v131
	v_mov_b32_e32 v45, v131
	v_mov_b32_e32 v50, v131
	v_mov_b32_e32 v51, v131
	v_mov_b32_e32 v52, v131
	v_mov_b32_e32 v53, v131
	v_mov_b32_e32 v14, v131
	v_mov_b32_e32 v16, v131
	v_mov_b32_e32 v17, v131
	v_mov_b32_e32 v18, v131
	v_mov_b32_e32 v19, v131
	v_mov_b32_e32 v20, v131
	v_mov_b32_e32 v21, v131
	v_mov_b32_e32 v30, v131
	v_mov_b32_e32 v31, v131
	v_mov_b32_e32 v32, v131
	v_mov_b32_e32 v33, v131
	v_mov_b32_e32 v46, v131
	v_mov_b32_e32 v47, v131
	v_mov_b32_e32 v48, v131
	v_mov_b32_e32 v49, v131
	v_mov_b32_e32 v54, v131
	v_mov_b32_e32 v55, v131
	v_mov_b32_e32 v56, v131
	v_mov_b32_e32 v57, v131
	v_mov_b32_e32 v58, v131
	v_mov_b32_e32 v59, v131
	v_mov_b32_e32 v60, v131
	v_mov_b32_e32 v61, v131
	v_mov_b32_e32 v78, v131
	v_mov_b32_e32 v79, v131
	v_mov_b32_e32 v80, v131
	v_mov_b32_e32 v81, v131
	v_mov_b32_e32 v82, v131
	v_mov_b32_e32 v83, v131
	v_mov_b32_e32 v84, v131
	v_mov_b32_e32 v85, v131
; template <bool SWAP, class Epi, bool THIN = false> ...
;     ...
;     for (int st = 0; st < ns; ++st) {
;       asm volatile("s_waitcnt vmcnt(0)" ::: "memory");
;       __builtin_amdgcn_s_barrier();
;       asm volatile("" ::: "memory");
;       if (st + 1 < ns) {
;         char* nb = smem + ((st + 1) & 1) * 65536;
;         const int ko = (st + 1) * 64;
; #pragma unroll
;         for (int i = 0; i < 4; ++i) { GLDS16(A + (size_t)(ap[i] + ko), nb + tid * 16 + i * 8192); GLDS16(Bt + (size_t)(bp[i] + ko), nb + 32768 + tid * 16 + i * 8192); }
;       }
;       const char* sa = smem + (st & 1) * 65536 + (wr * 64 + fr) * 128;
;       const char* sb = smem + (st & 1) * 65536 + 32768 + (wc * 128 + fr) * 128;
;       if constexpr (THIN) {
;         if (wc == 0) {
; #pragma unroll
;           for (int ks = 0; ks < 2; ++ks) {
;             bf16x8 af[4], bf[2];
; #pragma unroll
;             for (int m = 0; m < 4; ++m) af[m] = *(const bf16x8*)(sa + m * 2048 + (((ks * 4 + fq) ^ swz) << 4));
; #pragma unroll
;             for (int n = 0; n < 2; ++n) bf[n] = *(const bf16x8*)(sb + n * 2048 + (((ks * 4 + fq) ^ swz) << 4));
; #pragma unroll
;             for (int m = 0; m < 4; ++m)
; #pragma unroll
;               for (int n = 0; n < 2; ++n)
;                 acc[m][n] = SWAP ? __builtin_amdgcn_mfma_f32_16x16x32_bf16(bf[n], af[m], acc[m][n], 0, 0, 0)
;                                  : __builtin_amdgcn_mfma_f32_16x16x32_bf16(af[m], bf[n], acc[m][n], 0, 0, 0);
;           }
;         }
;       } else {
;       bf16x8 afA[4], afB[4], bfb[2][2];
; #pragma unroll
;       for (int m = 0; m < 4; ++m) afA[m] = *(const bf16x8*)(sa + m * 2048 + ((fq ^ swz) << 4));
; #pragma unroll
;       for (int n = 0; n < 2; ++n) bfb[0][n] = *(const bf16x8*)(sb + n * 2048 + ((fq ^ swz) << 4));
; #pragma unroll
;       for (int gq = 0; gq < 8; ++gq) {
;         const int ks = gq >> 2, nh = gq & 3;
;         if (gq < 7) {
;           const int ks2 = (gq + 1) >> 2, nh2 = (gq + 1) & 3;
; #pragma unroll
;           for (int n = 0; n < 2; ++n) bfb[(gq + 1) & 1][n] = *(const bf16x8*)(sb + (nh2 * 2 + n) * 2048 + (((ks2 * 4 + fq) ^ swz) << 4));
;         }
;         if (gq == 3) {
; #pragma unroll
;           for (int m = 0; m < 4; ++m) afB[m] = *(const bf16x8*)(sa + m * 2048 + (((4 + fq) ^ swz) << 4));
;         }
;         __builtin_amdgcn_sched_barrier(0);
; #pragma unroll
	v_mov_b32_e32 v34, v131
	v_mov_b32_e32 v35, v131
	v_mov_b32_e32 v36, v131
	v_mov_b32_e32 v37, v131
	v_mov_b32_e32 v38, v131
	v_mov_b32_e32 v39, v131
	v_mov_b32_e32 v40, v131
	v_mov_b32_e32 v41, v131
	v_mov_b32_e32 v66, v131
	v_mov_b32_e32 v67, v131
	v_mov_b32_e32 v68, v131
	v_mov_b32_e32 v69, v131
	v_mov_b32_e32 v74, v131
	v_mov_b32_e32 v75, v131
	v_mov_b32_e32 v76, v131
	v_mov_b32_e32 v77, v131
	v_mov_b32_e32 v86, v131
	v_mov_b32_e32 v87, v131
	v_mov_b32_e32 v88, v131
	v_mov_b32_e32 v89, v131
	v_mov_b32_e32 v94, v131
	v_mov_b32_e32 v95, v131
	v_mov_b32_e32 v96, v131
	v_mov_b32_e32 v97, v131
	v_mov_b32_e32 v106, v131
	v_mov_b32_e32 v107, v131
	v_mov_b32_e32 v108, v131
	v_mov_b32_e32 v109, v131
	v_mov_b32_e32 v110, v131
	v_mov_b32_e32 v111, v131
	v_mov_b32_e32 v112, v131
	v_mov_b32_e32 v113, v131
	v_mov_b32_e32 v62, v131
	v_mov_b32_e32 v63, v131
	v_mov_b32_e32 v64, v131
	v_mov_b32_e32 v65, v131
	v_mov_b32_e32 v70, v131
	v_mov_b32_e32 v71, v131
	v_mov_b32_e32 v72, v131
	v_mov_b32_e32 v73, v131
	v_mov_b32_e32 v98, v131
	v_mov_b32_e32 v99, v131
	v_mov_b32_e32 v100, v131
	v_mov_b32_e32 v101, v131
	v_mov_b32_e32 v102, v131
	v_mov_b32_e32 v103, v131
	v_mov_b32_e32 v104, v131
	v_mov_b32_e32 v105, v131
	v_mov_b32_e32 v114, v131
	v_mov_b32_e32 v115, v131
	v_mov_b32_e32 v116, v131
	v_mov_b32_e32 v117, v131
	v_mov_b32_e32 v118, v131
	v_mov_b32_e32 v119, v131
	v_mov_b32_e32 v120, v131
	v_mov_b32_e32 v121, v131
	v_mov_b32_e32 v122, v131
	v_mov_b32_e32 v123, v131
	v_mov_b32_e32 v124, v131
	v_mov_b32_e32 v125, v131
	v_mov_b32_e32 v126, v131
	v_mov_b32_e32 v127, v131
	v_mov_b32_e32 v128, v131
	v_mov_b32_e32 v129, v131
	v_lshlrev_b32_e32 v139, 1, v139
	v_lshlrev_b32_e32 v138, 1, v138
	v_lshlrev_b32_e32 v137, 1, v137
	v_lshlrev_b32_e32 v136, 1, v136
	v_lshlrev_b32_e32 v135, 1, v135
	v_lshlrev_b32_e32 v134, 1, v134
	v_lshlrev_b32_e32 v133, 1, v133
	v_lshlrev_b32_e32 v132, 1, v132
.LBB0_2643:
	s_add_i32 s8, s7, 0x10000
	s_and_b32 s9, s8, 0x10000
	v_add_u32_e32 v167, s9, v142
	s_nop 0
	v_readfirstlane_b32 s9, v167
	s_waitcnt vmcnt(0)
	s_barrier
	s_and_b32 s7, s7, 0x10000
	v_add_u32_e32 v130, s7, v143
	v_add_u32_e32 v167, v130, v145
	ds_read_b128 v[168:171], v167
	ds_read_b128 v[172:175], v167 offset:2048
	ds_read_b128 v[176:179], v167 offset:4096
	ds_read_b128 v[180:183], v167 offset:6144
	v_or_b32_e32 v167, s7, v144
	v_add_u32_e32 v204, v167, v145
	ds_read_b128 v[184:187], v204 offset:32768
	ds_read_b128 v[188:191], v204 offset:34816
	ds_read_b128 v[192:195], v204 offset:36864
	ds_read_b128 v[196:199], v204 offset:38912
	v_add_u32_e32 v130, v130, v146
	s_waitcnt lgkmcnt(0)
	v_mfma_f32_16x16x32_bf16 v[126:129], v[184:187], v[168:171], v[126:129]
	s_mov_b32 m0, s9
	v_mfma_f32_16x16x32_bf16 v[110:113], v[184:187], v[172:175], v[110:113]
	global_load_lds_dwordx4 v139, s[18:19]
	v_add_u32_e32 v139, 0x80, v139
	v_mfma_f32_16x16x32_bf16 v[82:85], v[184:187], v[176:179], v[82:85]
	v_mfma_f32_16x16x32_bf16 v[50:53], v[184:187], v[180:183], v[50:53]
	ds_read_b128 v[184:187], v204 offset:40960
	ds_read_b128 v[200:203], v204 offset:43008
	v_mfma_f32_16x16x32_bf16 v[122:125], v[188:191], v[168:171], v[122:125]
	s_add_u32 m0, s9, 0x8000
	v_mfma_f32_16x16x32_bf16 v[106:109], v[188:191], v[172:175], v[106:109]
	global_load_lds_dwordx4 v138, s[24:25]
	v_add_u32_e32 v138, 0x80, v138
	v_mfma_f32_16x16x32_bf16 v[78:81], v[188:191], v[176:179], v[78:81]
	v_mfma_f32_16x16x32_bf16 v[42:45], v[188:191], v[180:183], v[42:45]
	v_mfma_f32_16x16x32_bf16 v[118:121], v[192:195], v[168:171], v[118:121]
	s_add_u32 m0, s9, 0x2000
	v_mfma_f32_16x16x32_bf16 v[94:97], v[192:195], v[172:175], v[94:97]
	global_load_lds_dwordx4 v137, s[18:19]
	v_add_u32_e32 v137, 0x80, v137
	v_mfma_f32_16x16x32_bf16 v[58:61], v[192:195], v[176:179], v[58:61]
	v_mfma_f32_16x16x32_bf16 v[26:29], v[192:195], v[180:183], v[26:29]
	ds_read_b128 v[188:191], v204 offset:45056
	ds_read_b128 v[192:195], v204 offset:47104
	v_mfma_f32_16x16x32_bf16 v[114:117], v[196:199], v[168:171], v[114:117]
	s_add_u32 m0, s9, 0xa000
	v_mfma_f32_16x16x32_bf16 v[86:89], v[196:199], v[172:175], v[86:89]
	global_load_lds_dwordx4 v136, s[24:25]
	v_add_u32_e32 v136, 0x80, v136
	v_mfma_f32_16x16x32_bf16 v[54:57], v[196:199], v[176:179], v[54:57]
	v_mfma_f32_16x16x32_bf16 v[22:25], v[196:199], v[180:183], v[22:25]
	v_add_u32_e32 v167, v167, v146
	s_waitcnt lgkmcnt(0)
	v_mfma_f32_16x16x32_bf16 v[102:105], v[184:187], v[168:171], v[102:105]
	ds_read_b128 v[196:199], v167 offset:32768
	ds_read_b128 v[204:207], v167 offset:34816
	s_add_u32 m0, s9, 0x4000
	v_mfma_f32_16x16x32_bf16 v[74:77], v[184:187], v[172:175], v[74:77]
	global_load_lds_dwordx4 v135, s[18:19]
	v_add_u32_e32 v135, 0x80, v135
	v_mfma_f32_16x16x32_bf16 v[46:49], v[184:187], v[176:179], v[46:49]
	v_mfma_f32_16x16x32_bf16 v[10:13], v[184:187], v[180:183], v[10:13]
	ds_read_b128 v[184:187], v130
	ds_read_b128 v[208:211], v130 offset:2048
	ds_read_b128 v[212:215], v130 offset:4096
	ds_read_b128 v[216:219], v130 offset:6144
	v_mfma_f32_16x16x32_bf16 v[98:101], v[200:203], v[168:171], v[98:101]
	s_add_u32 m0, s9, 0xc000
	v_mfma_f32_16x16x32_bf16 v[66:69], v[200:203], v[172:175], v[66:69]
	global_load_lds_dwordx4 v134, s[24:25]
	v_add_u32_e32 v134, 0x80, v134
	v_mfma_f32_16x16x32_bf16 v[30:33], v[200:203], v[176:179], v[30:33]
	v_mfma_f32_16x16x32_bf16 v[6:9], v[200:203], v[180:183], v[6:9]
	v_mfma_f32_16x16x32_bf16 v[70:73], v[188:191], v[168:171], v[70:73]
	s_add_u32 m0, s9, 0x6000
	v_mfma_f32_16x16x32_bf16 v[62:65], v[192:195], v[168:171], v[62:65]
	global_load_lds_dwordx4 v133, s[18:19]
	v_add_u32_e32 v133, 0x80, v133
	v_mfma_f32_16x16x32_bf16 v[38:41], v[188:191], v[172:175], v[38:41]
	v_mfma_f32_16x16x32_bf16 v[34:37], v[192:195], v[172:175], v[34:37]
	ds_read_b128 v[168:171], v167 offset:36864
	ds_read_b128 v[172:175], v167 offset:38912
	v_mfma_f32_16x16x32_bf16 v[18:21], v[188:191], v[176:179], v[18:21]
	s_add_u32 m0, s9, 0xe000
	v_mfma_f32_16x16x32_bf16 v[14:17], v[192:195], v[176:179], v[14:17]
	global_load_lds_dwordx4 v132, s[24:25]
	v_add_u32_e32 v132, 0x80, v132
	v_mfma_f32_16x16x32_bf16 v[2:5], v[188:191], v[180:183], v[2:5]
	v_mfma_f32_16x16x32_bf16 v[90:93], v[192:195], v[180:183], v[90:93]
	ds_read_b128 v[176:179], v167 offset:40960
	ds_read_b128 v[180:183], v167 offset:43008
	s_waitcnt lgkmcnt(0)
; template <bool SWAP, class Epi, bool THIN = false> ...
;     ...
;       bf16x8 afA[4], afB[4], bfb[2][2];
; #pragma unroll
;       for (int m = 0; m < 4; ++m) afA[m] = *(const bf16x8*)(sa + m * 2048 + ((fq ^ swz) << 4));
; #pragma unroll
;       for (int n = 0; n < 2; ++n) bfb[0][n] = *(const bf16x8*)(sb + n * 2048 + ((fq ^ swz) << 4));
; #pragma unroll
;       for (int gq = 0; gq < 8; ++gq) {
;         const int ks = gq >> 2, nh = gq & 3;
;         if (gq < 7) {
;           const int ks2 = (gq + 1) >> 2, nh2 = (gq + 1) & 3;
; #pragma unroll
;           for (int n = 0; n < 2; ++n) bfb[(gq + 1) & 1][n] = *(const bf16x8*)(sb + (nh2 * 2 + n) * 2048 + (((ks2 * 4 + fq) ^ swz) << 4));
;         }
;         if (gq == 3) {
; #pragma unroll
;           for (int m = 0; m < 4; ++m) afB[m] = *(const bf16x8*)(sa + m * 2048 + (((4 + fq) ^ swz) << 4));
;         }
;         __builtin_amdgcn_sched_barrier(0);
; #pragma unroll
;         for (int m = 0; m < 4; ++m)
; #pragma unroll
;           for (int n = 0; n < 2; ++n) {
;             const bf16x8 av = ks ? afB[m] : afA[m];
;             acc[m][nh * 2 + n] = SWAP ? __builtin_amdgcn_mfma_f32_16x16x32_bf16(bfb[gq & 1][n], av, acc[m][nh * 2 + n], 0, 0, 0)
;                                       : __builtin_amdgcn_mfma_f32_16x16x32_bf16(av, bfb[gq & 1][n], acc[m][nh * 2 + n], 0, 0, 0);
;           }
;       }
	v_mfma_f32_16x16x32_bf16 v[126:129], v[196:199], v[184:187], v[126:129]
	v_mfma_f32_16x16x32_bf16 v[122:125], v[204:207], v[184:187], v[122:125]
	v_mfma_f32_16x16x32_bf16 v[110:113], v[196:199], v[208:211], v[110:113]
	v_mfma_f32_16x16x32_bf16 v[106:109], v[204:207], v[208:211], v[106:109]
	v_mfma_f32_16x16x32_bf16 v[82:85], v[196:199], v[212:215], v[82:85]
	v_mfma_f32_16x16x32_bf16 v[78:81], v[204:207], v[212:215], v[78:81]
	v_mfma_f32_16x16x32_bf16 v[50:53], v[196:199], v[216:219], v[50:53]
	v_mfma_f32_16x16x32_bf16 v[42:45], v[204:207], v[216:219], v[42:45]
	v_mfma_f32_16x16x32_bf16 v[118:121], v[168:171], v[184:187], v[118:121]
	v_mfma_f32_16x16x32_bf16 v[94:97], v[168:171], v[208:211], v[94:97]
	v_mfma_f32_16x16x32_bf16 v[58:61], v[168:171], v[212:215], v[58:61]
	v_mfma_f32_16x16x32_bf16 v[26:29], v[168:171], v[216:219], v[26:29]
	ds_read_b128 v[168:171], v167 offset:45056
	ds_read_b128 v[188:191], v167 offset:47104
	v_mfma_f32_16x16x32_bf16 v[114:117], v[172:175], v[184:187], v[114:117]
	v_mfma_f32_16x16x32_bf16 v[86:89], v[172:175], v[208:211], v[86:89]
	v_mfma_f32_16x16x32_bf16 v[54:57], v[172:175], v[212:215], v[54:57]
	v_mfma_f32_16x16x32_bf16 v[22:25], v[172:175], v[216:219], v[22:25]
	v_mfma_f32_16x16x32_bf16 v[102:105], v[176:179], v[184:187], v[102:105]
	v_mfma_f32_16x16x32_bf16 v[98:101], v[180:183], v[184:187], v[98:101]
	v_mfma_f32_16x16x32_bf16 v[74:77], v[176:179], v[208:211], v[74:77]
	v_mfma_f32_16x16x32_bf16 v[66:69], v[180:183], v[208:211], v[66:69]
	v_mfma_f32_16x16x32_bf16 v[46:49], v[176:179], v[212:215], v[46:49]
	v_mfma_f32_16x16x32_bf16 v[30:33], v[180:183], v[212:215], v[30:33]
	v_mfma_f32_16x16x32_bf16 v[10:13], v[176:179], v[216:219], v[10:13]
	v_mfma_f32_16x16x32_bf16 v[6:9], v[180:183], v[216:219], v[6:9]
	s_waitcnt lgkmcnt(0)
	v_mfma_f32_16x16x32_bf16 v[70:73], v[168:171], v[184:187], v[70:73]
	s_add_i32 s6, s6, 64
	s_cmpk_eq_i32 s6, 0x3c0
	s_mov_b32 s7, s8
	v_mfma_f32_16x16x32_bf16 v[62:65], v[188:191], v[184:187], v[62:65]
	v_mfma_f32_16x16x32_bf16 v[38:41], v[168:171], v[208:211], v[38:41]
	v_mfma_f32_16x16x32_bf16 v[34:37], v[188:191], v[208:211], v[34:37]
	v_mfma_f32_16x16x32_bf16 v[18:21], v[168:171], v[212:215], v[18:21]
	v_mfma_f32_16x16x32_bf16 v[14:17], v[188:191], v[212:215], v[14:17]
	v_mfma_f32_16x16x32_bf16 v[2:5], v[168:171], v[216:219], v[2:5]
	v_mfma_f32_16x16x32_bf16 v[90:93], v[188:191], v[216:219], v[90:93]
	s_cbranch_scc0 .LBB0_2643
	s_waitcnt vmcnt(0)
	s_barrier
	v_add_u32_e32 v130, v157, v145
	ds_read_b128 v[132:135], v130
	ds_read_b128 v[136:139], v130 offset:2048
	ds_read_b128 v[168:171], v130 offset:4096
	ds_read_b128 v[172:175], v130 offset:6144
	v_add_u32_e32 v130, v158, v145
	ds_read_b128 v[176:179], v130
	ds_read_b128 v[180:183], v130 offset:2048
	ds_read_b128 v[184:187], v130 offset:4096
	ds_read_b128 v[188:191], v130 offset:6144
	s_waitcnt lgkmcnt(0)
	v_mfma_f32_16x16x32_bf16 v[126:129], v[176:179], v[132:135], v[126:129]
	v_mfma_f32_16x16x32_bf16 v[110:113], v[176:179], v[136:139], v[110:113]
	v_mfma_f32_16x16x32_bf16 v[82:85], v[176:179], v[168:171], v[82:85]
	v_mfma_f32_16x16x32_bf16 v[50:53], v[176:179], v[172:175], v[50:53]
	ds_read_b128 v[176:179], v130 offset:8192
	ds_read_b128 v[192:195], v130 offset:10240
	v_mfma_f32_16x16x32_bf16 v[122:125], v[180:183], v[132:135], v[122:125]
	v_mfma_f32_16x16x32_bf16 v[106:109], v[180:183], v[136:139], v[106:109]
	v_mfma_f32_16x16x32_bf16 v[78:81], v[180:183], v[168:171], v[78:81]
	v_mfma_f32_16x16x32_bf16 v[42:45], v[180:183], v[172:175], v[42:45]
	v_mfma_f32_16x16x32_bf16 v[118:121], v[184:187], v[132:135], v[118:121]
	v_mfma_f32_16x16x32_bf16 v[180:183], v[184:187], v[136:139], v[94:97]
	v_mfma_f32_16x16x32_bf16 v[200:203], v[184:187], v[168:171], v[58:61]
	v_mfma_f32_16x16x32_bf16 v[204:207], v[188:191], v[168:171], v[54:57]
	v_mfma_f32_16x16x32_bf16 v[184:187], v[184:187], v[172:175], v[26:29]
	s_nop 2
	ds_read_b128 v[26:29], v130 offset:12288
	ds_read_b128 v[54:57], v130 offset:14336
	v_mfma_f32_16x16x32_bf16 v[114:117], v[188:191], v[132:135], v[114:117]
	v_mfma_f32_16x16x32_bf16 v[196:199], v[188:191], v[136:139], v[86:89]
	v_mfma_f32_16x16x32_bf16 v[188:191], v[188:191], v[172:175], v[22:25]
	v_add_u32_e32 v130, v158, v146
	s_waitcnt lgkmcnt(0)
; template <bool SWAP, class Epi, bool THIN = false> ...
;     ...
;       bf16x8 afA[4], afB[4], bfb[2][2];
; #pragma unroll
;       for (int m = 0; m < 4; ++m) afA[m] = *(const bf16x8*)(sa + m * 2048 + ((fq ^ swz) << 4));
; #pragma unroll
;       for (int n = 0; n < 2; ++n) bfb[0][n] = *(const bf16x8*)(sb + n * 2048 + ((fq ^ swz) << 4));
; #pragma unroll
;       for (int gq = 0; gq < 8; ++gq) {
;         const int ks = gq >> 2, nh = gq & 3;
;         if (gq < 7) {
;           const int ks2 = (gq + 1) >> 2, nh2 = (gq + 1) & 3;
; #pragma unroll
;           for (int n = 0; n < 2; ++n) bfb[(gq + 1) & 1][n] = *(const bf16x8*)(sb + (nh2 * 2 + n) * 2048 + (((ks2 * 4 + fq) ^ swz) << 4));
;         }
;         if (gq == 3) {
; #pragma unroll
;           for (int m = 0; m < 4; ++m) afB[m] = *(const bf16x8*)(sa + m * 2048 + (((4 + fq) ^ swz) << 4));
;         }
;         __builtin_amdgcn_sched_barrier(0);
; #pragma unroll
;         for (int m = 0; m < 4; ++m)
; #pragma unroll
;           for (int n = 0; n < 2; ++n) {
;             const bf16x8 av = ks ? afB[m] : afA[m];
;             acc[m][nh * 2 + n] = SWAP ? __builtin_amdgcn_mfma_f32_16x16x32_bf16(bfb[gq & 1][n], av, acc[m][nh * 2 + n], 0, 0, 0)
;                                       : __builtin_amdgcn_mfma_f32_16x16x32_bf16(av, bfb[gq & 1][n], acc[m][nh * 2 + n], 0, 0, 0);
;           }
;       }
;       }
;     }
;     __syncthreads();
;     const int te = get_tid512();
;     const int fr_e = te & 15, fq_e = (te & 63) >> 4, wr_e = te >> 7, wc_e = (te >> 6) & 1;
;     const int sub = 2 * mt + (wr_e >> 1);
;     const int g = sub / tpg, ti = sub - g * tpg;
;     const int rig0 = ti * step - halo;
;     const int rw = (wr_e & 1) * 64;
;     if constexpr (Epi::KIND == 0) {
; #pragma unroll
;       for (int m = 0; m < 4; ++m) {
;         const int rig = rig0 + rw + m * 16 + fr_e;
;         if constexpr (Epi::ROWSUM) {
;           float ss = 0.f;
; #pragma unroll
;           for (int n = 0; n < 8; ++n) {
;             const int col = nt * 256 + wc_e * 128 + n * 16 + fq_e * 4;
;             if (col < N) ss += epi.c4(g, rig, col, acc[m][n]);
;           }
;           ss += __shfl_xor(ss, 16); ss += __shfl_xor(ss, 32);
;           if (fq_e == 0) epi.rowsum(g, rig, nt * 2 + wc_e, ss);
;         } else {
; #pragma unroll
;           for (int n = 0; n < 8; ++n) {
	v_mfma_f32_16x16x32_bf16 v[208:211], v[192:195], v[168:171], v[30:33]
	ds_read_b128 v[22:25], v130
	ds_read_b128 v[86:89], v130 offset:2048
	s_nop 0
	v_add_u32_e32 v30, v157, v146
	v_mfma_f32_16x16x32_bf16 v[102:105], v[176:179], v[132:135], v[102:105]
	v_mfma_f32_16x16x32_bf16 v[74:77], v[176:179], v[136:139], v[74:77]
	v_mfma_f32_16x16x32_bf16 v[46:49], v[176:179], v[168:171], v[46:49]
	v_mfma_f32_16x16x32_bf16 v[10:13], v[176:179], v[172:175], v[10:13]
	ds_read_b128 v[176:179], v30
	ds_read_b128 v[212:215], v30 offset:2048
	ds_read_b128 v[216:219], v30 offset:4096
	ds_read_b128 v[220:223], v30 offset:6144
	v_mfma_f32_16x16x32_bf16 v[98:101], v[192:195], v[132:135], v[98:101]
	v_mfma_f32_16x16x32_bf16 v[66:69], v[192:195], v[136:139], v[66:69]
	v_mfma_f32_16x16x32_bf16 v[6:9], v[192:195], v[172:175], v[6:9]
	v_mfma_f32_16x16x32_bf16 v[224:227], v[26:29], v[136:139], v[38:41]
	v_mfma_f32_16x16x32_bf16 v[34:37], v[54:57], v[136:139], v[34:37]
	v_mfma_f32_16x16x32_bf16 v[136:139], v[26:29], v[168:171], v[18:21]
	v_mfma_f32_16x16x32_bf16 v[168:171], v[54:57], v[168:171], v[14:17]
	s_nop 2
	ds_read_b128 v[14:17], v130 offset:4096
	ds_read_b128 v[18:21], v130 offset:6144
	v_mfma_f32_16x16x32_bf16 v[192:195], v[26:29], v[132:135], v[70:73]
	v_mfma_f32_16x16x32_bf16 v[132:135], v[54:57], v[132:135], v[62:65]
	v_mfma_f32_16x16x32_bf16 v[2:5], v[26:29], v[172:175], v[2:5]
	v_mfma_f32_16x16x32_bf16 v[172:175], v[54:57], v[172:175], v[90:93]
	ds_read_b128 v[228:231], v130 offset:8192
	ds_read_b128 v[232:235], v130 offset:10240
	s_waitcnt lgkmcnt(0)
	v_mfma_f32_16x16x32_bf16 v[126:129], v[22:25], v[176:179], v[126:129]
	v_mfma_f32_16x16x32_bf16 v[122:125], v[86:89], v[176:179], v[122:125]
	v_mfma_f32_16x16x32_bf16 v[94:97], v[22:25], v[212:215], v[110:113]
	v_mfma_f32_16x16x32_bf16 v[90:93], v[86:89], v[212:215], v[106:109]
	v_mfma_f32_16x16x32_bf16 v[62:65], v[22:25], v[216:219], v[82:85]
	v_mfma_f32_16x16x32_bf16 v[58:61], v[86:89], v[216:219], v[78:81]
	v_mfma_f32_16x16x32_bf16 v[30:33], v[22:25], v[220:223], v[50:53]
	v_mfma_f32_16x16x32_bf16 v[26:29], v[86:89], v[220:223], v[42:45]
	v_mfma_f32_16x16x32_bf16 v[86:89], v[14:17], v[212:215], v[180:183]
	v_mfma_f32_16x16x32_bf16 v[22:25], v[14:17], v[220:223], v[184:187]
	s_nop 1
	ds_read_b128 v[180:183], v130 offset:12288
	ds_read_b128 v[184:187], v130 offset:14336
	v_mfma_f32_16x16x32_bf16 v[118:121], v[14:17], v[176:179], v[118:121]
	v_mfma_f32_16x16x32_bf16 v[114:117], v[18:21], v[176:179], v[114:117]
	v_mfma_f32_16x16x32_bf16 v[82:85], v[18:21], v[212:215], v[196:199]
	v_mfma_f32_16x16x32_bf16 v[54:57], v[14:17], v[216:219], v[200:203]
	v_mfma_f32_16x16x32_bf16 v[50:53], v[18:21], v[216:219], v[204:207]
	v_mfma_f32_16x16x32_bf16 v[18:21], v[18:21], v[220:223], v[188:191]
	v_mfma_f32_16x16x32_bf16 v[110:113], v[228:231], v[176:179], v[102:105]
	v_mfma_f32_16x16x32_bf16 v[106:109], v[232:235], v[176:179], v[98:101]
	v_mfma_f32_16x16x32_bf16 v[78:81], v[228:231], v[212:215], v[74:77]
	v_mfma_f32_16x16x32_bf16 v[70:73], v[232:235], v[212:215], v[66:69]
	v_mfma_f32_16x16x32_bf16 v[46:49], v[228:231], v[216:219], v[46:49]
	v_mfma_f32_16x16x32_bf16 v[38:41], v[232:235], v[216:219], v[208:211]
	v_mfma_f32_16x16x32_bf16 v[14:17], v[228:231], v[220:223], v[10:13]
	v_mfma_f32_16x16x32_bf16 v[6:9], v[232:235], v[220:223], v[6:9]
	v_mov_b32_e32 v130, v1
	s_waitcnt vmcnt(0) lgkmcnt(0)
	s_barrier
	v_mfma_f32_16x16x32_bf16 v[102:105], v[180:183], v[176:179], v[192:195]
	v_ashrrev_i32_e32 v11, 8, v130
	v_add_u32_e32 v11, s5, v11
	v_ashrrev_i32_e32 v12, 31, v11
	v_lshrrev_b32_e32 v12, 28, v12
	v_add_u32_e32 v12, v11, v12
	v_mfma_f32_16x16x32_bf16 v[98:101], v[184:187], v[176:179], v[132:135]
	v_ashrrev_i32_e32 v176, 4, v12
	v_lshlrev_b32_e32 v12, 11, v176
	v_lshlrev_b32_e32 v11, 7, v11
	v_sub_u32_e32 v11, v11, v12
	v_lshrrev_b32_e32 v12, 1, v130
	v_and_b32_e32 v10, 15, v130
	v_and_b32_e32 v12, 64, v12
	v_or3_b32 v134, v11, v12, v10
	v_lshlrev_b32_e32 v10, 1, v130
	v_and_b32_e32 v132, 0x80, v10
	v_mfma_f32_16x16x32_bf16 v[10:13], v[180:183], v[220:223], v[2:5]
	v_ashrrev_i32_e32 v177, 31, v176
	v_ashrrev_i32_e32 v135, 31, v134
	s_nop 0
	v_lshrrev_b32_e32 v2, 2, v130
	v_and_b32_e32 v2, 12, v2
	v_mfma_f32_16x16x32_bf16 v[74:77], v[180:183], v[212:215], v[224:227]
	v_or3_b32 v132, v2, v132, s4
	v_cmp_gt_i32_e32 vcc, s31, v132
	v_ashrrev_i32_e32 v133, 31, v132
	v_mfma_f32_16x16x32_bf16 v[66:69], v[184:187], v[212:215], v[34:37]
	v_mfma_f32_16x16x32_bf16 v[42:45], v[180:183], v[216:219], v[136:139]
	v_mfma_f32_16x16x32_bf16 v[34:37], v[184:187], v[216:219], v[168:171]
	s_nop 1
	v_lshlrev_b64 v[136:137], 11, v[176:177]
	v_lshl_add_u64 v[138:139], v[136:137], 0, v[134:135]
	v_lshlrev_b64 v[138:139], 11, v[138:139]
	v_mfma_f32_16x16x32_bf16 v[2:5], v[184:187], v[220:223], v[172:175]
	v_lshl_add_u64 v[138:139], s[20:21], 0, v[138:139]
	s_and_saveexec_b64 s[4:5], vcc
	s_cbranch_execz .LBB0_2646
	v_lshl_add_u64 v[168:169], v[132:133], 2, s[22:23]
	global_load_dwordx4 v[168:171], v[168:169], off
	s_waitcnt vmcnt(0)
	v_add_f32_e32 v126, v126, v168
	v_add_f32_e32 v127, v127, v169
	v_add_f32_e32 v128, v128, v170
	v_add_f32_e32 v129, v129, v171
	v_cvt_pk_bf16_f32 v126, v126, v127
	v_cvt_pk_bf16_f32 v127, v128, v129
	v_lshl_add_u64 v[128:129], v[132:133], 1, v[138:139]
	global_store_dwordx2 v[128:129], v[126:127], off

; #define GLDS16(gp, lp) __builtin_amdgcn_global_load_lds((const unsigned*)(gp), (__attribute__((address_space(3))) unsigned*)(lp), 16, 0, 0)
; template <bool SWAP, class Epi, bool THIN = false> ...
;     ...
;   for (; v < voff + ntiles; v += grid) {
;     const int w = v - voff;
;     int mt, nt;
;     if (w < full * 8 * NT) { const int sr = w / (8 * NT), rem = w - sr * 8 * NT; nt = rem >> 3; mt = sr * 8 + (rem & 7); }
;     else { const int w2 = w - full * 8 * NT, rl = MT - full * 8; nt = w2 / rl; mt = full * 8 + (w2 - nt * rl); }
;     unsigned ap[4], bp[4];
; #pragma unroll
;     for (int i = 0; i < 4; ++i) {
;       const int r = (tid >> 3) + 64 * i;
;       const int cs = tid & 7;
;       const int c = ((cs ^ ((r >> 1) & 7)) << 3);
;       const int sub = 2 * mt + (r >> 7);
;       const int g = sub / tpg, ti = sub - g * tpg;
;       int rig = ti * step - halo + (r & 127); rig = rig < 0 ? 0 : (rig > grows - 1 ? grows - 1 : rig);
;       ap[i] = (unsigned)((g * a_gstride + a_goff + rig) * lda + c);
;       int br = nt * 256 + r; br = br > N - 1 ? N - 1 : br;
;       bp[i] = (unsigned)(br * K + c);
;     }
;     const bool have_next = false;
;     f32x4 acc[4][8];
; #pragma unroll
;     for (int m = 0; m < 4; ++m)
; #pragma unroll
;       for (int n = 0; n < 8; ++n) acc[m][n] = (f32x4){0.f, 0.f, 0.f, 0.f};
;     if (!pre_issued) {
; #pragma unroll
;       for (int i = 0; i < 4; ++i) { GLDS16(A + (size_t)ap[i], smem + tid * 16 + i * 8192); GLDS16(Bt + (size_t)bp[i], smem + 32768 + tid * 16 + i * 8192); }
;     }
;     pre_issued = have_next;
.LBB0_2713:
	s_add_i32 s4, s3, 0xffffff00
	s_ashr_i32 s5, s4, 31
	s_lshr_b32 s5, s5, 26
	s_add_i32 s5, s4, s5
	s_ashr_i32 s6, s5, 6
	s_lshl_b32 s7, s3, 1
	s_lshl_b32 s5, s6, 4
	s_and_b32 s7, s7, 14
	s_or_b32 s5, s5, s7
	v_add_u32_e32 v2, s5, v143
	v_ashrrev_i32_e32 v3, 31, v2
	v_lshrrev_b32_e32 v3, 28, v3
	v_add_u32_e32 v3, v2, v3
	v_ashrrev_i32_e32 v3, 4, v3
	v_lshlrev_b32_e32 v4, 11, v3
	v_lshlrev_b32_e32 v2, 7, v2
	v_sub_u32_e32 v2, v2, v4
	v_or_b32_e32 v4, v2, v144
	v_min_i32_e32 v4, 0x7ff, v4
	v_lshlrev_b32_e32 v4, 10, v4
	v_cmp_lt_i32_e32 vcc, -1, v2
	s_lshl_b32 s7, s6, 11
	s_lshl_b32 s4, s4, 5
	v_cndmask_b32_e32 v2, 0, v4, vcc
	v_lshl_add_u32 v18, v3, 21, v2
	v_add_u32_e32 v3, s5, v146
	v_ashrrev_i32_e32 v4, 31, v3
	v_lshrrev_b32_e32 v4, 28, v4
	v_add_u32_e32 v4, v3, v4
	v_ashrrev_i32_e32 v4, 4, v4
	v_lshlrev_b32_e32 v5, 11, v4
	v_lshlrev_b32_e32 v3, 7, v3
	v_sub_u32_e32 v3, v3, v5
	v_or_b32_e32 v5, v3, v147
	v_min_i32_e32 v5, 0x7ff, v5
	s_sub_i32 s4, s4, s7
	v_lshlrev_b32_e32 v5, 10, v5
	v_cmp_lt_i32_e32 vcc, -1, v3
	s_and_b32 s4, s4, 0xffffff00
	v_add_u32_e32 v2, s4, v136
	v_cndmask_b32_e32 v3, 0, v5, vcc
	v_lshl_add_u32 v19, v4, 21, v3
	v_add_u32_e32 v3, s4, v145
	v_min_i32_e32 v3, 0x7ff, v3
	v_lshl_or_b32 v6, v3, 10, v137
	v_add_u32_e32 v3, s5, v149
	v_ashrrev_i32_e32 v5, 31, v3
	v_lshrrev_b32_e32 v5, 28, v5
	v_add_u32_e32 v5, v3, v5
	v_ashrrev_i32_e32 v5, 4, v5
	v_lshlrev_b32_e32 v7, 11, v5
	v_lshlrev_b32_e32 v3, 7, v3
	v_sub_u32_e32 v3, v3, v7
	v_or_b32_e32 v7, v3, v144
	v_min_i32_e32 v7, 0x7ff, v7
	v_lshlrev_b32_e32 v7, 10, v7
	v_cmp_lt_i32_e32 vcc, -1, v3
	v_or_b32_e32 v130, v18, v137
	v_min_i32_e32 v2, 0x7ff, v2
	v_cndmask_b32_e32 v3, 0, v7, vcc
	v_lshl_add_u32 v20, v5, 21, v3
	v_add_u32_e32 v3, s4, v148
	v_min_i32_e32 v3, 0x7ff, v3
	v_lshl_or_b32 v10, v3, 10, v137
	v_add_u32_e32 v3, s5, v151
	v_ashrrev_i32_e32 v5, 31, v3
	v_lshrrev_b32_e32 v5, 28, v5
	v_add_u32_e32 v5, v3, v5
	v_ashrrev_i32_e32 v5, 4, v5
	v_lshlrev_b32_e32 v7, 11, v5
	v_lshlrev_b32_e32 v3, 7, v3
	v_sub_u32_e32 v3, v3, v7
	v_or_b32_e32 v7, v3, v152
	v_min_i32_e32 v7, 0x7ff, v7
	v_lshlrev_b32_e32 v7, 10, v7
	v_cmp_lt_i32_e32 vcc, -1, v3
	v_readfirstlane_b32 s8, v138
	v_lshl_or_b32 v2, v2, 10, v137
	v_cndmask_b32_e32 v3, 0, v7, vcc
	v_lshl_add_u32 v21, v5, 21, v3
	v_add_u32_e32 v3, s4, v150
	v_min_i32_e32 v3, 0x7ff, v3
	v_lshl_or_b32 v14, v3, 10, v137
	v_lshl_add_u64 v[16:17], v[130:131], 1, s[18:19]
	s_mov_b32 m0, s8
	v_mov_b32_e32 v3, v131
	v_readfirstlane_b32 s8, v156
	v_or_b32_e32 v4, v19, v137
	global_load_lds_dwordx4 v[16:17], off
	v_lshl_add_u64 v[2:3], v[2:3], 1, s[24:25]
	s_mov_b32 m0, s8
	v_mov_b32_e32 v5, v131
	v_readfirstlane_b32 s8, v157
	global_load_lds_dwordx4 v[2:3], off
	v_lshl_add_u64 v[2:3], v[4:5], 1, s[18:19]
	s_mov_b32 m0, s8
	v_mov_b32_e32 v7, v131
	v_readfirstlane_b32 s8, v158
	v_or_b32_e32 v8, v20, v137
	global_load_lds_dwordx4 v[2:3], off
	v_lshl_add_u64 v[2:3], v[6:7], 1, s[24:25]
	s_mov_b32 m0, s8
	v_mov_b32_e32 v9, v131
	v_readfirstlane_b32 s8, v159
	global_load_lds_dwordx4 v[2:3], off
	v_lshl_add_u64 v[2:3], v[8:9], 1, s[18:19]
	s_mov_b32 m0, s8
	v_mov_b32_e32 v11, v131
	v_readfirstlane_b32 s8, v160
	v_or_b32_e32 v12, v21, v137
	global_load_lds_dwordx4 v[2:3], off
	v_lshl_add_u64 v[2:3], v[10:11], 1, s[24:25]
	s_mov_b32 m0, s8
	v_mov_b32_e32 v13, v131
	v_readfirstlane_b32 s8, v161
	global_load_lds_dwordx4 v[2:3], off
	v_lshl_add_u64 v[2:3], v[12:13], 1, s[18:19]
	s_mov_b32 m0, s8
	v_mov_b32_e32 v15, v131
	v_readfirstlane_b32 s8, v162
	global_load_lds_dwordx4 v[2:3], off
	v_lshl_add_u64 v[2:3], v[14:15], 1, s[24:25]
	s_mov_b32 m0, s8
	s_sub_i32 s7, s28, s7
	global_load_lds_dwordx4 v[2:3], off
	s_and_b32 s7, s7, 0xffffff00
	v_add_u32_e32 v2, s7, v150
	v_min_i32_e32 v2, 0x7ff, v2
	v_lshl_or_b32 v132, v2, 10, v155
	v_add_u32_e32 v2, s7, v148
	v_min_i32_e32 v2, 0x7ff, v2
	v_lshl_or_b32 v134, v2, 10, v155
	v_add_u32_e32 v2, s7, v145
	v_min_i32_e32 v2, 0x7ff, v2
	v_lshl_or_b32 v163, v2, 10, v155
	v_add_u32_e32 v2, s7, v136
	v_min_i32_e32 v2, 0x7ff, v2
	s_mov_b32 s6, 0
	v_or_b32_e32 v133, v21, v155
	v_or_b32_e32 v135, v20, v155
	v_or_b32_e32 v164, v19, v155
	v_lshl_or_b32 v165, v2, 10, v155
	v_or_b32_e32 v166, v18, v155
	s_mov_b32 s7, 0
	v_mov_b32_e32 v90, v131
	v_mov_b32_e32 v91, v131
	v_mov_b32_e32 v92, v131
	v_mov_b32_e32 v93, v131
	v_mov_b32_e32 v2, v131
	v_mov_b32_e32 v3, v131
	v_mov_b32_e32 v4, v131
	v_mov_b32_e32 v6, v131
	v_mov_b32_e32 v8, v131
	v_mov_b32_e32 v10, v131
	v_mov_b32_e32 v12, v131
	v_mov_b32_e32 v22, v131
	v_mov_b32_e32 v23, v131
	v_mov_b32_e32 v24, v131
	v_mov_b32_e32 v25, v131
	v_mov_b32_e32 v26, v131
	v_mov_b32_e32 v27, v131
	v_mov_b32_e32 v28, v131
	v_mov_b32_e32 v29, v131
	v_mov_b32_e32 v42, v131
	v_mov_b32_e32 v43, v131
	v_mov_b32_e32 v44, v131
	v_mov_b32_e32 v45, v131
	v_mov_b32_e32 v50, v131
	v_mov_b32_e32 v51, v131
	v_mov_b32_e32 v52, v131
	v_mov_b32_e32 v53, v131
	v_mov_b32_e32 v14, v131
	v_mov_b32_e32 v16, v131
	v_mov_b32_e32 v17, v131
	v_mov_b32_e32 v18, v131
	v_mov_b32_e32 v19, v131
	v_mov_b32_e32 v20, v131
	v_mov_b32_e32 v21, v131
	v_mov_b32_e32 v30, v131
	v_mov_b32_e32 v31, v131
	v_mov_b32_e32 v32, v131
	v_mov_b32_e32 v33, v131
	v_mov_b32_e32 v46, v131
	v_mov_b32_e32 v47, v131
	v_mov_b32_e32 v48, v131
	v_mov_b32_e32 v49, v131
	v_mov_b32_e32 v54, v131
	v_mov_b32_e32 v55, v131
	v_mov_b32_e32 v56, v131
	v_mov_b32_e32 v57, v131
	v_mov_b32_e32 v58, v131
	v_mov_b32_e32 v59, v131
	v_mov_b32_e32 v60, v131
	v_mov_b32_e32 v61, v131
	v_mov_b32_e32 v78, v131
	v_mov_b32_e32 v79, v131
	v_mov_b32_e32 v80, v131
	v_mov_b32_e32 v81, v131
	v_mov_b32_e32 v82, v131
	v_mov_b32_e32 v83, v131
	v_mov_b32_e32 v84, v131
; template <bool SWAP, class Epi, bool THIN = false> ...
;     ...
;     for (int st = 0; st < ns; ++st) {
;       asm volatile("s_waitcnt vmcnt(0)" ::: "memory");
;       __builtin_amdgcn_s_barrier();
;       asm volatile("" ::: "memory");
;       if (st + 1 < ns) {
;         char* nb = smem + ((st + 1) & 1) * 65536;
;         const int ko = (st + 1) * 64;
; #pragma unroll
;         for (int i = 0; i < 4; ++i) { GLDS16(A + (size_t)(ap[i] + ko), nb + tid * 16 + i * 8192); GLDS16(Bt + (size_t)(bp[i] + ko), nb + 32768 + tid * 16 + i * 8192); }
;       }
;       const char* sa = smem + (st & 1) * 65536 + (wr * 64 + fr) * 128;
;       const char* sb = smem + (st & 1) * 65536 + 32768 + (wc * 128 + fr) * 128;
;       if constexpr (THIN) {
;         if (wc == 0) {
; #pragma unroll
;           for (int ks = 0; ks < 2; ++ks) {
;             bf16x8 af[4], bf[2];
; #pragma unroll
;             for (int m = 0; m < 4; ++m) af[m] = *(const bf16x8*)(sa + m * 2048 + (((ks * 4 + fq) ^ swz) << 4));
; #pragma unroll
;             for (int n = 0; n < 2; ++n) bf[n] = *(const bf16x8*)(sb + n * 2048 + (((ks * 4 + fq) ^ swz) << 4));
; #pragma unroll
;             for (int m = 0; m < 4; ++m)
; #pragma unroll
;               for (int n = 0; n < 2; ++n)
;                 acc[m][n] = SWAP ? __builtin_amdgcn_mfma_f32_16x16x32_bf16(bf[n], af[m], acc[m][n], 0, 0, 0)
;                                  : __builtin_amdgcn_mfma_f32_16x16x32_bf16(af[m], bf[n], acc[m][n], 0, 0, 0);
;           }
;         }
;       } else {
;       bf16x8 afA[4], afB[4], bfb[2][2];
; #pragma unroll
;       for (int m = 0; m < 4; ++m) afA[m] = *(const bf16x8*)(sa + m * 2048 + ((fq ^ swz) << 4));
; #pragma unroll
;       for (int n = 0; n < 2; ++n) bfb[0][n] = *(const bf16x8*)(sb + n * 2048 + ((fq ^ swz) << 4));
; #pragma unroll
;       for (int gq = 0; gq < 8; ++gq) {
;         const int ks = gq >> 2, nh = gq & 3;
;         if (gq < 7) {
;           const int ks2 = (gq + 1) >> 2, nh2 = (gq + 1) & 3;
; #pragma unroll
;           for (int n = 0; n < 2; ++n) bfb[(gq + 1) & 1][n] = *(const bf16x8*)(sb + (nh2 * 2 + n) * 2048 + (((ks2 * 4 + fq) ^ swz) << 4));
;         }
;         if (gq == 3) {
; #pragma unroll
;           for (int m = 0; m < 4; ++m) afB[m] = *(const bf16x8*)(sa + m * 2048 + (((4 + fq) ^ swz) << 4));
;         }
;         __builtin_amdgcn_sched_barrier(0);
; #pragma unroll
	v_mov_b32_e32 v85, v131
	v_mov_b32_e32 v34, v131
	v_mov_b32_e32 v35, v131
	v_mov_b32_e32 v36, v131
	v_mov_b32_e32 v37, v131
	v_mov_b32_e32 v38, v131
	v_mov_b32_e32 v39, v131
	v_mov_b32_e32 v40, v131
	v_mov_b32_e32 v41, v131
	v_mov_b32_e32 v66, v131
	v_mov_b32_e32 v67, v131
	v_mov_b32_e32 v68, v131
	v_mov_b32_e32 v69, v131
	v_mov_b32_e32 v74, v131
	v_mov_b32_e32 v75, v131
	v_mov_b32_e32 v76, v131
	v_mov_b32_e32 v77, v131
	v_mov_b32_e32 v86, v131
	v_mov_b32_e32 v87, v131
	v_mov_b32_e32 v88, v131
	v_mov_b32_e32 v89, v131
	v_mov_b32_e32 v94, v131
	v_mov_b32_e32 v95, v131
	v_mov_b32_e32 v96, v131
	v_mov_b32_e32 v97, v131
	v_mov_b32_e32 v106, v131
	v_mov_b32_e32 v107, v131
	v_mov_b32_e32 v108, v131
	v_mov_b32_e32 v109, v131
	v_mov_b32_e32 v110, v131
	v_mov_b32_e32 v111, v131
	v_mov_b32_e32 v112, v131
	v_mov_b32_e32 v113, v131
	v_mov_b32_e32 v62, v131
	v_mov_b32_e32 v63, v131
	v_mov_b32_e32 v64, v131
	v_mov_b32_e32 v65, v131
	v_mov_b32_e32 v70, v131
	v_mov_b32_e32 v71, v131
	v_mov_b32_e32 v72, v131
	v_mov_b32_e32 v73, v131
	v_mov_b32_e32 v98, v131
	v_mov_b32_e32 v99, v131
	v_mov_b32_e32 v100, v131
	v_mov_b32_e32 v101, v131
	v_mov_b32_e32 v102, v131
	v_mov_b32_e32 v103, v131
	v_mov_b32_e32 v104, v131
	v_mov_b32_e32 v105, v131
	v_mov_b32_e32 v114, v131
	v_mov_b32_e32 v115, v131
	v_mov_b32_e32 v116, v131
	v_mov_b32_e32 v117, v131
	v_mov_b32_e32 v118, v131
	v_mov_b32_e32 v119, v131
	v_mov_b32_e32 v120, v131
	v_mov_b32_e32 v121, v131
	v_mov_b32_e32 v122, v131
	v_mov_b32_e32 v123, v131
	v_mov_b32_e32 v124, v131
	v_mov_b32_e32 v125, v131
	v_mov_b32_e32 v126, v131
	v_mov_b32_e32 v127, v131
	v_mov_b32_e32 v128, v131
	v_mov_b32_e32 v129, v131
	v_lshlrev_b32_e32 v166, 1, v166
	v_lshlrev_b32_e32 v165, 1, v165
	v_lshlrev_b32_e32 v164, 1, v164
	v_lshlrev_b32_e32 v163, 1, v163
	v_lshlrev_b32_e32 v135, 1, v135
	v_lshlrev_b32_e32 v134, 1, v134
	v_lshlrev_b32_e32 v133, 1, v133
	v_lshlrev_b32_e32 v132, 1, v132
.LBB0_2714:
	s_add_i32 s8, s7, 0x10000
	s_and_b32 s9, s8, 0x10000
	v_add_u32_e32 v167, s9, v138
	s_nop 0
	v_readfirstlane_b32 s9, v167
	s_waitcnt vmcnt(0)
	s_barrier
	s_and_b32 s7, s7, 0x10000
	v_add_u32_e32 v130, s7, v139
	v_add_u32_e32 v167, v130, v141
	ds_read_b128 v[168:171], v167
	ds_read_b128 v[172:175], v167 offset:2048
	ds_read_b128 v[176:179], v167 offset:4096
	ds_read_b128 v[180:183], v167 offset:6144
	v_or_b32_e32 v167, s7, v140
	v_add_u32_e32 v204, v167, v141
	ds_read_b128 v[184:187], v204 offset:32768
	ds_read_b128 v[188:191], v204 offset:34816
	ds_read_b128 v[192:195], v204 offset:36864
	ds_read_b128 v[196:199], v204 offset:38912
	v_add_u32_e32 v130, v130, v142
	s_waitcnt lgkmcnt(0)
	v_mfma_f32_16x16x32_bf16 v[126:129], v[168:171], v[184:187], v[126:129]
	s_mov_b32 m0, s9
	v_mfma_f32_16x16x32_bf16 v[110:113], v[172:175], v[184:187], v[110:113]
	global_load_lds_dwordx4 v166, s[18:19]
	v_add_u32_e32 v166, 0x80, v166
	v_mfma_f32_16x16x32_bf16 v[82:85], v[176:179], v[184:187], v[82:85]
	v_mfma_f32_16x16x32_bf16 v[50:53], v[180:183], v[184:187], v[50:53]
	ds_read_b128 v[184:187], v204 offset:40960
	ds_read_b128 v[200:203], v204 offset:43008
	v_mfma_f32_16x16x32_bf16 v[122:125], v[168:171], v[188:191], v[122:125]
	s_add_u32 m0, s9, 0x8000
	v_mfma_f32_16x16x32_bf16 v[106:109], v[172:175], v[188:191], v[106:109]
	global_load_lds_dwordx4 v165, s[24:25]
	v_add_u32_e32 v165, 0x80, v165
	v_mfma_f32_16x16x32_bf16 v[78:81], v[176:179], v[188:191], v[78:81]
	v_mfma_f32_16x16x32_bf16 v[42:45], v[180:183], v[188:191], v[42:45]
	v_mfma_f32_16x16x32_bf16 v[118:121], v[168:171], v[192:195], v[118:121]
	s_add_u32 m0, s9, 0x2000
	v_mfma_f32_16x16x32_bf16 v[94:97], v[172:175], v[192:195], v[94:97]
	global_load_lds_dwordx4 v164, s[18:19]
	v_add_u32_e32 v164, 0x80, v164
	v_mfma_f32_16x16x32_bf16 v[58:61], v[176:179], v[192:195], v[58:61]
	v_mfma_f32_16x16x32_bf16 v[26:29], v[180:183], v[192:195], v[26:29]
	ds_read_b128 v[188:191], v204 offset:45056
	ds_read_b128 v[192:195], v204 offset:47104
	v_mfma_f32_16x16x32_bf16 v[114:117], v[168:171], v[196:199], v[114:117]
	s_add_u32 m0, s9, 0xa000
	v_mfma_f32_16x16x32_bf16 v[86:89], v[172:175], v[196:199], v[86:89]
	global_load_lds_dwordx4 v163, s[24:25]
	v_add_u32_e32 v163, 0x80, v163
	v_mfma_f32_16x16x32_bf16 v[54:57], v[176:179], v[196:199], v[54:57]
	v_mfma_f32_16x16x32_bf16 v[22:25], v[180:183], v[196:199], v[22:25]
	v_add_u32_e32 v167, v167, v142
	s_waitcnt lgkmcnt(0)
	v_mfma_f32_16x16x32_bf16 v[102:105], v[168:171], v[184:187], v[102:105]
	ds_read_b128 v[196:199], v167 offset:32768
	ds_read_b128 v[204:207], v167 offset:34816
	s_add_u32 m0, s9, 0x4000
	v_mfma_f32_16x16x32_bf16 v[74:77], v[172:175], v[184:187], v[74:77]
	global_load_lds_dwordx4 v135, s[18:19]
	v_add_u32_e32 v135, 0x80, v135
	v_mfma_f32_16x16x32_bf16 v[46:49], v[176:179], v[184:187], v[46:49]
	v_mfma_f32_16x16x32_bf16 v[10:13], v[180:183], v[184:187], v[10:13]
	ds_read_b128 v[184:187], v130
	ds_read_b128 v[208:211], v130 offset:2048
	ds_read_b128 v[212:215], v130 offset:4096
	ds_read_b128 v[216:219], v130 offset:6144
	v_mfma_f32_16x16x32_bf16 v[98:101], v[168:171], v[200:203], v[98:101]
	s_add_u32 m0, s9, 0xc000
	v_mfma_f32_16x16x32_bf16 v[66:69], v[172:175], v[200:203], v[66:69]
	global_load_lds_dwordx4 v134, s[24:25]
	v_add_u32_e32 v134, 0x80, v134
	v_mfma_f32_16x16x32_bf16 v[30:33], v[176:179], v[200:203], v[30:33]
	v_mfma_f32_16x16x32_bf16 v[6:9], v[180:183], v[200:203], v[6:9]
	v_mfma_f32_16x16x32_bf16 v[70:73], v[168:171], v[188:191], v[70:73]
	s_add_u32 m0, s9, 0x6000
	v_mfma_f32_16x16x32_bf16 v[62:65], v[168:171], v[192:195], v[62:65]
	global_load_lds_dwordx4 v133, s[18:19]
	v_add_u32_e32 v133, 0x80, v133
	v_mfma_f32_16x16x32_bf16 v[38:41], v[172:175], v[188:191], v[38:41]
	v_mfma_f32_16x16x32_bf16 v[34:37], v[172:175], v[192:195], v[34:37]
	ds_read_b128 v[168:171], v167 offset:36864
	ds_read_b128 v[172:175], v167 offset:38912
	v_mfma_f32_16x16x32_bf16 v[18:21], v[176:179], v[188:191], v[18:21]
	s_add_u32 m0, s9, 0xe000
	v_mfma_f32_16x16x32_bf16 v[14:17], v[176:179], v[192:195], v[14:17]
	global_load_lds_dwordx4 v132, s[24:25]
	v_add_u32_e32 v132, 0x80, v132
	v_mfma_f32_16x16x32_bf16 v[2:5], v[180:183], v[188:191], v[2:5]
	v_mfma_f32_16x16x32_bf16 v[90:93], v[180:183], v[192:195], v[90:93]
	ds_read_b128 v[176:179], v167 offset:40960
	ds_read_b128 v[180:183], v167 offset:43008
	s_waitcnt lgkmcnt(0)
; template <bool SWAP, class Epi, bool THIN = false> ...
;     ...
;       bf16x8 afA[4], afB[4], bfb[2][2];
; #pragma unroll
;       for (int m = 0; m < 4; ++m) afA[m] = *(const bf16x8*)(sa + m * 2048 + ((fq ^ swz) << 4));
; #pragma unroll
;       for (int n = 0; n < 2; ++n) bfb[0][n] = *(const bf16x8*)(sb + n * 2048 + ((fq ^ swz) << 4));
; #pragma unroll
;       for (int gq = 0; gq < 8; ++gq) {
;         const int ks = gq >> 2, nh = gq & 3;
;         if (gq < 7) {
;           const int ks2 = (gq + 1) >> 2, nh2 = (gq + 1) & 3;
; #pragma unroll
;           for (int n = 0; n < 2; ++n) bfb[(gq + 1) & 1][n] = *(const bf16x8*)(sb + (nh2 * 2 + n) * 2048 + (((ks2 * 4 + fq) ^ swz) << 4));
;         }
;         if (gq == 3) {
; #pragma unroll
;           for (int m = 0; m < 4; ++m) afB[m] = *(const bf16x8*)(sa + m * 2048 + (((4 + fq) ^ swz) << 4));
;         }
;         __builtin_amdgcn_sched_barrier(0);
; #pragma unroll
;         for (int m = 0; m < 4; ++m)
; #pragma unroll
;           for (int n = 0; n < 2; ++n) {
;             const bf16x8 av = ks ? afB[m] : afA[m];
;             acc[m][nh * 2 + n] = SWAP ? __builtin_amdgcn_mfma_f32_16x16x32_bf16(bfb[gq & 1][n], av, acc[m][nh * 2 + n], 0, 0, 0)
;                                       : __builtin_amdgcn_mfma_f32_16x16x32_bf16(av, bfb[gq & 1][n], acc[m][nh * 2 + n], 0, 0, 0);
;           }
;       }
	v_mfma_f32_16x16x32_bf16 v[126:129], v[184:187], v[196:199], v[126:129]
	v_mfma_f32_16x16x32_bf16 v[122:125], v[184:187], v[204:207], v[122:125]
	v_mfma_f32_16x16x32_bf16 v[110:113], v[208:211], v[196:199], v[110:113]
	v_mfma_f32_16x16x32_bf16 v[106:109], v[208:211], v[204:207], v[106:109]
	v_mfma_f32_16x16x32_bf16 v[82:85], v[212:215], v[196:199], v[82:85]
	v_mfma_f32_16x16x32_bf16 v[78:81], v[212:215], v[204:207], v[78:81]
	v_mfma_f32_16x16x32_bf16 v[50:53], v[216:219], v[196:199], v[50:53]
	v_mfma_f32_16x16x32_bf16 v[42:45], v[216:219], v[204:207], v[42:45]
	v_mfma_f32_16x16x32_bf16 v[118:121], v[184:187], v[168:171], v[118:121]
	v_mfma_f32_16x16x32_bf16 v[94:97], v[208:211], v[168:171], v[94:97]
	v_mfma_f32_16x16x32_bf16 v[58:61], v[212:215], v[168:171], v[58:61]
	v_mfma_f32_16x16x32_bf16 v[26:29], v[216:219], v[168:171], v[26:29]
	ds_read_b128 v[168:171], v167 offset:45056
	ds_read_b128 v[188:191], v167 offset:47104
	v_mfma_f32_16x16x32_bf16 v[114:117], v[184:187], v[172:175], v[114:117]
	v_mfma_f32_16x16x32_bf16 v[86:89], v[208:211], v[172:175], v[86:89]
	v_mfma_f32_16x16x32_bf16 v[54:57], v[212:215], v[172:175], v[54:57]
	v_mfma_f32_16x16x32_bf16 v[22:25], v[216:219], v[172:175], v[22:25]
	v_mfma_f32_16x16x32_bf16 v[102:105], v[184:187], v[176:179], v[102:105]
	v_mfma_f32_16x16x32_bf16 v[98:101], v[184:187], v[180:183], v[98:101]
	v_mfma_f32_16x16x32_bf16 v[74:77], v[208:211], v[176:179], v[74:77]
	v_mfma_f32_16x16x32_bf16 v[66:69], v[208:211], v[180:183], v[66:69]
	v_mfma_f32_16x16x32_bf16 v[46:49], v[212:215], v[176:179], v[46:49]
	v_mfma_f32_16x16x32_bf16 v[30:33], v[212:215], v[180:183], v[30:33]
	v_mfma_f32_16x16x32_bf16 v[10:13], v[216:219], v[176:179], v[10:13]
	v_mfma_f32_16x16x32_bf16 v[6:9], v[216:219], v[180:183], v[6:9]
	s_waitcnt lgkmcnt(0)
	v_mfma_f32_16x16x32_bf16 v[70:73], v[184:187], v[168:171], v[70:73]
	s_add_i32 s6, s6, 64
	s_cmpk_eq_i32 s6, 0x3c0
	s_mov_b32 s7, s8
	v_mfma_f32_16x16x32_bf16 v[62:65], v[184:187], v[188:191], v[62:65]
	v_mfma_f32_16x16x32_bf16 v[38:41], v[208:211], v[168:171], v[38:41]
	v_mfma_f32_16x16x32_bf16 v[34:37], v[208:211], v[188:191], v[34:37]
	v_mfma_f32_16x16x32_bf16 v[18:21], v[212:215], v[168:171], v[18:21]
	v_mfma_f32_16x16x32_bf16 v[14:17], v[212:215], v[188:191], v[14:17]
	v_mfma_f32_16x16x32_bf16 v[2:5], v[216:219], v[168:171], v[2:5]
	v_mfma_f32_16x16x32_bf16 v[90:93], v[216:219], v[188:191], v[90:93]
	s_cbranch_scc0 .LBB0_2714
	s_waitcnt vmcnt(0)
	s_barrier
	v_add_u32_e32 v130, v153, v141
	ds_read_b128 v[132:135], v130
	ds_read_b128 v[164:167], v130 offset:2048
	ds_read_b128 v[168:171], v130 offset:4096
	ds_read_b128 v[172:175], v130 offset:6144
	v_add_u32_e32 v130, v154, v141
	ds_read_b128 v[176:179], v130
	ds_read_b128 v[180:183], v130 offset:2048
	ds_read_b128 v[184:187], v130 offset:4096
	ds_read_b128 v[188:191], v130 offset:6144
	s_waitcnt lgkmcnt(0)
	v_mfma_f32_16x16x32_bf16 v[126:129], v[132:135], v[176:179], v[126:129]
	v_mfma_f32_16x16x32_bf16 v[110:113], v[164:167], v[176:179], v[110:113]
	v_mfma_f32_16x16x32_bf16 v[82:85], v[168:171], v[176:179], v[82:85]
	v_mfma_f32_16x16x32_bf16 v[50:53], v[172:175], v[176:179], v[50:53]
	ds_read_b128 v[176:179], v130 offset:8192
	ds_read_b128 v[192:195], v130 offset:10240
	v_mfma_f32_16x16x32_bf16 v[122:125], v[132:135], v[180:183], v[122:125]
	v_mfma_f32_16x16x32_bf16 v[106:109], v[164:167], v[180:183], v[106:109]
	v_mfma_f32_16x16x32_bf16 v[78:81], v[168:171], v[180:183], v[78:81]
	v_mfma_f32_16x16x32_bf16 v[42:45], v[172:175], v[180:183], v[42:45]
	v_mfma_f32_16x16x32_bf16 v[118:121], v[132:135], v[184:187], v[118:121]
	v_mfma_f32_16x16x32_bf16 v[180:183], v[164:167], v[184:187], v[94:97]
	v_mfma_f32_16x16x32_bf16 v[200:203], v[168:171], v[184:187], v[58:61]
	v_mfma_f32_16x16x32_bf16 v[204:207], v[168:171], v[188:191], v[54:57]
	v_mfma_f32_16x16x32_bf16 v[184:187], v[172:175], v[184:187], v[26:29]
	s_nop 2
	ds_read_b128 v[26:29], v130 offset:12288
	ds_read_b128 v[54:57], v130 offset:14336
	v_mfma_f32_16x16x32_bf16 v[114:117], v[132:135], v[188:191], v[114:117]
	v_mfma_f32_16x16x32_bf16 v[196:199], v[164:167], v[188:191], v[86:89]
	v_mfma_f32_16x16x32_bf16 v[188:191], v[172:175], v[188:191], v[22:25]
	v_add_u32_e32 v130, v154, v142
	s_waitcnt lgkmcnt(0)
; __device__ __forceinline__ unsigned pack2(float a, float b) { unsigned r; asm("v_cvt_pk_bf16_f32 %0, %1, %2" : "=v"(r) : "v"(a), "v"(b)); return r; }
;   __device__ __forceinline__ void r4(int g, int rig, int col, f32x4 v) const {
;     const float b = bias[col];
;     uint2 u; u.x = pack2(v[0] + b, v[1] + b); u.y = pack2(v[2] + b, v[3] + b);
;     *(uint2*)(out + (size_t)col * 16384 + (size_t)g * 2048 + rig) = u;
;   }
; template <bool SWAP, class Epi, bool THIN = false> ...
;     ...
;       for (int m = 0; m < 4; ++m) {
;         const int rig = rig0 + rw + m * 16 + fq_e * 4;
; #pragma unroll
;         for (int n = 0; n < 8; ++n) {
;           const int col = nt * 256 + wc_e * 128 + n * 16 + fr_e;
;           if (col < N) epi.r4(g, rig, col, acc[m][n]);
	v_mfma_f32_16x16x32_bf16 v[208:211], v[168:171], v[192:195], v[30:33]
	ds_read_b128 v[22:25], v130
	ds_read_b128 v[86:89], v130 offset:2048
	s_nop 0
	v_add_u32_e32 v30, v153, v142
	v_mfma_f32_16x16x32_bf16 v[102:105], v[132:135], v[176:179], v[102:105]
	v_mfma_f32_16x16x32_bf16 v[74:77], v[164:167], v[176:179], v[74:77]
	v_mfma_f32_16x16x32_bf16 v[46:49], v[168:171], v[176:179], v[46:49]
	v_mfma_f32_16x16x32_bf16 v[10:13], v[172:175], v[176:179], v[10:13]
	ds_read_b128 v[176:179], v30
	ds_read_b128 v[212:215], v30 offset:2048
	ds_read_b128 v[216:219], v30 offset:4096
	ds_read_b128 v[220:223], v30 offset:6144
	v_mfma_f32_16x16x32_bf16 v[98:101], v[132:135], v[192:195], v[98:101]
	v_mfma_f32_16x16x32_bf16 v[66:69], v[164:167], v[192:195], v[66:69]
	v_mfma_f32_16x16x32_bf16 v[6:9], v[172:175], v[192:195], v[6:9]
	v_mfma_f32_16x16x32_bf16 v[192:195], v[164:167], v[26:29], v[38:41]
	v_mfma_f32_16x16x32_bf16 v[34:37], v[164:167], v[54:57], v[34:37]
	v_mfma_f32_16x16x32_bf16 v[164:167], v[168:171], v[26:29], v[18:21]
	v_mfma_f32_16x16x32_bf16 v[168:171], v[168:171], v[54:57], v[14:17]
	s_nop 2
	ds_read_b128 v[14:17], v130 offset:4096
	ds_read_b128 v[18:21], v130 offset:6144
	v_mfma_f32_16x16x32_bf16 v[70:73], v[132:135], v[26:29], v[70:73]
	v_mfma_f32_16x16x32_bf16 v[132:135], v[132:135], v[54:57], v[62:65]
	v_mfma_f32_16x16x32_bf16 v[2:5], v[172:175], v[26:29], v[2:5]
	v_mfma_f32_16x16x32_bf16 v[172:175], v[172:175], v[54:57], v[90:93]
	ds_read_b128 v[224:227], v130 offset:8192
	ds_read_b128 v[228:231], v130 offset:10240
	s_waitcnt lgkmcnt(0)
	v_mfma_f32_16x16x32_bf16 v[126:129], v[176:179], v[22:25], v[126:129]
	v_mfma_f32_16x16x32_bf16 v[122:125], v[176:179], v[86:89], v[122:125]
	v_mfma_f32_16x16x32_bf16 v[94:97], v[212:215], v[22:25], v[110:113]
	v_mfma_f32_16x16x32_bf16 v[90:93], v[212:215], v[86:89], v[106:109]
	v_mfma_f32_16x16x32_bf16 v[62:65], v[216:219], v[22:25], v[82:85]
	v_mfma_f32_16x16x32_bf16 v[58:61], v[216:219], v[86:89], v[78:81]
	v_mfma_f32_16x16x32_bf16 v[30:33], v[220:223], v[22:25], v[50:53]
	v_mfma_f32_16x16x32_bf16 v[26:29], v[220:223], v[86:89], v[42:45]
	v_mfma_f32_16x16x32_bf16 v[86:89], v[212:215], v[14:17], v[180:183]
	v_mfma_f32_16x16x32_bf16 v[22:25], v[220:223], v[14:17], v[184:187]
	s_nop 1
	ds_read_b128 v[180:183], v130 offset:12288
	ds_read_b128 v[184:187], v130 offset:14336
	v_mfma_f32_16x16x32_bf16 v[118:121], v[176:179], v[14:17], v[118:121]
	v_mfma_f32_16x16x32_bf16 v[114:117], v[176:179], v[18:21], v[114:117]
	v_mfma_f32_16x16x32_bf16 v[82:85], v[212:215], v[18:21], v[196:199]
	v_mfma_f32_16x16x32_bf16 v[54:57], v[216:219], v[14:17], v[200:203]
	v_mfma_f32_16x16x32_bf16 v[50:53], v[216:219], v[18:21], v[204:207]
	v_mfma_f32_16x16x32_bf16 v[18:21], v[220:223], v[18:21], v[188:191]
	v_mfma_f32_16x16x32_bf16 v[110:113], v[176:179], v[224:227], v[102:105]
	v_mfma_f32_16x16x32_bf16 v[106:109], v[176:179], v[228:231], v[98:101]
	v_mfma_f32_16x16x32_bf16 v[78:81], v[212:215], v[224:227], v[74:77]
	v_mfma_f32_16x16x32_bf16 v[74:77], v[212:215], v[228:231], v[66:69]
	v_mfma_f32_16x16x32_bf16 v[46:49], v[216:219], v[224:227], v[46:49]
	v_mfma_f32_16x16x32_bf16 v[38:41], v[216:219], v[228:231], v[208:211]
	v_mfma_f32_16x16x32_bf16 v[14:17], v[220:223], v[224:227], v[10:13]
	v_mfma_f32_16x16x32_bf16 v[6:9], v[220:223], v[228:231], v[6:9]
	v_mov_b32_e32 v130, v1
	s_waitcnt vmcnt(0) lgkmcnt(0)
	s_barrier
	v_mfma_f32_16x16x32_bf16 v[98:101], v[176:179], v[184:187], v[132:135]
	v_ashrrev_i32_e32 v10, 8, v130
	v_add_u32_e32 v10, s5, v10
	v_ashrrev_i32_e32 v11, 31, v10
	v_lshrrev_b32_e32 v11, 28, v11
	v_add_u32_e32 v11, v10, v11
	v_ashrrev_i32_e32 v132, 4, v11
	v_lshlrev_b32_e32 v11, 11, v132
	v_lshlrev_b32_e32 v10, 7, v10
	v_sub_u32_e32 v10, v10, v11
	v_lshrrev_b32_e32 v11, 1, v130
	v_lshrrev_b32_e32 v12, 2, v130
	v_and_b32_e32 v11, 64, v11
	v_and_b32_e32 v12, 12, v12
	v_mfma_f32_16x16x32_bf16 v[42:45], v[216:219], v[180:183], v[164:167]
	v_and_b32_e32 v133, 15, v130
	s_nop 1
	v_or3_b32 v164, v10, v11, v12
	v_mfma_f32_16x16x32_bf16 v[10:13], v[220:223], v[180:183], v[2:5]
	v_ashrrev_i32_e32 v165, 31, v164
	s_nop 1
	v_lshlrev_b32_e32 v2, 1, v130
	v_and_b32_e32 v2, 0x80, v2
	v_mfma_f32_16x16x32_bf16 v[102:105], v[176:179], v[180:183], v[70:73]
	v_or3_b32 v134, v133, v2, s4
	v_ashrrev_i32_e32 v133, 31, v132
	v_lshlrev_b64 v[132:133], 12, v[132:133]
	v_mfma_f32_16x16x32_bf16 v[70:73], v[212:215], v[180:183], v[192:195]
	v_lshl_add_u64 v[132:133], s[20:21], 0, v[132:133]
	v_lshl_add_u64 v[132:133], v[164:165], 1, v[132:133]
	v_cmp_gt_i32_e32 vcc, s30, v134
	v_mfma_f32_16x16x32_bf16 v[66:69], v[212:215], v[184:187], v[34:37]
	v_ashrrev_i32_e32 v135, 31, v134
	v_mfma_f32_16x16x32_bf16 v[34:37], v[216:219], v[184:187], v[168:171]
	v_mfma_f32_16x16x32_bf16 v[2:5], v[220:223], v[184:187], v[172:175]
	s_and_saveexec_b64 s[4:5], vcc
	s_cbranch_execz .LBB0_2717
	v_lshl_add_u64 v[164:165], v[134:135], 2, s[22:23]
	global_load_dword v130, v[164:165], off
	v_lshlrev_b64 v[164:165], 15, v[134:135]
	s_waitcnt vmcnt(0)
	v_add_f32_e32 v126, v126, v130
	v_add_f32_e32 v127, v127, v130
	v_add_f32_e32 v128, v128, v130
	v_add_f32_e32 v129, v129, v130
	v_cvt_pk_bf16_f32 v126, v126, v127
	v_cvt_pk_bf16_f32 v127, v128, v129
	v_lshl_add_u64 v[128:129], v[132:133], 0, v[164:165]
	global_store_dwordx2 v[128:129], v[126:127], off

; #define GLDS16(gp, lp) __builtin_amdgcn_global_load_lds((const unsigned*)(gp), (__attribute__((address_space(3))) unsigned*)(lp), 16, 0, 0)
; template <bool SWAP, class Epi, bool THIN = false> ...
;     ...
;   for (; v < voff + ntiles; v += grid) {
;     const int w = v - voff;
;     int mt, nt;
;     if (w < full * 8 * NT) { const int sr = w / (8 * NT), rem = w - sr * 8 * NT; nt = rem >> 3; mt = sr * 8 + (rem & 7); }
;     else { const int w2 = w - full * 8 * NT, rl = MT - full * 8; nt = w2 / rl; mt = full * 8 + (w2 - nt * rl); }
;     unsigned ap[4], bp[4];
; #pragma unroll
;     for (int i = 0; i < 4; ++i) {
;       const int r = (tid >> 3) + 64 * i;
;       const int cs = tid & 7;
;       const int c = ((cs ^ ((r >> 1) & 7)) << 3);
;       const int sub = 2 * mt + (r >> 7);
;       const int g = sub / tpg, ti = sub - g * tpg;
;       int rig = ti * step - halo + (r & 127); rig = rig < 0 ? 0 : (rig > grows - 1 ? grows - 1 : rig);
;       ap[i] = (unsigned)((g * a_gstride + a_goff + rig) * lda + c);
;       int br = nt * 256 + r; br = br > N - 1 ? N - 1 : br;
;       bp[i] = (unsigned)(br * K + c);
;     }
;     const bool have_next = false;
;     f32x4 acc[4][8];
; #pragma unroll
;     for (int m = 0; m < 4; ++m)
; #pragma unroll
;       for (int n = 0; n < 8; ++n) acc[m][n] = (f32x4){0.f, 0.f, 0.f, 0.f};
;     if (!pre_issued) {
; #pragma unroll
;       for (int i = 0; i < 4; ++i) { GLDS16(A + (size_t)ap[i], smem + tid * 16 + i * 8192); GLDS16(Bt + (size_t)bp[i], smem + 32768 + tid * 16 + i * 8192); }
;     }
;     pre_issued = have_next;
.LBB0_3111:
	s_ashr_i32 s4, s3, 31
	s_lshr_b32 s4, s4, 27
	s_add_i32 s4, s3, s4
	s_ashr_i32 s4, s4, 5
	s_lshl_b32 s6, s3, 1
	s_lshl_b32 s5, s4, 4
	s_and_b32 s6, s6, 14
	s_or_b32 s5, s5, s6
	v_add_u32_e32 v2, s5, v161
	v_ashrrev_i32_e32 v3, 31, v2
	v_lshrrev_b32_e32 v3, 28, v3
	v_add_u32_e32 v3, v2, v3
	v_ashrrev_i32_e32 v18, 4, v3
	v_lshlrev_b32_e32 v3, 11, v18
	v_lshlrev_b32_e32 v2, 7, v2
	v_sub_u32_e32 v2, v2, v3
	v_or_b32_e32 v4, v2, v162
	v_min_i32_e32 v4, 0x7ff, v4
	v_cmp_lt_i32_e32 vcc, -1, v2
	s_lshl_b32 s6, s4, 10
	s_lshl_b32 s4, s3, 5
	v_cndmask_b32_e32 v19, 0, v4, vcc
	v_add_u32_e32 v2, v19, v3
	v_add_u32_e32 v3, s5, v164
	v_ashrrev_i32_e32 v4, 31, v3
	v_lshrrev_b32_e32 v4, 28, v4
	v_add_u32_e32 v4, v3, v4
	v_ashrrev_i32_e32 v20, 4, v4
	v_lshlrev_b32_e32 v4, 11, v20
	v_lshlrev_b32_e32 v3, 7, v3
	v_sub_u32_e32 v3, v3, v4
	v_or_b32_e32 v5, v3, v165
	v_min_i32_e32 v5, 0x7ff, v5
	v_cmp_lt_i32_e32 vcc, -1, v3
	s_sub_i32 s4, s4, s6
	s_and_b32 s4, s4, 0xffffff00
	v_cndmask_b32_e32 v21, 0, v5, vcc
	v_add_u32_e32 v3, v21, v4
	v_lshl_or_b32 v4, v3, 10, v155
	v_add_u32_e32 v3, s4, v163
	v_min_i32_e32 v3, 0x3ff, v3
	v_lshl_or_b32 v6, v3, 10, v155
	v_add_u32_e32 v3, s5, v167
	v_ashrrev_i32_e32 v5, 31, v3
	v_lshrrev_b32_e32 v5, 28, v5
	v_add_u32_e32 v5, v3, v5
	v_ashrrev_i32_e32 v22, 4, v5
	v_lshlrev_b32_e32 v5, 11, v22
	v_lshlrev_b32_e32 v3, 7, v3
	v_sub_u32_e32 v3, v3, v5
	v_or_b32_e32 v7, v3, v162
	v_min_i32_e32 v7, 0x7ff, v7
	v_cmp_lt_i32_e32 vcc, -1, v3
	v_lshl_or_b32 v138, v2, 10, v155
	v_add_u32_e32 v2, s4, v154
	v_cndmask_b32_e32 v23, 0, v7, vcc
	v_add_u32_e32 v3, v23, v5
	v_lshl_or_b32 v8, v3, 10, v155
	v_add_u32_e32 v3, s4, v166
	v_min_i32_e32 v3, 0x3ff, v3
	v_lshl_or_b32 v10, v3, 10, v155
	v_add_u32_e32 v3, s5, v169
	v_ashrrev_i32_e32 v5, 31, v3
	v_lshrrev_b32_e32 v5, 28, v5
	v_add_u32_e32 v5, v3, v5
	v_ashrrev_i32_e32 v24, 4, v5
	v_lshlrev_b32_e32 v5, 11, v24
	v_lshlrev_b32_e32 v3, 7, v3
	v_sub_u32_e32 v3, v3, v5
	v_or_b32_e32 v7, v3, v170
	v_min_i32_e32 v7, 0x7ff, v7
	v_cmp_lt_i32_e32 vcc, -1, v3
	v_min_i32_e32 v2, 0x3ff, v2
	v_readfirstlane_b32 s8, v156
	v_cndmask_b32_e32 v25, 0, v7, vcc
	v_add_u32_e32 v3, v25, v5
	v_lshl_or_b32 v12, v3, 10, v155
	v_add_u32_e32 v3, s4, v168
	v_min_i32_e32 v3, 0x3ff, v3
	v_lshl_or_b32 v2, v2, 10, v155
	v_lshl_or_b32 v14, v3, 10, v155
	v_lshl_add_u64 v[16:17], v[138:139], 1, s[22:23]
	s_mov_b32 m0, s8
	v_mov_b32_e32 v3, v139
	v_readfirstlane_b32 s8, v172
	global_load_lds_dwordx4 v[16:17], off
	v_lshl_add_u64 v[2:3], v[2:3], 1, s[28:29]
	s_mov_b32 m0, s8
	v_mov_b32_e32 v5, v139
	v_readfirstlane_b32 s8, v173
	global_load_lds_dwordx4 v[2:3], off
	v_lshl_add_u64 v[2:3], v[4:5], 1, s[22:23]
	s_mov_b32 m0, s8
	v_mov_b32_e32 v7, v139
	v_readfirstlane_b32 s8, v174
	global_load_lds_dwordx4 v[2:3], off
	v_lshl_add_u64 v[2:3], v[6:7], 1, s[28:29]
	s_mov_b32 m0, s8
	v_mov_b32_e32 v9, v139
	v_readfirstlane_b32 s8, v175
	global_load_lds_dwordx4 v[2:3], off
	v_lshl_add_u64 v[2:3], v[8:9], 1, s[22:23]
	s_mov_b32 m0, s8
	v_mov_b32_e32 v11, v139
	v_readfirstlane_b32 s8, v176
	global_load_lds_dwordx4 v[2:3], off
	v_lshl_add_u64 v[2:3], v[10:11], 1, s[28:29]
	s_mov_b32 m0, s8
	v_mov_b32_e32 v13, v139
	v_readfirstlane_b32 s8, v177
	global_load_lds_dwordx4 v[2:3], off
	v_lshl_add_u64 v[2:3], v[12:13], 1, s[22:23]
	s_mov_b32 m0, s8
	v_mov_b32_e32 v15, v139
	v_readfirstlane_b32 s8, v178
	global_load_lds_dwordx4 v[2:3], off
	v_lshl_add_u64 v[2:3], v[14:15], 1, s[28:29]
	s_mov_b32 m0, s8
	s_sub_i32 s6, s33, s6
	global_load_lds_dwordx4 v[2:3], off
	s_and_b32 s6, s6, 0xffffff00
	v_add_u32_e32 v2, s6, v168
	v_min_i32_e32 v2, 0x3ff, v2
	v_lshl_or_b32 v130, v2, 10, v171
	v_lshl_or_b32 v2, v24, 21, v171
	v_lshl_add_u32 v131, v25, 10, v2
	v_add_u32_e32 v2, s6, v166
	v_min_i32_e32 v2, 0x3ff, v2
	v_lshl_or_b32 v132, v2, 10, v171
	v_lshl_or_b32 v2, v22, 21, v171
	v_lshl_add_u32 v133, v23, 10, v2
	v_add_u32_e32 v2, s6, v163
	v_min_i32_e32 v2, 0x3ff, v2
	v_lshl_or_b32 v134, v2, 10, v171
	v_lshl_or_b32 v2, v20, 21, v171
	v_lshl_add_u32 v135, v21, 10, v2
	v_add_u32_e32 v2, s6, v154
	v_min_i32_e32 v2, 0x3ff, v2
	v_lshl_or_b32 v136, v2, 10, v171
	v_lshl_or_b32 v2, v18, 21, v171
	s_mov_b32 s7, 0
	v_lshl_add_u32 v137, v19, 10, v2
	s_mov_b32 s6, 0
	v_mov_b32_e32 v90, v139
	v_mov_b32_e32 v91, v139
	v_mov_b32_e32 v92, v139
	v_mov_b32_e32 v93, v139
	v_mov_b32_e32 v2, v139
	v_mov_b32_e32 v3, v139
	v_mov_b32_e32 v4, v139
	v_mov_b32_e32 v6, v139
	v_mov_b32_e32 v8, v139
	v_mov_b32_e32 v10, v139
	v_mov_b32_e32 v12, v139
	v_mov_b32_e32 v22, v139
	v_mov_b32_e32 v23, v139
	v_mov_b32_e32 v24, v139
	v_mov_b32_e32 v25, v139
	v_mov_b32_e32 v26, v139
	v_mov_b32_e32 v27, v139
	v_mov_b32_e32 v28, v139
	v_mov_b32_e32 v29, v139
	v_mov_b32_e32 v38, v139
	v_mov_b32_e32 v39, v139
	v_mov_b32_e32 v40, v139
	v_mov_b32_e32 v41, v139
	v_mov_b32_e32 v50, v139
	v_mov_b32_e32 v51, v139
	v_mov_b32_e32 v52, v139
	v_mov_b32_e32 v53, v139
	v_mov_b32_e32 v14, v139
	v_mov_b32_e32 v16, v139
	v_mov_b32_e32 v17, v139
	v_mov_b32_e32 v18, v139
	v_mov_b32_e32 v19, v139
	v_mov_b32_e32 v20, v139
	v_mov_b32_e32 v21, v139
	v_mov_b32_e32 v34, v139
	v_mov_b32_e32 v35, v139
	v_mov_b32_e32 v36, v139
	v_mov_b32_e32 v37, v139
	v_mov_b32_e32 v46, v139
	v_mov_b32_e32 v47, v139
	v_mov_b32_e32 v48, v139
	v_mov_b32_e32 v49, v139
	v_mov_b32_e32 v54, v139
	v_mov_b32_e32 v55, v139
	v_mov_b32_e32 v56, v139
	v_mov_b32_e32 v57, v139
	v_mov_b32_e32 v58, v139
	v_mov_b32_e32 v59, v139
	v_mov_b32_e32 v60, v139
	v_mov_b32_e32 v61, v139
	v_mov_b32_e32 v78, v139
	v_mov_b32_e32 v79, v139
	v_mov_b32_e32 v80, v139
	v_mov_b32_e32 v81, v139
	v_mov_b32_e32 v82, v139
	v_mov_b32_e32 v83, v139
	v_mov_b32_e32 v84, v139
; template <bool SWAP, class Epi, bool THIN = false> ...
;     ...
;     for (int st = 0; st < ns; ++st) {
;       asm volatile("s_waitcnt vmcnt(0)" ::: "memory");
;       __builtin_amdgcn_s_barrier();
;       asm volatile("" ::: "memory");
;       if (st + 1 < ns) {
;         char* nb = smem + ((st + 1) & 1) * 65536;
;         const int ko = (st + 1) * 64;
; #pragma unroll
;         for (int i = 0; i < 4; ++i) { GLDS16(A + (size_t)(ap[i] + ko), nb + tid * 16 + i * 8192); GLDS16(Bt + (size_t)(bp[i] + ko), nb + 32768 + tid * 16 + i * 8192); }
;       }
;       const char* sa = smem + (st & 1) * 65536 + (wr * 64 + fr) * 128;
;       const char* sb = smem + (st & 1) * 65536 + 32768 + (wc * 128 + fr) * 128;
;       if constexpr (THIN) {
;         if (wc == 0) {
; #pragma unroll
;           for (int ks = 0; ks < 2; ++ks) {
;             bf16x8 af[4], bf[2];
; #pragma unroll
;             for (int m = 0; m < 4; ++m) af[m] = *(const bf16x8*)(sa + m * 2048 + (((ks * 4 + fq) ^ swz) << 4));
; #pragma unroll
;             for (int n = 0; n < 2; ++n) bf[n] = *(const bf16x8*)(sb + n * 2048 + (((ks * 4 + fq) ^ swz) << 4));
; #pragma unroll
;             for (int m = 0; m < 4; ++m)
; #pragma unroll
;               for (int n = 0; n < 2; ++n)
;                 acc[m][n] = SWAP ? __builtin_amdgcn_mfma_f32_16x16x32_bf16(bf[n], af[m], acc[m][n], 0, 0, 0)
;                                  : __builtin_amdgcn_mfma_f32_16x16x32_bf16(af[m], bf[n], acc[m][n], 0, 0, 0);
;           }
;         }
;       } else {
;       bf16x8 afA[4], afB[4], bfb[2][2];
; #pragma unroll
;       for (int m = 0; m < 4; ++m) afA[m] = *(const bf16x8*)(sa + m * 2048 + ((fq ^ swz) << 4));
; #pragma unroll
;       for (int n = 0; n < 2; ++n) bfb[0][n] = *(const bf16x8*)(sb + n * 2048 + ((fq ^ swz) << 4));
; #pragma unroll
;       for (int gq = 0; gq < 8; ++gq) {
;         const int ks = gq >> 2, nh = gq & 3;
;         if (gq < 7) {
;           const int ks2 = (gq + 1) >> 2, nh2 = (gq + 1) & 3;
; #pragma unroll
;           for (int n = 0; n < 2; ++n) bfb[(gq + 1) & 1][n] = *(const bf16x8*)(sb + (nh2 * 2 + n) * 2048 + (((ks2 * 4 + fq) ^ swz) << 4));
;         }
;         if (gq == 3) {
; #pragma unroll
;           for (int m = 0; m < 4; ++m) afB[m] = *(const bf16x8*)(sa + m * 2048 + (((4 + fq) ^ swz) << 4));
;         }
;         __builtin_amdgcn_sched_barrier(0);
; #pragma unroll
	v_mov_b32_e32 v85, v139
	v_mov_b32_e32 v30, v139
	v_mov_b32_e32 v31, v139
	v_mov_b32_e32 v32, v139
	v_mov_b32_e32 v33, v139
	v_mov_b32_e32 v42, v139
	v_mov_b32_e32 v43, v139
	v_mov_b32_e32 v44, v139
	v_mov_b32_e32 v45, v139
	v_mov_b32_e32 v66, v139
	v_mov_b32_e32 v67, v139
	v_mov_b32_e32 v68, v139
	v_mov_b32_e32 v69, v139
	v_mov_b32_e32 v74, v139
	v_mov_b32_e32 v75, v139
	v_mov_b32_e32 v76, v139
	v_mov_b32_e32 v77, v139
	v_mov_b32_e32 v86, v139
	v_mov_b32_e32 v87, v139
	v_mov_b32_e32 v88, v139
	v_mov_b32_e32 v89, v139
	v_mov_b32_e32 v94, v139
	v_mov_b32_e32 v95, v139
	v_mov_b32_e32 v96, v139
	v_mov_b32_e32 v97, v139
	v_mov_b32_e32 v106, v139
	v_mov_b32_e32 v107, v139
	v_mov_b32_e32 v108, v139
	v_mov_b32_e32 v109, v139
	v_mov_b32_e32 v110, v139
	v_mov_b32_e32 v111, v139
	v_mov_b32_e32 v112, v139
	v_mov_b32_e32 v113, v139
	v_mov_b32_e32 v62, v139
	v_mov_b32_e32 v63, v139
	v_mov_b32_e32 v64, v139
	v_mov_b32_e32 v65, v139
	v_mov_b32_e32 v70, v139
	v_mov_b32_e32 v71, v139
	v_mov_b32_e32 v72, v139
	v_mov_b32_e32 v73, v139
	v_mov_b32_e32 v98, v139
	v_mov_b32_e32 v99, v139
	v_mov_b32_e32 v100, v139
	v_mov_b32_e32 v101, v139
	v_mov_b32_e32 v102, v139
	v_mov_b32_e32 v103, v139
	v_mov_b32_e32 v104, v139
	v_mov_b32_e32 v105, v139
	v_mov_b32_e32 v114, v139
	v_mov_b32_e32 v115, v139
	v_mov_b32_e32 v116, v139
	v_mov_b32_e32 v117, v139
	v_mov_b32_e32 v118, v139
	v_mov_b32_e32 v119, v139
	v_mov_b32_e32 v120, v139
	v_mov_b32_e32 v121, v139
	v_mov_b32_e32 v122, v139
	v_mov_b32_e32 v123, v139
	v_mov_b32_e32 v124, v139
	v_mov_b32_e32 v125, v139
	v_mov_b32_e32 v126, v139
	v_mov_b32_e32 v127, v139
	v_mov_b32_e32 v128, v139
	v_mov_b32_e32 v129, v139
	v_lshlrev_b32_e32 v137, 1, v137
	v_lshlrev_b32_e32 v136, 1, v136
	v_lshlrev_b32_e32 v135, 1, v135
	v_lshlrev_b32_e32 v134, 1, v134
	v_lshlrev_b32_e32 v133, 1, v133
	v_lshlrev_b32_e32 v132, 1, v132
	v_lshlrev_b32_e32 v131, 1, v131
	v_lshlrev_b32_e32 v130, 1, v130
.LBB0_3112:
	s_add_i32 s9, s7, 0x10000
	s_and_b32 s8, s9, 0x10000
	v_add_u32_e32 v142, s8, v156
	s_nop 0
	v_readfirstlane_b32 s10, v142
	s_waitcnt vmcnt(0)
	s_barrier
	s_and_b32 s7, s7, 0x10000
	v_add_u32_e32 v138, s7, v157
	v_add_u32_e32 v152, v138, v159
	ds_read_b128 v[140:143], v152
	ds_read_b128 v[144:147], v152 offset:2048
	ds_read_b128 v[148:151], v152 offset:4096
	ds_read_b128 v[180:183], v152 offset:6144
	v_or_b32_e32 v152, s7, v158
	v_add_u32_e32 v153, v152, v159
	ds_read_b128 v[184:187], v153 offset:32768
	ds_read_b128 v[188:191], v153 offset:34816
	ds_read_b128 v[192:195], v153 offset:36864
	ds_read_b128 v[196:199], v153 offset:38912
	v_add_u32_e32 v138, v138, v160
	s_waitcnt lgkmcnt(0)
	v_mfma_f32_16x16x32_bf16 v[126:129], v[184:187], v[140:143], v[126:129]
	s_mov_b32 m0, s10
	v_mfma_f32_16x16x32_bf16 v[110:113], v[184:187], v[144:147], v[110:113]
	global_load_lds_dwordx4 v137, s[22:23]
	v_add_u32_e32 v137, 0x80, v137
	v_mfma_f32_16x16x32_bf16 v[82:85], v[184:187], v[148:151], v[82:85]
	v_mfma_f32_16x16x32_bf16 v[50:53], v[184:187], v[180:183], v[50:53]
	ds_read_b128 v[184:187], v153 offset:40960
	ds_read_b128 v[200:203], v153 offset:43008
	v_mfma_f32_16x16x32_bf16 v[122:125], v[188:191], v[140:143], v[122:125]
	s_add_u32 m0, s10, 0x8000
	v_mfma_f32_16x16x32_bf16 v[106:109], v[188:191], v[144:147], v[106:109]
	global_load_lds_dwordx4 v136, s[28:29]
	v_add_u32_e32 v136, 0x80, v136
	v_mfma_f32_16x16x32_bf16 v[78:81], v[188:191], v[148:151], v[78:81]
	v_mfma_f32_16x16x32_bf16 v[38:41], v[188:191], v[180:183], v[38:41]
	v_mfma_f32_16x16x32_bf16 v[118:121], v[192:195], v[140:143], v[118:121]
	s_add_u32 m0, s10, 0x2000
	v_mfma_f32_16x16x32_bf16 v[94:97], v[192:195], v[144:147], v[94:97]
	global_load_lds_dwordx4 v135, s[22:23]
	v_add_u32_e32 v135, 0x80, v135
	v_mfma_f32_16x16x32_bf16 v[58:61], v[192:195], v[148:151], v[58:61]
	v_mfma_f32_16x16x32_bf16 v[26:29], v[192:195], v[180:183], v[26:29]
	ds_read_b128 v[188:191], v153 offset:45056
	ds_read_b128 v[192:195], v153 offset:47104
	v_mfma_f32_16x16x32_bf16 v[114:117], v[196:199], v[140:143], v[114:117]
	s_add_u32 m0, s10, 0xa000
	v_mfma_f32_16x16x32_bf16 v[86:89], v[196:199], v[144:147], v[86:89]
	global_load_lds_dwordx4 v134, s[28:29]
	v_add_u32_e32 v134, 0x80, v134
	v_mfma_f32_16x16x32_bf16 v[54:57], v[196:199], v[148:151], v[54:57]
	v_mfma_f32_16x16x32_bf16 v[22:25], v[196:199], v[180:183], v[22:25]
	v_add_u32_e32 v152, v152, v160
	s_waitcnt lgkmcnt(0)
	v_mfma_f32_16x16x32_bf16 v[102:105], v[184:187], v[140:143], v[102:105]
	ds_read_b128 v[196:199], v152 offset:32768
	ds_read_b128 v[204:207], v152 offset:34816
	s_add_u32 m0, s10, 0x4000
	v_mfma_f32_16x16x32_bf16 v[74:77], v[184:187], v[144:147], v[74:77]
	global_load_lds_dwordx4 v133, s[22:23]
	v_add_u32_e32 v133, 0x80, v133
	v_mfma_f32_16x16x32_bf16 v[46:49], v[184:187], v[148:151], v[46:49]
	v_mfma_f32_16x16x32_bf16 v[10:13], v[184:187], v[180:183], v[10:13]
	ds_read_b128 v[184:187], v138
	ds_read_b128 v[208:211], v138 offset:2048
	ds_read_b128 v[212:215], v138 offset:4096
	ds_read_b128 v[216:219], v138 offset:6144
	v_mfma_f32_16x16x32_bf16 v[98:101], v[200:203], v[140:143], v[98:101]
	s_add_u32 m0, s10, 0xc000
	v_mfma_f32_16x16x32_bf16 v[66:69], v[200:203], v[144:147], v[66:69]
	global_load_lds_dwordx4 v132, s[28:29]
	v_add_u32_e32 v132, 0x80, v132
	v_mfma_f32_16x16x32_bf16 v[34:37], v[200:203], v[148:151], v[34:37]
	v_mfma_f32_16x16x32_bf16 v[6:9], v[200:203], v[180:183], v[6:9]
	v_mfma_f32_16x16x32_bf16 v[70:73], v[188:191], v[140:143], v[70:73]
	s_add_u32 m0, s10, 0x6000
	v_mfma_f32_16x16x32_bf16 v[62:65], v[192:195], v[140:143], v[62:65]
	global_load_lds_dwordx4 v131, s[22:23]
	v_add_u32_e32 v131, 0x80, v131
	v_mfma_f32_16x16x32_bf16 v[42:45], v[188:191], v[144:147], v[42:45]
	v_mfma_f32_16x16x32_bf16 v[30:33], v[192:195], v[144:147], v[30:33]
	ds_read_b128 v[140:143], v152 offset:36864
	ds_read_b128 v[144:147], v152 offset:38912
	v_mfma_f32_16x16x32_bf16 v[18:21], v[188:191], v[148:151], v[18:21]
	s_add_u32 m0, s10, 0xe000
	v_mfma_f32_16x16x32_bf16 v[14:17], v[192:195], v[148:151], v[14:17]
	global_load_lds_dwordx4 v130, s[28:29]
	v_add_u32_e32 v130, 0x80, v130
	v_mfma_f32_16x16x32_bf16 v[2:5], v[188:191], v[180:183], v[2:5]
	v_mfma_f32_16x16x32_bf16 v[90:93], v[192:195], v[180:183], v[90:93]
	ds_read_b128 v[148:151], v152 offset:40960
	ds_read_b128 v[180:183], v152 offset:43008
	s_waitcnt lgkmcnt(0)
; template <bool SWAP, class Epi, bool THIN = false> ...
;     ...
;       bf16x8 afA[4], afB[4], bfb[2][2];
; #pragma unroll
;       for (int m = 0; m < 4; ++m) afA[m] = *(const bf16x8*)(sa + m * 2048 + ((fq ^ swz) << 4));
; #pragma unroll
;       for (int n = 0; n < 2; ++n) bfb[0][n] = *(const bf16x8*)(sb + n * 2048 + ((fq ^ swz) << 4));
; #pragma unroll
;       for (int gq = 0; gq < 8; ++gq) {
;         const int ks = gq >> 2, nh = gq & 3;
;         if (gq < 7) {
;           const int ks2 = (gq + 1) >> 2, nh2 = (gq + 1) & 3;
; #pragma unroll
;           for (int n = 0; n < 2; ++n) bfb[(gq + 1) & 1][n] = *(const bf16x8*)(sb + (nh2 * 2 + n) * 2048 + (((ks2 * 4 + fq) ^ swz) << 4));
;         }
;         if (gq == 3) {
; #pragma unroll
;           for (int m = 0; m < 4; ++m) afB[m] = *(const bf16x8*)(sa + m * 2048 + (((4 + fq) ^ swz) << 4));
;         }
;         __builtin_amdgcn_sched_barrier(0);
; #pragma unroll
;         for (int m = 0; m < 4; ++m)
; #pragma unroll
;           for (int n = 0; n < 2; ++n) {
;             const bf16x8 av = ks ? afB[m] : afA[m];
;             acc[m][nh * 2 + n] = SWAP ? __builtin_amdgcn_mfma_f32_16x16x32_bf16(bfb[gq & 1][n], av, acc[m][nh * 2 + n], 0, 0, 0)
;                                       : __builtin_amdgcn_mfma_f32_16x16x32_bf16(av, bfb[gq & 1][n], acc[m][nh * 2 + n], 0, 0, 0);
;           }
;       }
	v_mfma_f32_16x16x32_bf16 v[126:129], v[196:199], v[184:187], v[126:129]
	v_mfma_f32_16x16x32_bf16 v[122:125], v[204:207], v[184:187], v[122:125]
	v_mfma_f32_16x16x32_bf16 v[110:113], v[196:199], v[208:211], v[110:113]
	v_mfma_f32_16x16x32_bf16 v[106:109], v[204:207], v[208:211], v[106:109]
	v_mfma_f32_16x16x32_bf16 v[82:85], v[196:199], v[212:215], v[82:85]
	v_mfma_f32_16x16x32_bf16 v[78:81], v[204:207], v[212:215], v[78:81]
	v_mfma_f32_16x16x32_bf16 v[50:53], v[196:199], v[216:219], v[50:53]
	v_mfma_f32_16x16x32_bf16 v[38:41], v[204:207], v[216:219], v[38:41]
	v_mfma_f32_16x16x32_bf16 v[118:121], v[140:143], v[184:187], v[118:121]
	v_mfma_f32_16x16x32_bf16 v[94:97], v[140:143], v[208:211], v[94:97]
	v_mfma_f32_16x16x32_bf16 v[58:61], v[140:143], v[212:215], v[58:61]
	v_mfma_f32_16x16x32_bf16 v[26:29], v[140:143], v[216:219], v[26:29]
	ds_read_b128 v[140:143], v152 offset:45056
	ds_read_b128 v[188:191], v152 offset:47104
	v_mfma_f32_16x16x32_bf16 v[114:117], v[144:147], v[184:187], v[114:117]
	v_mfma_f32_16x16x32_bf16 v[86:89], v[144:147], v[208:211], v[86:89]
	v_mfma_f32_16x16x32_bf16 v[54:57], v[144:147], v[212:215], v[54:57]
	v_mfma_f32_16x16x32_bf16 v[22:25], v[144:147], v[216:219], v[22:25]
	v_mfma_f32_16x16x32_bf16 v[102:105], v[148:151], v[184:187], v[102:105]
	v_mfma_f32_16x16x32_bf16 v[98:101], v[180:183], v[184:187], v[98:101]
	v_mfma_f32_16x16x32_bf16 v[74:77], v[148:151], v[208:211], v[74:77]
	v_mfma_f32_16x16x32_bf16 v[66:69], v[180:183], v[208:211], v[66:69]
	v_mfma_f32_16x16x32_bf16 v[46:49], v[148:151], v[212:215], v[46:49]
	v_mfma_f32_16x16x32_bf16 v[34:37], v[180:183], v[212:215], v[34:37]
	v_mfma_f32_16x16x32_bf16 v[10:13], v[148:151], v[216:219], v[10:13]
	v_mfma_f32_16x16x32_bf16 v[6:9], v[180:183], v[216:219], v[6:9]
	s_waitcnt lgkmcnt(0)
	v_mfma_f32_16x16x32_bf16 v[70:73], v[140:143], v[184:187], v[70:73]
	s_add_i32 s6, s6, 64
	s_cmpk_eq_i32 s6, 0x3c0
	s_mov_b32 s7, s9
	v_mfma_f32_16x16x32_bf16 v[62:65], v[188:191], v[184:187], v[62:65]
	v_mfma_f32_16x16x32_bf16 v[42:45], v[140:143], v[208:211], v[42:45]
	v_mfma_f32_16x16x32_bf16 v[30:33], v[188:191], v[208:211], v[30:33]
	v_mfma_f32_16x16x32_bf16 v[18:21], v[140:143], v[212:215], v[18:21]
	v_mfma_f32_16x16x32_bf16 v[14:17], v[188:191], v[212:215], v[14:17]
	v_mfma_f32_16x16x32_bf16 v[2:5], v[140:143], v[216:219], v[2:5]
	v_mfma_f32_16x16x32_bf16 v[90:93], v[188:191], v[216:219], v[90:93]
	s_cbranch_scc0 .LBB0_3112
	v_add_u32_e32 v138, s8, v157
	v_add_u32_e32 v152, s8, v158
	s_waitcnt vmcnt(0)
	s_barrier
	v_add_u32_e32 v144, v138, v159
	v_add_u32_e32 v153, v152, v159
	ds_read_b128 v[130:133], v144
	ds_read_b128 v[134:137], v144 offset:2048
	ds_read_b128 v[140:143], v144 offset:4096
	ds_read_b128 v[144:147], v144 offset:6144
	ds_read_b128 v[148:151], v153 offset:32768
	ds_read_b128 v[180:183], v153 offset:34816
	ds_read_b128 v[184:187], v153 offset:36864
	ds_read_b128 v[188:191], v153 offset:38912
	v_add_u32_e32 v138, v138, v160
	s_waitcnt lgkmcnt(0)
	v_mfma_f32_16x16x32_bf16 v[126:129], v[148:151], v[130:133], v[126:129]
	v_mfma_f32_16x16x32_bf16 v[110:113], v[148:151], v[134:137], v[110:113]
	v_mfma_f32_16x16x32_bf16 v[82:85], v[148:151], v[140:143], v[82:85]
	v_mfma_f32_16x16x32_bf16 v[50:53], v[148:151], v[144:147], v[50:53]
	ds_read_b128 v[148:151], v153 offset:40960
	ds_read_b128 v[192:195], v153 offset:43008
	v_mfma_f32_16x16x32_bf16 v[122:125], v[180:183], v[130:133], v[122:125]
	v_mfma_f32_16x16x32_bf16 v[106:109], v[180:183], v[134:137], v[106:109]
	v_mfma_f32_16x16x32_bf16 v[78:81], v[180:183], v[140:143], v[78:81]
	v_mfma_f32_16x16x32_bf16 v[38:41], v[180:183], v[144:147], v[38:41]
	v_mfma_f32_16x16x32_bf16 v[118:121], v[184:187], v[130:133], v[118:121]
	v_mfma_f32_16x16x32_bf16 v[180:183], v[184:187], v[134:137], v[94:97]
	v_mfma_f32_16x16x32_bf16 v[200:203], v[184:187], v[140:143], v[58:61]
	v_mfma_f32_16x16x32_bf16 v[204:207], v[188:191], v[140:143], v[54:57]
	v_mfma_f32_16x16x32_bf16 v[184:187], v[184:187], v[144:147], v[26:29]
	s_nop 2
	ds_read_b128 v[26:29], v153 offset:45056
	ds_read_b128 v[54:57], v153 offset:47104
	v_mfma_f32_16x16x32_bf16 v[114:117], v[188:191], v[130:133], v[114:117]
	v_mfma_f32_16x16x32_bf16 v[196:199], v[188:191], v[134:137], v[86:89]
	v_mfma_f32_16x16x32_bf16 v[188:191], v[188:191], v[144:147], v[22:25]
	v_add_u32_e32 v152, v152, v160
	s_waitcnt lgkmcnt(0)
; __device__ __forceinline__ int get_tid512() { int t = threadIdx.x; asm volatile("" : "+v"(t)); return t; }
; __device__ __forceinline__ float bf2f(bf16_t h) { return __uint_as_float(((unsigned)h) << 16); }
;   __device__ __forceinline__ void c4(int g, int rig, int col, f32x4 v) const {
;     const size_t o = ((size_t)g * 2048 + rig) * 1024 + col;
;     f32x4 bs;
;     if (BASE_F32) bs = __builtin_nontemporal_load((const f32x4*)((const float*)base + o));
;     else {
;       const uint2 u = *(const uint2*)((const bf16_t*)base + o);
;       bs[0] = bf2f((bf16_t)(u.x & 0xffff)); bs[1] = bf2f((bf16_t)(u.x >> 16)); bs[2] = bf2f((bf16_t)(u.y & 0xffff)); bs[3] = bf2f((bf16_t)(u.y >> 16));
;     }
;     const f32x4 gt = *(const f32x4*)(gate + (size_t)g * 6144 + col);
;     f32x4 bi = {0.f, 0.f, 0.f, 0.f};
;     if (bias) bi = *(const f32x4*)(bias + col);
; template <bool SWAP, class Epi, bool THIN = false> ...
;     ...
;     __syncthreads();
;     const int te = get_tid512();
;     const int fr_e = te & 15, fq_e = (te & 63) >> 4, wr_e = te >> 7, wc_e = (te >> 6) & 1;
;     const int sub = 2 * mt + (wr_e >> 1);
;     const int g = sub / tpg, ti = sub - g * tpg;
;     const int rig0 = ti * step - halo;
;     const int rw = (wr_e & 1) * 64;
;     if constexpr (Epi::KIND == 0) {
; #pragma unroll
;       for (int m = 0; m < 4; ++m) {
;         const int rig = rig0 + rw + m * 16 + fr_e;
;         if constexpr (Epi::ROWSUM) {
;           float ss = 0.f;
; #pragma unroll
;           for (int n = 0; n < 8; ++n) {
;             const int col = nt * 256 + wc_e * 128 + n * 16 + fq_e * 4;
;             if (col < N) ss += epi.c4(g, rig, col, acc[m][n]);
;           }
;           ss += __shfl_xor(ss, 16); ss += __shfl_xor(ss, 32);
;           if (fq_e == 0) epi.rowsum(g, rig, nt * 2 + wc_e, ss);
;         } else {
; #pragma unroll
;           for (int n = 0; n < 8; ++n) {
;             const int col = nt * 256 + wc_e * 128 + n * 16 + fq_e * 4;
;             if (col < N) epi.c4(g, rig, col, acc[m][n]);
	v_mfma_f32_16x16x32_bf16 v[102:105], v[148:151], v[130:133], v[102:105]
	ds_read_b128 v[22:25], v152 offset:32768
	ds_read_b128 v[86:89], v152 offset:34816
	v_mfma_f32_16x16x32_bf16 v[74:77], v[148:151], v[134:137], v[74:77]
	v_mfma_f32_16x16x32_bf16 v[46:49], v[148:151], v[140:143], v[46:49]
	v_mfma_f32_16x16x32_bf16 v[10:13], v[148:151], v[144:147], v[10:13]
	ds_read_b128 v[148:151], v138
	ds_read_b128 v[208:211], v138 offset:2048
	ds_read_b128 v[212:215], v138 offset:4096
	ds_read_b128 v[216:219], v138 offset:6144
	v_mfma_f32_16x16x32_bf16 v[98:101], v[192:195], v[130:133], v[98:101]
	v_mfma_f32_16x16x32_bf16 v[66:69], v[192:195], v[134:137], v[66:69]
	v_mfma_f32_16x16x32_bf16 v[34:37], v[192:195], v[140:143], v[34:37]
	v_mfma_f32_16x16x32_bf16 v[6:9], v[192:195], v[144:147], v[6:9]
	v_mfma_f32_16x16x32_bf16 v[220:223], v[26:29], v[140:143], v[18:21]
	v_mfma_f32_16x16x32_bf16 v[140:143], v[54:57], v[140:143], v[14:17]
	s_nop 2
	ds_read_b128 v[14:17], v152 offset:36864
	ds_read_b128 v[18:21], v152 offset:38912
	v_mfma_f32_16x16x32_bf16 v[70:73], v[26:29], v[130:133], v[70:73]
	v_mfma_f32_16x16x32_bf16 v[2:5], v[26:29], v[144:147], v[2:5]
	v_mfma_f32_16x16x32_bf16 v[130:133], v[54:57], v[130:133], v[62:65]
	v_mfma_f32_16x16x32_bf16 v[192:195], v[26:29], v[134:137], v[42:45]
	v_mfma_f32_16x16x32_bf16 v[134:137], v[54:57], v[134:137], v[30:33]
	v_mfma_f32_16x16x32_bf16 v[224:227], v[54:57], v[144:147], v[90:93]
	ds_read_b128 v[144:147], v152 offset:40960
	ds_read_b128 v[228:231], v152 offset:43008
	s_waitcnt lgkmcnt(0)
	v_mfma_f32_16x16x32_bf16 v[126:129], v[22:25], v[148:151], v[126:129]
	v_mfma_f32_16x16x32_bf16 v[122:125], v[86:89], v[148:151], v[122:125]
	v_mfma_f32_16x16x32_bf16 v[94:97], v[22:25], v[208:211], v[110:113]
	v_mfma_f32_16x16x32_bf16 v[90:93], v[86:89], v[208:211], v[106:109]
	v_mfma_f32_16x16x32_bf16 v[62:65], v[22:25], v[212:215], v[82:85]
	v_mfma_f32_16x16x32_bf16 v[58:61], v[86:89], v[212:215], v[78:81]
	v_mfma_f32_16x16x32_bf16 v[30:33], v[22:25], v[216:219], v[50:53]
	v_mfma_f32_16x16x32_bf16 v[26:29], v[86:89], v[216:219], v[38:41]
	v_mfma_f32_16x16x32_bf16 v[86:89], v[14:17], v[208:211], v[180:183]
	v_mfma_f32_16x16x32_bf16 v[22:25], v[14:17], v[216:219], v[184:187]
	s_nop 1
	ds_read_b128 v[180:183], v152 offset:45056
	ds_read_b128 v[184:187], v152 offset:47104
	v_mfma_f32_16x16x32_bf16 v[118:121], v[14:17], v[148:151], v[118:121]
	v_mfma_f32_16x16x32_bf16 v[114:117], v[18:21], v[148:151], v[114:117]
	v_mfma_f32_16x16x32_bf16 v[82:85], v[18:21], v[208:211], v[196:199]
	v_mfma_f32_16x16x32_bf16 v[54:57], v[14:17], v[212:215], v[200:203]
	v_mfma_f32_16x16x32_bf16 v[50:53], v[18:21], v[212:215], v[204:207]
	v_mfma_f32_16x16x32_bf16 v[18:21], v[18:21], v[216:219], v[188:191]
	v_mfma_f32_16x16x32_bf16 v[110:113], v[144:147], v[148:151], v[102:105]
	v_mfma_f32_16x16x32_bf16 v[106:109], v[228:231], v[148:151], v[98:101]
	v_mfma_f32_16x16x32_bf16 v[78:81], v[144:147], v[208:211], v[74:77]
	v_mfma_f32_16x16x32_bf16 v[74:77], v[228:231], v[208:211], v[66:69]
	v_mfma_f32_16x16x32_bf16 v[46:49], v[144:147], v[212:215], v[46:49]
	v_mfma_f32_16x16x32_bf16 v[42:45], v[228:231], v[212:215], v[34:37]
	v_mfma_f32_16x16x32_bf16 v[14:17], v[144:147], v[216:219], v[10:13]
	v_mfma_f32_16x16x32_bf16 v[10:13], v[228:231], v[216:219], v[6:9]
	v_mov_b32_e32 v138, v1
	s_waitcnt vmcnt(0) lgkmcnt(0)
	s_barrier
	v_mfma_f32_16x16x32_bf16 v[98:101], v[184:187], v[148:151], v[130:133]
	v_ashrrev_i32_e32 v7, 8, v138
	v_add_u32_e32 v7, s5, v7
	v_ashrrev_i32_e32 v8, 31, v7
	v_lshrrev_b32_e32 v8, 28, v8
	v_add_u32_e32 v8, v7, v8
	v_ashrrev_i32_e32 v130, 4, v8
	v_lshlrev_b32_e32 v8, 11, v130
	v_lshlrev_b32_e32 v7, 7, v7
	v_sub_u32_e32 v7, v7, v8
	v_lshrrev_b32_e32 v8, 1, v138
	v_and_b32_e32 v6, 15, v138
	v_and_b32_e32 v8, 64, v8
	v_or3_b32 v144, v7, v8, v6
	v_lshlrev_b32_e32 v6, 1, v138
	v_and_b32_e32 v131, 0x80, v6
	v_mfma_f32_16x16x32_bf16 v[6:9], v[180:183], v[216:219], v[2:5]
	v_ashrrev_i32_e32 v145, 31, v144
	v_lshlrev_b64 v[132:133], 10, v[144:145]
	s_nop 0
	v_lshrrev_b32_e32 v2, 2, v138
	v_and_b32_e32 v2, 12, v2
	v_mfma_f32_16x16x32_bf16 v[102:105], v[180:183], v[148:151], v[70:73]
	v_mfma_f32_16x16x32_bf16 v[70:73], v[180:183], v[208:211], v[192:195]
	v_mfma_f32_16x16x32_bf16 v[66:69], v[184:187], v[208:211], v[134:137]
	v_mfma_f32_16x16x32_bf16 v[38:41], v[180:183], v[212:215], v[220:223]
	v_mfma_f32_16x16x32_bf16 v[34:37], v[184:187], v[212:215], v[140:143]
	s_nop 2
	v_or3_b32 v140, v2, v131, s4
	v_mfma_f32_16x16x32_bf16 v[2:5], v[184:187], v[216:219], v[224:227]
	v_ashrrev_i32_e32 v131, 31, v130
	v_lshlrev_b64 v[146:147], 21, v[130:131]
	v_mad_i64_i32 v[130:131], s[4:5], v130, s39, 0
	v_lshl_add_u64 v[132:133], v[132:133], 0, v[146:147]
	v_lshl_add_u64 v[142:143], s[30:31], 0, v[130:131]
	v_cndmask_b32_e64 v130, 0, 1, s[34:35]
	v_cmp_gt_i32_e64 s[6:7], s40, v140
	v_ashrrev_i32_e32 v141, 31, v140
	v_lshl_add_u64 v[148:149], v[132:133], 1, s[24:25]
	v_cmp_ne_u32_e64 s[4:5], 1, v130
	s_and_saveexec_b64 s[8:9], s[6:7]
	s_cbranch_execz .LBB0_3118
	v_lshl_add_u64 v[150:151], v[140:141], 1, v[148:149]
	v_lshl_add_u64 v[130:131], v[140:141], 2, v[142:143]
	global_load_dwordx2 v[152:153], v[150:151], off
	s_and_b64 vcc, exec, s[4:5]
	global_load_dwordx4 v[130:133], v[130:131], off
	s_cbranch_vccnz .LBB0_3116
	v_lshl_add_u64 v[134:135], v[140:141], 2, s[26:27]
	global_load_dwordx4 v[134:137], v[134:135], off
	s_branch .LBB0_3117
